# v12 + GEMM main loops: two coarse vmcnt(6) waits per iteration replaced by per-phase vmcnt(10) waits before the first barrier of phases 1,2,4,5,6,8 (5 phases of DMA lead instead of 3)
# baseline (speedup 1.0000x reference)
.LBB0_211:
	s_add_i32 s60, s60, 1
	s_mov_b64 s[36:37], s[18:19]
	s_mul_i32 s18, s60, s26
	s_add_i32 s38, s18, s2
	s_cmpk_gt_i32 s38, 0x1ff
	s_cselect_b64 s[44:45], -1, 0
	s_lshl_b32 s18, s38, 3
	s_and_b32 s18, s18, 56
	s_bfe_u32 s19, s38, 0x30003
	s_mov_b32 s27, s61
	s_or_b32 s61, s18, s19
	s_mov_b32 s3, s42
	s_ashr_i32 s42, s38, 6
	s_lshl_b32 s18, s61, 19
	s_mov_b64 s[4:5], s[20:21]
	s_add_u32 s20, s14, s18
	s_addc_u32 s21, s15, 0
	s_ashr_i32 s43, s42, 31
	s_lshl_b64 s[18:19], s[42:43], 19
	s_add_u32 s18, s16, s18
	s_addc_u32 s19, s17, s19
	s_cmpk_lt_i32 s38, 0x200
	s_cselect_b32 s38, s21, s5
	s_cselect_b32 s43, s20, s4
	s_cselect_b32 s62, s19, s37
	s_cselect_b32 s63, s18, s36
	s_add_u32 s64, s36, 0x100
	s_addc_u32 s65, s37, 0
	s_mov_b32 s66, -2
	s_waitcnt lgkmcnt(0)
	s_add_u32 s36, s4, 0x100
	s_addc_u32 s37, s5, 0
	s_add_i32 s67, 0, 0x10000
	v_add_u32_e32 v1, s67, v191
	ds_read_b128 v[34:37], v1
	ds_read_b128 v[38:41], v1 offset:1024
	ds_read_b128 v[42:45], v1 offset:2048
	ds_read_b128 v[46:49], v1 offset:3072
	s_cmp_eq_u32 s66, 12
	s_cselect_b32 s49, s38, s37
	s_cselect_b32 s48, s43, s36
	s_cselect_b32 s47, s62, s65
	s_cselect_b32 s46, s63, s64
	v_lshl_add_u64 v[186:187], s[4:5], 0, v[168:169]
	s_add_i32 m0, s53, 0xc000
	ds_read_b128 v[50:53], v206
	ds_read_b128 v[58:61], v206 offset:1024
	ds_read_b128 v[62:65], v206 offset:2048
	ds_read_b128 v[66:69], v206 offset:3072
	ds_read_b128 v[170:173], v206 offset:4096
	ds_read_b128 v[174:177], v206 offset:5120
	ds_read_b128 v[178:181], v206 offset:6144
	ds_read_b128 v[182:185], v206 offset:7168
	global_load_lds_dwordx4 v[186:187], off
	v_lshl_add_u64 v[186:187], s[4:5], 0, v[166:167]
	s_add_i32 m0, s53, 0xe000
	s_nop 0
	global_load_lds_dwordx4 v[186:187], off
	s_waitcnt lgkmcnt(8)
	s_waitcnt vmcnt(10)
	s_barrier
	s_waitcnt lgkmcnt(0)
	s_setprio 1
	s_waitcnt lgkmcnt(0)
	v_mfma_f32_16x16x32_bf16 v[158:161], v[34:37], v[50:53], 0
	v_mfma_f32_16x16x32_bf16 v[154:157], v[42:45], v[50:53], 0
	v_mfma_f32_16x16x32_bf16 v[142:145], v[34:37], v[62:65], 0
	v_mfma_f32_16x16x32_bf16 v[138:141], v[42:45], v[62:65], 0
	v_mfma_f32_16x16x32_bf16 v[126:129], v[34:37], v[170:173], 0
	v_mfma_f32_16x16x32_bf16 v[122:125], v[42:45], v[170:173], 0
	v_mfma_f32_16x16x32_bf16 v[110:113], v[34:37], v[178:181], 0
	v_mfma_f32_16x16x32_bf16 v[106:109], v[42:45], v[178:181], 0
	v_mfma_f32_16x16x32_bf16 v[158:161], v[38:41], v[58:61], v[158:161]
	v_mfma_f32_16x16x32_bf16 v[154:157], v[46:49], v[58:61], v[154:157]
	v_mfma_f32_16x16x32_bf16 v[142:145], v[38:41], v[66:69], v[142:145]
	v_mfma_f32_16x16x32_bf16 v[138:141], v[46:49], v[66:69], v[138:141]
	v_mfma_f32_16x16x32_bf16 v[126:129], v[38:41], v[174:177], v[126:129]
	v_mfma_f32_16x16x32_bf16 v[122:125], v[46:49], v[174:177], v[122:125]
	v_mfma_f32_16x16x32_bf16 v[110:113], v[38:41], v[182:185], v[110:113]
	v_mfma_f32_16x16x32_bf16 v[106:109], v[46:49], v[182:185], v[106:109]
	s_setprio 0
	s_barrier
	s_add_i32 s68, 0, 0x14000
	s_add_i32 s4, s67, s52
	v_add_u32_e32 v1, s68, v191
	v_lshl_add_u64 v[214:215], s[46:47], 0, v[164:165]
	s_mov_b32 m0, s4
	ds_read_b128 v[186:189], v1
	ds_read_b128 v[208:211], v1 offset:1024
	ds_read_b128 v[222:225], v1 offset:2048
	ds_read_b128 v[226:229], v1 offset:3072
	global_load_lds_dwordx4 v[214:215], off
	v_lshl_add_u64 v[238:239], s[46:47], 0, v[162:163]
	s_add_i32 m0, s4, 0x2000
	s_nop 0
	global_load_lds_dwordx4 v[238:239], off
	s_waitcnt vmcnt(10)
	s_barrier
	s_waitcnt lgkmcnt(0)
	s_setprio 1
	s_waitcnt lgkmcnt(0)
	v_mfma_f32_16x16x32_bf16 v[150:153], v[186:189], v[50:53], 0
	v_mfma_f32_16x16x32_bf16 v[50:53], v[222:225], v[50:53], 0
	v_mfma_f32_16x16x32_bf16 v[150:153], v[208:211], v[58:61], v[150:153]
	v_mfma_f32_16x16x32_bf16 v[50:53], v[226:229], v[58:61], v[50:53]
	v_mfma_f32_16x16x32_bf16 v[58:61], v[186:189], v[62:65], 0
	v_mfma_f32_16x16x32_bf16 v[62:65], v[222:225], v[62:65], 0
	v_mfma_f32_16x16x32_bf16 v[114:117], v[222:225], v[170:173], 0
	v_mfma_f32_16x16x32_bf16 v[102:105], v[186:189], v[178:181], 0
	v_mfma_f32_16x16x32_bf16 v[98:101], v[222:225], v[178:181], 0
	v_mfma_f32_16x16x32_bf16 v[58:61], v[208:211], v[66:69], v[58:61]
	v_mfma_f32_16x16x32_bf16 v[62:65], v[226:229], v[66:69], v[62:65]
	v_mfma_f32_16x16x32_bf16 v[66:69], v[186:189], v[170:173], 0
	v_mfma_f32_16x16x32_bf16 v[114:117], v[226:229], v[174:177], v[114:117]
	v_mfma_f32_16x16x32_bf16 v[102:105], v[208:211], v[182:185], v[102:105]
	v_mfma_f32_16x16x32_bf16 v[98:101], v[226:229], v[182:185], v[98:101]
	v_mfma_f32_16x16x32_bf16 v[66:69], v[208:211], v[174:177], v[66:69]
	s_setprio 0
	s_mov_b32 m0, s53
	v_lshl_add_u64 v[240:241], s[48:49], 0, v[164:165]
	s_barrier
	ds_read_b128 v[118:121], v206 offset:16384
	ds_read_b128 v[130:133], v206 offset:17408
	ds_read_b128 v[134:137], v206 offset:18432
	ds_read_b128 v[146:149], v206 offset:19456
	ds_read_b128 v[170:173], v206 offset:20480
	ds_read_b128 v[174:177], v206 offset:21504
	ds_read_b128 v[178:181], v206 offset:22528
	ds_read_b128 v[182:185], v206 offset:23552
	global_load_lds_dwordx4 v[240:241], off
	v_lshl_add_u64 v[242:243], s[48:49], 0, v[162:163]
	s_mov_b32 m0, s54
	s_nop 0
	global_load_lds_dwordx4 v[242:243], off
	s_barrier
	s_waitcnt lgkmcnt(0)
	s_setprio 1
	s_waitcnt lgkmcnt(0)
	v_mfma_f32_16x16x32_bf16 v[94:97], v[34:37], v[118:121], 0
	v_mfma_f32_16x16x32_bf16 v[90:93], v[42:45], v[118:121], 0
	v_mfma_f32_16x16x32_bf16 v[78:81], v[34:37], v[134:137], 0
	v_mfma_f32_16x16x32_bf16 v[74:77], v[42:45], v[134:137], 0
	v_mfma_f32_16x16x32_bf16 v[30:33], v[34:37], v[170:173], 0
	v_mfma_f32_16x16x32_bf16 v[26:29], v[42:45], v[170:173], 0
	v_mfma_f32_16x16x32_bf16 v[14:17], v[34:37], v[178:181], 0
	v_mfma_f32_16x16x32_bf16 v[10:13], v[42:45], v[178:181], 0
	v_mfma_f32_16x16x32_bf16 v[94:97], v[38:41], v[130:133], v[94:97]
	v_mfma_f32_16x16x32_bf16 v[90:93], v[46:49], v[130:133], v[90:93]
	v_mfma_f32_16x16x32_bf16 v[78:81], v[38:41], v[146:149], v[78:81]
	v_mfma_f32_16x16x32_bf16 v[74:77], v[46:49], v[146:149], v[74:77]
	v_mfma_f32_16x16x32_bf16 v[30:33], v[38:41], v[174:177], v[30:33]
	v_mfma_f32_16x16x32_bf16 v[26:29], v[46:49], v[174:177], v[26:29]
	v_mfma_f32_16x16x32_bf16 v[14:17], v[38:41], v[182:185], v[14:17]
	v_mfma_f32_16x16x32_bf16 v[10:13], v[46:49], v[182:185], v[10:13]
	s_setprio 0
	s_barrier
	s_add_u32 s4, s46, 0x40000
	s_addc_u32 s5, s47, 0
	s_add_i32 s67, s68, s52
	v_lshl_add_u64 v[34:35], s[4:5], 0, v[164:165]
	s_mov_b32 m0, s67
	s_nop 0
	global_load_lds_dwordx4 v[34:35], off
	v_lshl_add_u64 v[34:35], s[4:5], 0, v[162:163]
	s_add_i32 m0, s67, 0x2000
	s_nop 0
	global_load_lds_dwordx4 v[34:35], off
	s_waitcnt vmcnt(10)
	s_barrier
	s_setprio 1
	v_mfma_f32_16x16x32_bf16 v[22:25], v[186:189], v[170:173], 0
	v_mfma_f32_16x16x32_bf16 v[18:21], v[222:225], v[170:173], 0
	v_mfma_f32_16x16x32_bf16 v[6:9], v[186:189], v[178:181], 0
	v_mfma_f32_16x16x32_bf16 v[2:5], v[222:225], v[178:181], 0
	v_mfma_f32_16x16x32_bf16 v[34:37], v[186:189], v[118:121], 0
	v_mfma_f32_16x16x32_bf16 v[38:41], v[222:225], v[118:121], 0
	v_mfma_f32_16x16x32_bf16 v[42:45], v[186:189], v[134:137], 0
	v_mfma_f32_16x16x32_bf16 v[46:49], v[222:225], v[134:137], 0
	v_mfma_f32_16x16x32_bf16 v[22:25], v[208:211], v[174:177], v[22:25]
	v_mfma_f32_16x16x32_bf16 v[18:21], v[226:229], v[174:177], v[18:21]
	v_mfma_f32_16x16x32_bf16 v[6:9], v[208:211], v[182:185], v[6:9]
	v_mfma_f32_16x16x32_bf16 v[2:5], v[226:229], v[182:185], v[2:5]
	v_mfma_f32_16x16x32_bf16 v[34:37], v[208:211], v[130:133], v[34:37]
	v_mfma_f32_16x16x32_bf16 v[38:41], v[226:229], v[130:133], v[38:41]
	v_mfma_f32_16x16x32_bf16 v[42:45], v[208:211], v[146:149], v[42:45]
	v_mfma_f32_16x16x32_bf16 v[46:49], v[226:229], v[146:149], v[46:49]
	s_setprio 0
	s_add_i32 s67, 0, 0x18000
	v_add_u32_e32 v1, s67, v191
	s_barrier
	ds_read_b128 v[54:57], v1
	ds_read_b128 v[70:73], v1 offset:1024
	ds_read_b128 v[82:85], v1 offset:2048
	ds_read_b128 v[86:89], v1 offset:3072
	s_add_u32 s4, s48, 0x40000
	s_addc_u32 s5, s49, 0
	s_mov_b32 m0, s55
	v_lshl_add_u64 v[134:135], s[4:5], 0, v[164:165]
	ds_read_b128 v[118:121], v206 offset:32768
	ds_read_b128 v[130:133], v206 offset:33792
	ds_read_b128 v[170:173], v206 offset:34816
	ds_read_b128 v[174:177], v206 offset:35840
	ds_read_b128 v[178:181], v206 offset:36864
	ds_read_b128 v[182:185], v206 offset:37888
	ds_read_b128 v[186:189], v206 offset:38912
	ds_read_b128 v[208:211], v206 offset:39936
	global_load_lds_dwordx4 v[134:135], off
	v_lshl_add_u64 v[134:135], s[4:5], 0, v[162:163]
	s_mov_b32 m0, s56
	s_nop 0
	global_load_lds_dwordx4 v[134:135], off
	s_waitcnt lgkmcnt(8)
	s_waitcnt vmcnt(10)
	s_barrier
	s_waitcnt lgkmcnt(0)
	s_setprio 1
	s_waitcnt lgkmcnt(0)
	v_mfma_f32_16x16x32_bf16 v[134:137], v[54:57], v[118:121], v[158:161]
	v_mfma_f32_16x16x32_bf16 v[158:161], v[70:73], v[130:133], v[134:137]
	v_mfma_f32_16x16x32_bf16 v[134:137], v[82:85], v[118:121], v[154:157]
	v_mfma_f32_16x16x32_bf16 v[154:157], v[86:89], v[130:133], v[134:137]
	v_mfma_f32_16x16x32_bf16 v[134:137], v[54:57], v[170:173], v[142:145]
	v_mfma_f32_16x16x32_bf16 v[142:145], v[70:73], v[174:177], v[134:137]
	v_mfma_f32_16x16x32_bf16 v[134:137], v[82:85], v[170:173], v[138:141]
	v_mfma_f32_16x16x32_bf16 v[126:129], v[54:57], v[178:181], v[126:129]
	v_mfma_f32_16x16x32_bf16 v[122:125], v[82:85], v[178:181], v[122:125]
	v_mfma_f32_16x16x32_bf16 v[110:113], v[54:57], v[186:189], v[110:113]
	v_mfma_f32_16x16x32_bf16 v[106:109], v[82:85], v[186:189], v[106:109]
	v_mfma_f32_16x16x32_bf16 v[138:141], v[86:89], v[174:177], v[134:137]
	v_mfma_f32_16x16x32_bf16 v[126:129], v[70:73], v[182:185], v[126:129]
	v_mfma_f32_16x16x32_bf16 v[122:125], v[86:89], v[182:185], v[122:125]
	v_mfma_f32_16x16x32_bf16 v[110:113], v[70:73], v[208:211], v[110:113]
	v_mfma_f32_16x16x32_bf16 v[106:109], v[86:89], v[208:211], v[106:109]
	s_setprio 0
	s_barrier
	s_add_i32 s48, 0, 0x1c000
	s_add_i32 s4, s67, s52
	v_add_u32_e32 v1, s48, v191
	v_lshl_add_u64 v[134:135], v[214:215], 0, s[22:23]
	s_mov_b32 m0, s4
	ds_read_b128 v[222:225], v1
	ds_read_b128 v[226:229], v1 offset:1024
	ds_read_b128 v[230:233], v1 offset:2048
	ds_read_b128 v[234:237], v1 offset:3072
	global_load_lds_dwordx4 v[134:135], off
	v_lshl_add_u64 v[134:135], v[238:239], 0, s[22:23]
	s_add_i32 m0, s4, 0x2000
	s_nop 0
	global_load_lds_dwordx4 v[134:135], off
	s_waitcnt vmcnt(10)
	s_barrier
	s_waitcnt lgkmcnt(0)
	s_setprio 1
	s_waitcnt lgkmcnt(0)
	v_mfma_f32_16x16x32_bf16 v[50:53], v[230:233], v[118:121], v[50:53]
	v_mfma_f32_16x16x32_bf16 v[134:137], v[222:225], v[118:121], v[150:153]
	v_mfma_f32_16x16x32_bf16 v[146:149], v[234:237], v[130:133], v[50:53]
	v_mfma_f32_16x16x32_bf16 v[50:53], v[222:225], v[170:173], v[58:61]
	v_mfma_f32_16x16x32_bf16 v[150:153], v[226:229], v[130:133], v[134:137]
	v_mfma_f32_16x16x32_bf16 v[134:137], v[226:229], v[174:177], v[50:53]
	v_mfma_f32_16x16x32_bf16 v[50:53], v[230:233], v[170:173], v[62:65]
	v_mfma_f32_16x16x32_bf16 v[130:133], v[234:237], v[174:177], v[50:53]
	v_mfma_f32_16x16x32_bf16 v[50:53], v[222:225], v[178:181], v[66:69]
	v_mfma_f32_16x16x32_bf16 v[118:121], v[226:229], v[182:185], v[50:53]
	v_mfma_f32_16x16x32_bf16 v[50:53], v[230:233], v[178:181], v[114:117]
	v_mfma_f32_16x16x32_bf16 v[114:117], v[234:237], v[182:185], v[50:53]
	v_mfma_f32_16x16x32_bf16 v[50:53], v[222:225], v[186:189], v[102:105]
	v_mfma_f32_16x16x32_bf16 v[102:105], v[226:229], v[208:211], v[50:53]
	v_mfma_f32_16x16x32_bf16 v[50:53], v[230:233], v[186:189], v[98:101]
	v_mfma_f32_16x16x32_bf16 v[98:101], v[234:237], v[208:211], v[50:53]
	s_setprio 0
	s_mov_b32 m0, s58
	v_lshl_add_u64 v[186:187], v[240:241], 0, s[22:23]
	s_barrier
	s_nop 2
	ds_read_b128 v[50:53], v206 offset:49152
	ds_read_b128 v[58:61], v206 offset:50176
	ds_read_b128 v[62:65], v206 offset:51200
	ds_read_b128 v[66:69], v206 offset:52224
	ds_read_b128 v[170:173], v206 offset:53248
	ds_read_b128 v[174:177], v206 offset:54272
	ds_read_b128 v[178:181], v206 offset:55296
	ds_read_b128 v[182:185], v206 offset:56320
	global_load_lds_dwordx4 v[186:187], off
	v_lshl_add_u64 v[186:187], v[242:243], 0, s[22:23]
	s_mov_b32 m0, s59
	s_nop 0
	global_load_lds_dwordx4 v[186:187], off
	s_barrier
	s_waitcnt lgkmcnt(0)
	s_setprio 1
	s_waitcnt lgkmcnt(0)
	v_mfma_f32_16x16x32_bf16 v[94:97], v[54:57], v[50:53], v[94:97]
	v_mfma_f32_16x16x32_bf16 v[90:93], v[82:85], v[50:53], v[90:93]
	v_mfma_f32_16x16x32_bf16 v[78:81], v[54:57], v[62:65], v[78:81]
	v_mfma_f32_16x16x32_bf16 v[74:77], v[82:85], v[62:65], v[74:77]
	v_mfma_f32_16x16x32_bf16 v[30:33], v[54:57], v[170:173], v[30:33]
	v_mfma_f32_16x16x32_bf16 v[26:29], v[82:85], v[170:173], v[26:29]
	v_mfma_f32_16x16x32_bf16 v[14:17], v[54:57], v[178:181], v[14:17]
	v_mfma_f32_16x16x32_bf16 v[10:13], v[82:85], v[178:181], v[10:13]
	v_mfma_f32_16x16x32_bf16 v[94:97], v[70:73], v[58:61], v[94:97]
	v_mfma_f32_16x16x32_bf16 v[90:93], v[86:89], v[58:61], v[90:93]
	v_mfma_f32_16x16x32_bf16 v[78:81], v[70:73], v[66:69], v[78:81]
	v_mfma_f32_16x16x32_bf16 v[74:77], v[86:89], v[66:69], v[74:77]
	v_mfma_f32_16x16x32_bf16 v[30:33], v[70:73], v[174:177], v[30:33]
	v_mfma_f32_16x16x32_bf16 v[26:29], v[86:89], v[174:177], v[26:29]
	v_mfma_f32_16x16x32_bf16 v[14:17], v[70:73], v[182:185], v[14:17]
	v_mfma_f32_16x16x32_bf16 v[10:13], v[86:89], v[182:185], v[10:13]
	s_setprio 0
	s_barrier
	s_add_u32 s4, s46, 0x40080
	s_addc_u32 s5, s47, 0
	s_add_i32 s46, s48, s52
	v_lshl_add_u64 v[54:55], s[4:5], 0, v[164:165]
	s_mov_b32 m0, s46
	s_nop 0
	global_load_lds_dwordx4 v[54:55], off
	v_lshl_add_u64 v[54:55], s[4:5], 0, v[162:163]
	s_add_i32 m0, s46, 0x2000
	s_nop 0
	global_load_lds_dwordx4 v[54:55], off
	s_waitcnt vmcnt(10)
	s_barrier
	s_setprio 1
	v_mfma_f32_16x16x32_bf16 v[34:37], v[222:225], v[50:53], v[34:37]
	v_mfma_f32_16x16x32_bf16 v[86:89], v[226:229], v[58:61], v[34:37]
	v_mfma_f32_16x16x32_bf16 v[34:37], v[230:233], v[50:53], v[38:41]
	v_mfma_f32_16x16x32_bf16 v[82:85], v[234:237], v[58:61], v[34:37]
	v_mfma_f32_16x16x32_bf16 v[34:37], v[222:225], v[62:65], v[42:45]
	v_mfma_f32_16x16x32_bf16 v[70:73], v[226:229], v[66:69], v[34:37]
	v_mfma_f32_16x16x32_bf16 v[34:37], v[230:233], v[62:65], v[46:49]
	v_mfma_f32_16x16x32_bf16 v[22:25], v[222:225], v[170:173], v[22:25]
	v_mfma_f32_16x16x32_bf16 v[18:21], v[230:233], v[170:173], v[18:21]
	v_mfma_f32_16x16x32_bf16 v[6:9], v[222:225], v[178:181], v[6:9]
	v_mfma_f32_16x16x32_bf16 v[2:5], v[230:233], v[178:181], v[2:5]
	v_mfma_f32_16x16x32_bf16 v[54:57], v[234:237], v[66:69], v[34:37]
	v_mfma_f32_16x16x32_bf16 v[22:25], v[226:229], v[174:177], v[22:25]
	v_mfma_f32_16x16x32_bf16 v[18:21], v[234:237], v[174:177], v[18:21]
	v_mfma_f32_16x16x32_bf16 v[6:9], v[226:229], v[182:185], v[6:9]
	v_mfma_f32_16x16x32_bf16 v[2:5], v[234:237], v[182:185], v[2:5]
	s_setprio 0
	s_add_i32 s66, s66, 2
	s_add_u32 s64, s64, 0x100
	s_addc_u32 s65, s65, 0
	s_cmp_gt_u32 s66, 13
	s_mov_b64 s[4:5], s[36:37]
	s_barrier
.LBB0_212:
	s_add_u32 s36, s4, 0x100
	s_addc_u32 s37, s5, 0
	s_add_i32 s67, 0, 0x10000
	v_add_u32_e32 v1, s67, v191
	ds_read_b128 v[34:37], v1
	ds_read_b128 v[38:41], v1 offset:1024
	ds_read_b128 v[42:45], v1 offset:2048
	ds_read_b128 v[46:49], v1 offset:3072
	s_cmp_eq_u32 s66, 12
	s_cselect_b32 s49, s38, s37
	s_cselect_b32 s48, s43, s36
	s_cselect_b32 s47, s62, s65
	s_cselect_b32 s46, s63, s64
	v_lshl_add_u64 v[186:187], s[4:5], 0, v[168:169]
	s_add_i32 m0, s53, 0xc000
	ds_read_b128 v[50:53], v206
	ds_read_b128 v[58:61], v206 offset:1024
	ds_read_b128 v[62:65], v206 offset:2048
	ds_read_b128 v[66:69], v206 offset:3072
	ds_read_b128 v[170:173], v206 offset:4096
	ds_read_b128 v[174:177], v206 offset:5120
	ds_read_b128 v[178:181], v206 offset:6144
	ds_read_b128 v[182:185], v206 offset:7168
	global_load_lds_dwordx4 v[186:187], off
	v_lshl_add_u64 v[186:187], s[4:5], 0, v[166:167]
	s_add_i32 m0, s53, 0xe000
	s_nop 0
	global_load_lds_dwordx4 v[186:187], off
	s_waitcnt lgkmcnt(8)
	s_waitcnt vmcnt(10)
	s_barrier
	s_waitcnt lgkmcnt(0)
	s_setprio 1
	s_waitcnt lgkmcnt(0)
	v_mfma_f32_16x16x32_bf16 v[158:161], v[34:37], v[50:53], v[158:161]
	v_mfma_f32_16x16x32_bf16 v[154:157], v[42:45], v[50:53], v[154:157]
	v_mfma_f32_16x16x32_bf16 v[142:145], v[34:37], v[62:65], v[142:145]
	v_mfma_f32_16x16x32_bf16 v[138:141], v[42:45], v[62:65], v[138:141]
	v_mfma_f32_16x16x32_bf16 v[126:129], v[34:37], v[170:173], v[126:129]
	v_mfma_f32_16x16x32_bf16 v[122:125], v[42:45], v[170:173], v[122:125]
	v_mfma_f32_16x16x32_bf16 v[110:113], v[34:37], v[178:181], v[110:113]
	v_mfma_f32_16x16x32_bf16 v[106:109], v[42:45], v[178:181], v[106:109]
	v_mfma_f32_16x16x32_bf16 v[158:161], v[38:41], v[58:61], v[158:161]
	v_mfma_f32_16x16x32_bf16 v[154:157], v[46:49], v[58:61], v[154:157]
	v_mfma_f32_16x16x32_bf16 v[142:145], v[38:41], v[66:69], v[142:145]
	v_mfma_f32_16x16x32_bf16 v[138:141], v[46:49], v[66:69], v[138:141]
	v_mfma_f32_16x16x32_bf16 v[126:129], v[38:41], v[174:177], v[126:129]
	v_mfma_f32_16x16x32_bf16 v[122:125], v[46:49], v[174:177], v[122:125]
	v_mfma_f32_16x16x32_bf16 v[110:113], v[38:41], v[182:185], v[110:113]
	v_mfma_f32_16x16x32_bf16 v[106:109], v[46:49], v[182:185], v[106:109]
	s_setprio 0
	s_barrier
	s_add_i32 s68, 0, 0x14000
	s_add_i32 s4, s67, s52
	v_add_u32_e32 v1, s68, v191
	v_lshl_add_u64 v[214:215], s[46:47], 0, v[164:165]
	s_mov_b32 m0, s4
	ds_read_b128 v[186:189], v1
	ds_read_b128 v[208:211], v1 offset:1024
	ds_read_b128 v[222:225], v1 offset:2048
	ds_read_b128 v[226:229], v1 offset:3072
	global_load_lds_dwordx4 v[214:215], off
	v_lshl_add_u64 v[238:239], s[46:47], 0, v[162:163]
	s_add_i32 m0, s4, 0x2000
	s_nop 0
	global_load_lds_dwordx4 v[238:239], off
	s_waitcnt vmcnt(10)
	s_barrier
	s_waitcnt lgkmcnt(0)
	s_setprio 1
	s_waitcnt lgkmcnt(0)
	v_mfma_f32_16x16x32_bf16 v[150:153], v[186:189], v[50:53], v[150:153]
	v_mfma_f32_16x16x32_bf16 v[50:53], v[222:225], v[50:53], v[146:149]
	v_mfma_f32_16x16x32_bf16 v[150:153], v[208:211], v[58:61], v[150:153]
	v_mfma_f32_16x16x32_bf16 v[50:53], v[226:229], v[58:61], v[50:53]
	v_mfma_f32_16x16x32_bf16 v[58:61], v[186:189], v[62:65], v[134:137]
	v_mfma_f32_16x16x32_bf16 v[62:65], v[222:225], v[62:65], v[130:133]
	v_mfma_f32_16x16x32_bf16 v[114:117], v[222:225], v[170:173], v[114:117]
	v_mfma_f32_16x16x32_bf16 v[102:105], v[186:189], v[178:181], v[102:105]
	v_mfma_f32_16x16x32_bf16 v[98:101], v[222:225], v[178:181], v[98:101]
	v_mfma_f32_16x16x32_bf16 v[58:61], v[208:211], v[66:69], v[58:61]
	v_mfma_f32_16x16x32_bf16 v[62:65], v[226:229], v[66:69], v[62:65]
	v_mfma_f32_16x16x32_bf16 v[66:69], v[186:189], v[170:173], v[118:121]
	v_mfma_f32_16x16x32_bf16 v[114:117], v[226:229], v[174:177], v[114:117]
	v_mfma_f32_16x16x32_bf16 v[102:105], v[208:211], v[182:185], v[102:105]
	v_mfma_f32_16x16x32_bf16 v[98:101], v[226:229], v[182:185], v[98:101]
	v_mfma_f32_16x16x32_bf16 v[66:69], v[208:211], v[174:177], v[66:69]
	s_setprio 0
	s_mov_b32 m0, s53
	v_lshl_add_u64 v[240:241], s[48:49], 0, v[164:165]
	s_barrier
	ds_read_b128 v[118:121], v206 offset:16384
	ds_read_b128 v[130:133], v206 offset:17408
	ds_read_b128 v[134:137], v206 offset:18432
	ds_read_b128 v[146:149], v206 offset:19456
	ds_read_b128 v[170:173], v206 offset:20480
	ds_read_b128 v[174:177], v206 offset:21504
	ds_read_b128 v[178:181], v206 offset:22528
	ds_read_b128 v[182:185], v206 offset:23552
	global_load_lds_dwordx4 v[240:241], off
	v_lshl_add_u64 v[242:243], s[48:49], 0, v[162:163]
	s_mov_b32 m0, s54
	s_nop 0
	global_load_lds_dwordx4 v[242:243], off
	s_barrier
	s_waitcnt lgkmcnt(0)
	s_setprio 1
	s_waitcnt lgkmcnt(0)
	v_mfma_f32_16x16x32_bf16 v[94:97], v[34:37], v[118:121], v[94:97]
	v_mfma_f32_16x16x32_bf16 v[90:93], v[42:45], v[118:121], v[90:93]
	v_mfma_f32_16x16x32_bf16 v[78:81], v[34:37], v[134:137], v[78:81]
	v_mfma_f32_16x16x32_bf16 v[74:77], v[42:45], v[134:137], v[74:77]
	v_mfma_f32_16x16x32_bf16 v[30:33], v[34:37], v[170:173], v[30:33]
	v_mfma_f32_16x16x32_bf16 v[26:29], v[42:45], v[170:173], v[26:29]
	v_mfma_f32_16x16x32_bf16 v[14:17], v[34:37], v[178:181], v[14:17]
	v_mfma_f32_16x16x32_bf16 v[10:13], v[42:45], v[178:181], v[10:13]
	v_mfma_f32_16x16x32_bf16 v[94:97], v[38:41], v[130:133], v[94:97]
	v_mfma_f32_16x16x32_bf16 v[90:93], v[46:49], v[130:133], v[90:93]
	v_mfma_f32_16x16x32_bf16 v[78:81], v[38:41], v[146:149], v[78:81]
	v_mfma_f32_16x16x32_bf16 v[74:77], v[46:49], v[146:149], v[74:77]
	v_mfma_f32_16x16x32_bf16 v[30:33], v[38:41], v[174:177], v[30:33]
	v_mfma_f32_16x16x32_bf16 v[26:29], v[46:49], v[174:177], v[26:29]
	v_mfma_f32_16x16x32_bf16 v[14:17], v[38:41], v[182:185], v[14:17]
	v_mfma_f32_16x16x32_bf16 v[10:13], v[46:49], v[182:185], v[10:13]
	s_setprio 0
	s_barrier
	s_add_u32 s4, s46, 0x40000
	s_addc_u32 s5, s47, 0
	s_add_i32 s67, s68, s52
	v_lshl_add_u64 v[34:35], s[4:5], 0, v[164:165]
	s_mov_b32 m0, s67
	s_nop 0
	global_load_lds_dwordx4 v[34:35], off
	v_lshl_add_u64 v[34:35], s[4:5], 0, v[162:163]
	s_add_i32 m0, s67, 0x2000
	s_nop 0
	global_load_lds_dwordx4 v[34:35], off
	s_waitcnt vmcnt(10)
	s_barrier
	s_setprio 1
	v_mfma_f32_16x16x32_bf16 v[22:25], v[186:189], v[170:173], v[22:25]
	v_mfma_f32_16x16x32_bf16 v[18:21], v[222:225], v[170:173], v[18:21]
	v_mfma_f32_16x16x32_bf16 v[6:9], v[186:189], v[178:181], v[6:9]
	v_mfma_f32_16x16x32_bf16 v[2:5], v[222:225], v[178:181], v[2:5]
	v_mfma_f32_16x16x32_bf16 v[34:37], v[186:189], v[118:121], v[86:89]
	v_mfma_f32_16x16x32_bf16 v[38:41], v[222:225], v[118:121], v[82:85]
	v_mfma_f32_16x16x32_bf16 v[42:45], v[186:189], v[134:137], v[70:73]
	v_mfma_f32_16x16x32_bf16 v[46:49], v[222:225], v[134:137], v[54:57]
	v_mfma_f32_16x16x32_bf16 v[22:25], v[208:211], v[174:177], v[22:25]
	v_mfma_f32_16x16x32_bf16 v[18:21], v[226:229], v[174:177], v[18:21]
	v_mfma_f32_16x16x32_bf16 v[6:9], v[208:211], v[182:185], v[6:9]
	v_mfma_f32_16x16x32_bf16 v[2:5], v[226:229], v[182:185], v[2:5]
	v_mfma_f32_16x16x32_bf16 v[34:37], v[208:211], v[130:133], v[34:37]
	v_mfma_f32_16x16x32_bf16 v[38:41], v[226:229], v[130:133], v[38:41]
	v_mfma_f32_16x16x32_bf16 v[42:45], v[208:211], v[146:149], v[42:45]
	v_mfma_f32_16x16x32_bf16 v[46:49], v[226:229], v[146:149], v[46:49]
	s_setprio 0
	s_add_i32 s67, 0, 0x18000
	v_add_u32_e32 v1, s67, v191
	s_barrier
	ds_read_b128 v[54:57], v1
	ds_read_b128 v[70:73], v1 offset:1024
	ds_read_b128 v[82:85], v1 offset:2048
	ds_read_b128 v[86:89], v1 offset:3072
	s_add_u32 s4, s48, 0x40000
	s_addc_u32 s5, s49, 0
	s_mov_b32 m0, s55
	v_lshl_add_u64 v[134:135], s[4:5], 0, v[164:165]
	ds_read_b128 v[118:121], v206 offset:32768
	ds_read_b128 v[130:133], v206 offset:33792
	ds_read_b128 v[170:173], v206 offset:34816
	ds_read_b128 v[174:177], v206 offset:35840
	ds_read_b128 v[178:181], v206 offset:36864
	ds_read_b128 v[182:185], v206 offset:37888
	ds_read_b128 v[186:189], v206 offset:38912
	ds_read_b128 v[208:211], v206 offset:39936
	global_load_lds_dwordx4 v[134:135], off
	v_lshl_add_u64 v[134:135], s[4:5], 0, v[162:163]
	s_mov_b32 m0, s56
	s_nop 0
	global_load_lds_dwordx4 v[134:135], off
	s_waitcnt lgkmcnt(8)
	s_waitcnt vmcnt(10)
	s_barrier
	s_waitcnt lgkmcnt(0)
	s_setprio 1
	s_waitcnt lgkmcnt(0)
	v_mfma_f32_16x16x32_bf16 v[134:137], v[54:57], v[118:121], v[158:161]
	v_mfma_f32_16x16x32_bf16 v[158:161], v[70:73], v[130:133], v[134:137]
	v_mfma_f32_16x16x32_bf16 v[134:137], v[82:85], v[118:121], v[154:157]
	v_mfma_f32_16x16x32_bf16 v[154:157], v[86:89], v[130:133], v[134:137]
	v_mfma_f32_16x16x32_bf16 v[134:137], v[54:57], v[170:173], v[142:145]
	v_mfma_f32_16x16x32_bf16 v[142:145], v[70:73], v[174:177], v[134:137]
	v_mfma_f32_16x16x32_bf16 v[134:137], v[82:85], v[170:173], v[138:141]
	v_mfma_f32_16x16x32_bf16 v[126:129], v[54:57], v[178:181], v[126:129]
	v_mfma_f32_16x16x32_bf16 v[122:125], v[82:85], v[178:181], v[122:125]
	v_mfma_f32_16x16x32_bf16 v[110:113], v[54:57], v[186:189], v[110:113]
	v_mfma_f32_16x16x32_bf16 v[106:109], v[82:85], v[186:189], v[106:109]
	v_mfma_f32_16x16x32_bf16 v[138:141], v[86:89], v[174:177], v[134:137]
	v_mfma_f32_16x16x32_bf16 v[126:129], v[70:73], v[182:185], v[126:129]
	v_mfma_f32_16x16x32_bf16 v[122:125], v[86:89], v[182:185], v[122:125]
	v_mfma_f32_16x16x32_bf16 v[110:113], v[70:73], v[208:211], v[110:113]
	v_mfma_f32_16x16x32_bf16 v[106:109], v[86:89], v[208:211], v[106:109]
	s_setprio 0
	s_barrier
	s_add_i32 s48, 0, 0x1c000
	s_add_i32 s4, s67, s52
	v_add_u32_e32 v1, s48, v191
	v_lshl_add_u64 v[134:135], v[214:215], 0, s[22:23]
	s_mov_b32 m0, s4
	ds_read_b128 v[222:225], v1
	ds_read_b128 v[226:229], v1 offset:1024
	ds_read_b128 v[230:233], v1 offset:2048
	ds_read_b128 v[234:237], v1 offset:3072
	global_load_lds_dwordx4 v[134:135], off
	v_lshl_add_u64 v[134:135], v[238:239], 0, s[22:23]
	s_add_i32 m0, s4, 0x2000
	s_nop 0
	global_load_lds_dwordx4 v[134:135], off
	s_waitcnt vmcnt(10)
	s_barrier
	s_waitcnt lgkmcnt(0)
	s_setprio 1
	s_waitcnt lgkmcnt(0)
	v_mfma_f32_16x16x32_bf16 v[50:53], v[230:233], v[118:121], v[50:53]
	v_mfma_f32_16x16x32_bf16 v[134:137], v[222:225], v[118:121], v[150:153]
	v_mfma_f32_16x16x32_bf16 v[146:149], v[234:237], v[130:133], v[50:53]
	v_mfma_f32_16x16x32_bf16 v[50:53], v[222:225], v[170:173], v[58:61]
	v_mfma_f32_16x16x32_bf16 v[150:153], v[226:229], v[130:133], v[134:137]
	v_mfma_f32_16x16x32_bf16 v[134:137], v[226:229], v[174:177], v[50:53]
	v_mfma_f32_16x16x32_bf16 v[50:53], v[230:233], v[170:173], v[62:65]
	v_mfma_f32_16x16x32_bf16 v[130:133], v[234:237], v[174:177], v[50:53]
	v_mfma_f32_16x16x32_bf16 v[50:53], v[222:225], v[178:181], v[66:69]
	v_mfma_f32_16x16x32_bf16 v[118:121], v[226:229], v[182:185], v[50:53]
	v_mfma_f32_16x16x32_bf16 v[50:53], v[230:233], v[178:181], v[114:117]
	v_mfma_f32_16x16x32_bf16 v[114:117], v[234:237], v[182:185], v[50:53]
	v_mfma_f32_16x16x32_bf16 v[50:53], v[222:225], v[186:189], v[102:105]
	v_mfma_f32_16x16x32_bf16 v[102:105], v[226:229], v[208:211], v[50:53]
	v_mfma_f32_16x16x32_bf16 v[50:53], v[230:233], v[186:189], v[98:101]
	v_mfma_f32_16x16x32_bf16 v[98:101], v[234:237], v[208:211], v[50:53]
	s_setprio 0
	s_mov_b32 m0, s58
	v_lshl_add_u64 v[186:187], v[240:241], 0, s[22:23]
	s_barrier
	s_nop 2
	ds_read_b128 v[50:53], v206 offset:49152
	ds_read_b128 v[58:61], v206 offset:50176
	ds_read_b128 v[62:65], v206 offset:51200
	ds_read_b128 v[66:69], v206 offset:52224
	ds_read_b128 v[170:173], v206 offset:53248
	ds_read_b128 v[174:177], v206 offset:54272
	ds_read_b128 v[178:181], v206 offset:55296
	ds_read_b128 v[182:185], v206 offset:56320
	global_load_lds_dwordx4 v[186:187], off
	v_lshl_add_u64 v[186:187], v[242:243], 0, s[22:23]
	s_mov_b32 m0, s59
	s_nop 0
	global_load_lds_dwordx4 v[186:187], off
	s_barrier
	s_waitcnt lgkmcnt(0)
	s_setprio 1
	s_waitcnt lgkmcnt(0)
	v_mfma_f32_16x16x32_bf16 v[94:97], v[54:57], v[50:53], v[94:97]
	v_mfma_f32_16x16x32_bf16 v[90:93], v[82:85], v[50:53], v[90:93]
	v_mfma_f32_16x16x32_bf16 v[78:81], v[54:57], v[62:65], v[78:81]
	v_mfma_f32_16x16x32_bf16 v[74:77], v[82:85], v[62:65], v[74:77]
	v_mfma_f32_16x16x32_bf16 v[30:33], v[54:57], v[170:173], v[30:33]
	v_mfma_f32_16x16x32_bf16 v[26:29], v[82:85], v[170:173], v[26:29]
	v_mfma_f32_16x16x32_bf16 v[14:17], v[54:57], v[178:181], v[14:17]
	v_mfma_f32_16x16x32_bf16 v[10:13], v[82:85], v[178:181], v[10:13]
	v_mfma_f32_16x16x32_bf16 v[94:97], v[70:73], v[58:61], v[94:97]
	v_mfma_f32_16x16x32_bf16 v[90:93], v[86:89], v[58:61], v[90:93]
	v_mfma_f32_16x16x32_bf16 v[78:81], v[70:73], v[66:69], v[78:81]
	v_mfma_f32_16x16x32_bf16 v[74:77], v[86:89], v[66:69], v[74:77]
	v_mfma_f32_16x16x32_bf16 v[30:33], v[70:73], v[174:177], v[30:33]
	v_mfma_f32_16x16x32_bf16 v[26:29], v[86:89], v[174:177], v[26:29]
	v_mfma_f32_16x16x32_bf16 v[14:17], v[70:73], v[182:185], v[14:17]
	v_mfma_f32_16x16x32_bf16 v[10:13], v[86:89], v[182:185], v[10:13]
	s_setprio 0
	s_barrier
	s_add_u32 s4, s46, 0x40080
	s_addc_u32 s5, s47, 0
	s_add_i32 s46, s48, s52
	v_lshl_add_u64 v[54:55], s[4:5], 0, v[164:165]
	s_mov_b32 m0, s46
	s_nop 0
	global_load_lds_dwordx4 v[54:55], off
	v_lshl_add_u64 v[54:55], s[4:5], 0, v[162:163]
	s_add_i32 m0, s46, 0x2000
	s_nop 0
	global_load_lds_dwordx4 v[54:55], off
	s_waitcnt vmcnt(10)
	s_barrier
	s_setprio 1
	v_mfma_f32_16x16x32_bf16 v[34:37], v[222:225], v[50:53], v[34:37]
	v_mfma_f32_16x16x32_bf16 v[86:89], v[226:229], v[58:61], v[34:37]
	v_mfma_f32_16x16x32_bf16 v[34:37], v[230:233], v[50:53], v[38:41]
	v_mfma_f32_16x16x32_bf16 v[82:85], v[234:237], v[58:61], v[34:37]
	v_mfma_f32_16x16x32_bf16 v[34:37], v[222:225], v[62:65], v[42:45]
	v_mfma_f32_16x16x32_bf16 v[70:73], v[226:229], v[66:69], v[34:37]
	v_mfma_f32_16x16x32_bf16 v[34:37], v[230:233], v[62:65], v[46:49]
	v_mfma_f32_16x16x32_bf16 v[22:25], v[222:225], v[170:173], v[22:25]
	v_mfma_f32_16x16x32_bf16 v[18:21], v[230:233], v[170:173], v[18:21]
	v_mfma_f32_16x16x32_bf16 v[6:9], v[222:225], v[178:181], v[6:9]
	v_mfma_f32_16x16x32_bf16 v[2:5], v[230:233], v[178:181], v[2:5]
	v_mfma_f32_16x16x32_bf16 v[54:57], v[234:237], v[66:69], v[34:37]
	v_mfma_f32_16x16x32_bf16 v[22:25], v[226:229], v[174:177], v[22:25]
	v_mfma_f32_16x16x32_bf16 v[18:21], v[234:237], v[174:177], v[18:21]
	v_mfma_f32_16x16x32_bf16 v[6:9], v[226:229], v[182:185], v[6:9]
	v_mfma_f32_16x16x32_bf16 v[2:5], v[234:237], v[182:185], v[2:5]
	s_setprio 0
	s_add_i32 s66, s66, 2
	s_add_u32 s64, s64, 0x100
	s_addc_u32 s65, s65, 0
	s_cmp_gt_u32 s66, 13
	s_mov_b64 s[4:5], s[36:37]
	s_barrier
	s_cbranch_scc0 .LBB0_212
	v_lshl_or_b32 v208, s3, 8, v192
	v_mov_b32_e32 v1, v190
	v_ashrrev_i32_e32 v209, 31, v208
	v_lshlrev_b64 v[34:35], 2, v[208:209]
	v_lshl_add_u64 v[36:37], s[8:9], 0, v[34:35]
	flat_load_dwordx4 v[62:65], v[36:37]
	flat_load_dwordx4 v[50:53], v[36:37] offset:16
	v_lshl_add_u64 v[34:35], s[10:11], 0, v[34:35]
	flat_load_dwordx4 v[66:69], v[34:35]
	flat_load_dwordx4 v[42:45], v[34:35] offset:16
	flat_load_dwordx4 v[58:61], v[36:37] offset:512
	flat_load_dwordx4 v[38:41], v[36:37] offset:528
	flat_load_dwordx4 v[46:49], v[34:35] offset:512
	s_nop 0
	flat_load_dwordx4 v[34:37], v[34:35] offset:528
	s_lshl_b32 s37, s27, 8
	v_lshl_add_u32 v170, v1, 3, 0
	v_add_u32_e32 v170, 0x20040, v170
	s_waitcnt vmcnt(0)
	ds_read_b64 v[188:189], v170
	s_mov_b32 s4, 0xbf3a00e3
	s_cmp_gt_i32 s3, 3
	v_mov_b64_e32 v[176:177], s[4:5]
	s_cselect_b64 s[4:5], -1, 0
	s_and_b64 s[46:47], s[40:41], s[4:5]
	s_mov_b32 s4, 0x3f07dc22
	s_mov_b32 s38, 0x3f35f0e3
	s_mov_b32 s48, 0xbe11a98e
	s_mov_b32 s62, 0x3e027906
	s_lshl_b32 s3, s3, 2
	s_and_b32 s36, s3, 12
	s_mov_b32 s3, 0x1020000
	v_add_u32_e32 v170, s37, v1
	v_lshlrev_b32_e32 v1, 10, v170
	s_waitcnt lgkmcnt(0)
	v_xor_b32_e32 v65, 0x80000000, v65
	v_xor_b32_e32 v64, 0x80000000, v64
	v_pk_fma_f32 v[158:159], v[62:63], v[188:189], v[158:159] op_sel_hi:[1,0,1] neg_lo:[1,0,0] neg_hi:[1,0,0]
	v_xor_b32_e32 v53, 0x80000000, v53
	v_xor_b32_e32 v52, 0x80000000, v52
	v_pk_fma_f32 v[154:155], v[50:51], v[188:189], v[154:155] op_sel_hi:[1,0,1] neg_lo:[1,0,0] neg_hi:[1,0,0]
	v_pk_fma_f32 v[160:161], v[64:65], v[188:189], v[160:161] op_sel_hi:[1,0,1]
	v_pk_fma_f32 v[158:159], v[188:189], v[158:159], v[66:67] op_sel:[1,0,0]
	v_pk_fma_f32 v[172:173], v[52:53], v[188:189], v[156:157] op_sel_hi:[1,0,1]
	v_pk_fma_f32 v[156:157], v[188:189], v[154:155], v[42:43] op_sel:[1,0,0]
	v_pk_fma_f32 v[154:155], v[188:189], v[160:161], v[68:69] op_sel:[1,0,0]
	v_fma_f32 v175, |v159|, s1, 1.0
	v_fma_f32 v171, |v158|, s1, 1.0
	v_pk_fma_f32 v[160:161], v[188:189], v[172:173], v[44:45] op_sel:[1,0,0]
	v_fma_f32 v172, |v156|, s1, 1.0
	v_rcp_f32_e32 v175, v175
	v_fma_f32 v187, |v155|, s1, 1.0
	v_mul_f32_e32 v174, v158, v158
	v_rcp_f32_e32 v182, v171
	v_rcp_f32_e32 v183, v172
	v_rcp_f32_e32 v215, v187
	v_mul_f32_e32 v173, v156, v156
	v_fma_f32 v179, |v157|, s1, 1.0
	v_mul_f32_e32 v180, v157, v157
	v_mul_f32_e32 v171, 0xbf38aa3b, v174
	v_mul_f32_e32 v186, v154, v154
	v_fma_f32 v181, |v154|, s1, 1.0
	v_mul_f32_e32 v172, 0xbf38aa3b, v173
	v_rcp_f32_e32 v185, v179
	v_mul_f32_e32 v173, 0xbf38aa3b, v180
	v_fma_f32 v179, |v160|, s1, 1.0
	v_mul_f32_e32 v209, v160, v160
	v_exp_f32_e32 v180, v171
	v_mul_f32_e32 v171, 0xbf38aa3b, v186
	v_fma_f32 v211, |v161|, s1, 1.0
	v_rcp_f32_e32 v184, v181
	v_exp_f32_e32 v181, v172
	v_rcp_f32_e32 v210, v179
	v_mul_f32_e32 v179, 0xbf38aa3b, v209
	v_exp_f32_e32 v172, v171
	v_fmamk_f32 v171, v175, 0x3f07dc22, v218
	v_rcp_f32_e32 v211, v211
	v_exp_f32_e32 v214, v179
	v_pk_fma_f32 v[186:187], v[182:183], s[4:5], v[176:177] op_sel_hi:[1,0,0]
	v_fmaak_f32 v171, v175, v171, 0x3f35f0e3
	v_fmamk_f32 v179, v215, 0x3f07dc22, v218
	v_pk_fma_f32 v[186:187], v[182:183], v[186:187], s[38:39] op_sel_hi:[1,1,0]
	v_fmaak_f32 v171, v175, v171, 0xbe11a98e
	v_fmaak_f32 v179, v215, v179, 0x3f35f0e3
	v_pk_fma_f32 v[186:187], v[182:183], v[186:187], s[48:49] op_sel_hi:[1,1,0]
	v_fmaak_f32 v171, v175, v171, 0x3e027906
	v_fmaak_f32 v179, v215, v179, 0xbe11a98e
	v_mul_f32_e32 v212, v161, v161
	v_pk_fma_f32 v[224:225], v[182:183], v[186:187], s[62:63] op_sel_hi:[1,1,0]
	v_mul_f32_e32 v186, v175, v171
	v_fmaak_f32 v171, v215, v179, 0x3e027906
	v_pk_fma_f32 v[222:223], v[184:185], s[4:5], v[176:177] op_sel_hi:[1,0,0]
	v_pk_mul_f32 v[224:225], v[182:183], v[224:225]
	v_mul_f32_e32 v182, v215, v171
	v_mul_f32_e32 v171, 0xbf38aa3b, v212
	v_pk_fma_f32 v[176:177], v[210:211], s[4:5], v[176:177] op_sel_hi:[1,0,0]
	v_exp_f32_e32 v215, v171
	v_pk_fma_f32 v[176:177], v[210:211], v[176:177], s[38:39] op_sel_hi:[1,1,0]
	v_cmp_gt_f32_e32 vcc, 0, v161
	v_pk_fma_f32 v[176:177], v[210:211], v[176:177], s[48:49] op_sel_hi:[1,1,0]
	v_pk_fma_f32 v[150:151], v[58:59], v[188:189], v[150:151] op_sel_hi:[1,0,1] neg_lo:[1,0,0] neg_hi:[1,0,0]
	v_pk_fma_f32 v[176:177], v[210:211], v[176:177], s[62:63] op_sel_hi:[1,1,0]
	v_pk_fma_f32 v[150:151], v[188:189], v[150:151], v[46:47] op_sel:[1,0,0]
	v_pk_mul_f32 v[176:177], v[210:211], v[176:177]
	v_fma_f32 v175, |v150|, s1, 1.0
	v_pk_mul_f32 v[176:177], v[214:215], v[176:177]
	v_rcp_f32_e32 v175, v175
	v_pk_mul_f32 v[210:211], v[160:161], v[176:177]
	v_pk_fma_f32 v[176:177], v[160:161], v[176:177], v[160:161] neg_lo:[1,0,0] neg_hi:[1,0,0]
	v_mul_f32_e32 v178, v159, v159
	v_cndmask_b32_e32 v177, v177, v211, vcc
	v_cmp_gt_f32_e32 vcc, 0, v160
	v_xor_b32_e32 v61, 0x80000000, v61
	v_xor_b32_e32 v60, 0x80000000, v60
	v_cndmask_b32_e32 v176, v176, v210, vcc
	v_mul_f32_e32 v160, v176, v176
	v_pk_fma_f32 v[160:161], v[176:177], v[176:177], v[160:161] op_sel_hi:[1,1,0]
	v_mul_f32_e32 v174, 0xbf38aa3b, v178
	v_lshrrev_b32_e32 v160, 10, v208
	v_mul_f32_e32 v207, v155, v155
	v_mul_lo_u32 v160, v160, s3
	s_movk_i32 s4, 0x3ff
	v_pk_fma_f32 v[152:153], v[60:61], v[188:189], v[152:153] op_sel_hi:[1,0,1]
	v_exp_f32_e32 v178, v174
	v_mul_f32_e32 v174, 0xbf38aa3b, v207
	v_and_or_b32 v207, v208, s4, v160
	v_add_u32_e32 v171, 0x80, v208
	v_pk_fma_f32 v[208:209], v[188:189], v[152:153], v[48:49] op_sel:[1,0,0]
	v_fmamk_f32 v152, v175, 0x3f07dc22, v218
	v_fmaak_f32 v152, v175, v152, 0x3f35f0e3
	v_mul_f32_e32 v153, v150, v150
	v_mul_f32_e32 v153, 0xbf38aa3b, v153
	v_fmaak_f32 v152, v175, v152, 0xbe11a98e
	v_exp_f32_e32 v153, v153
	v_fmaak_f32 v152, v175, v152, 0x3e027906
	v_mul_f32_e32 v152, v175, v152
	v_fma_f32 v175, |v151|, s1, 1.0
	v_rcp_f32_e32 v175, v175
	v_mul_f32_e32 v152, v153, v152
	v_mul_f32_e32 v153, v150, v152
	v_fma_f32 v152, -v150, v152, v150
	v_cmp_gt_f32_e32 vcc, 0, v150
	v_pk_fma_f32 v[146:147], v[38:39], v[188:189], v[146:147] op_sel_hi:[1,0,1] neg_lo:[1,0,0] neg_hi:[1,0,0]
	v_xor_b32_e32 v41, 0x80000000, v41
	v_cndmask_b32_e32 v150, v152, v153, vcc
	v_fmamk_f32 v152, v175, 0x3f07dc22, v218
	v_fmaak_f32 v152, v175, v152, 0x3f35f0e3
	v_mul_f32_e32 v153, v151, v151
	v_fmaak_f32 v152, v175, v152, 0xbe11a98e
	v_mul_f32_e32 v153, 0xbf38aa3b, v153
	v_fmaak_f32 v152, v175, v152, 0x3e027906
	v_exp_f32_e32 v153, v153
	v_mul_f32_e32 v152, v175, v152
	v_fma_f32 v175, |v208|, s1, 1.0
	v_rcp_f32_e32 v175, v175
	v_mul_f32_e32 v152, v153, v152
	v_mul_f32_e32 v153, v151, v152
	v_fma_f32 v152, -v151, v152, v151
	v_cmp_gt_f32_e32 vcc, 0, v151
	v_fmamk_f32 v151, v175, 0x3f07dc22, v218
	v_fmaak_f32 v151, v175, v151, 0x3f35f0e3
	v_cndmask_b32_e32 v152, v152, v153, vcc
	v_mul_f32_e32 v153, v208, v208
	v_mul_f32_e32 v153, 0xbf38aa3b, v153
	v_fmaak_f32 v151, v175, v151, 0xbe11a98e
	v_exp_f32_e32 v153, v153
	v_fmaak_f32 v151, v175, v151, 0x3e027906
	v_mul_f32_e32 v151, v175, v151
	v_fma_f32 v175, |v209|, s1, 1.0
	v_rcp_f32_e32 v175, v175
	v_mul_f32_e32 v151, v153, v151
	v_mul_f32_e32 v153, v208, v151
	v_fma_f32 v151, -v208, v151, v208
	v_cmp_gt_f32_e32 vcc, 0, v208
	v_pk_fma_f32 v[146:147], v[188:189], v[146:147], v[34:35] op_sel:[1,0,0]
	v_xor_b32_e32 v40, 0x80000000, v40
	v_cndmask_b32_e32 v208, v151, v153, vcc
	v_fmamk_f32 v151, v175, 0x3f07dc22, v218
	v_fmaak_f32 v151, v175, v151, 0x3f35f0e3
	v_fmaak_f32 v151, v175, v151, 0xbe11a98e
	v_fmaak_f32 v151, v175, v151, 0x3e027906
	v_mul_f32_e32 v151, v175, v151
	v_fma_f32 v175, |v146|, s1, 1.0
	v_rcp_f32_e32 v175, v175
	v_mul_f32_e32 v183, v146, v146
	v_mul_f32_e32 v153, v209, v209
	v_mul_f32_e32 v183, 0xbf38aa3b, v183
	v_fmamk_f32 v179, v175, 0x3f07dc22, v218
	v_mul_f32_e32 v153, 0xbf38aa3b, v153
	v_fmaak_f32 v179, v175, v179, 0x3f35f0e3
	v_exp_f32_e32 v183, v183
	v_exp_f32_e32 v153, v153
	v_fmaak_f32 v179, v175, v179, 0xbe11a98e
	v_fmaak_f32 v179, v175, v179, 0x3e027906
	v_mul_f32_e32 v175, v175, v179
	v_mul_f32_e32 v175, v183, v175
	v_fma_f32 v183, |v147|, s1, 1.0
	v_mul_f32_e32 v151, v153, v151
	v_rcp_f32_e32 v183, v183
	v_mul_f32_e32 v153, v209, v151
	v_fma_f32 v151, -v209, v151, v209
	v_cmp_gt_f32_e32 vcc, 0, v209
	v_mul_f32_e32 v179, v146, v175
	v_fma_f32 v175, -v146, v175, v146
	v_cndmask_b32_e32 v210, v151, v153, vcc
	v_cmp_gt_f32_e32 vcc, 0, v146
	v_pk_fma_f32 v[148:149], v[40:41], v[188:189], v[148:149] op_sel_hi:[1,0,1]
	v_fmamk_f32 v146, v183, 0x3f07dc22, v218
	v_cndmask_b32_e32 v214, v175, v179, vcc
	v_mul_f32_e32 v175, v147, v147
	v_mul_f32_e32 v175, 0xbf38aa3b, v175
	v_pk_fma_f32 v[148:149], v[188:189], v[148:149], v[36:37] op_sel:[1,0,0]
	v_fmaak_f32 v146, v183, v146, 0x3f35f0e3
	v_exp_f32_e32 v175, v175
	v_fmaak_f32 v146, v183, v146, 0xbe11a98e
	v_fma_f32 v179, |v148|, s1, 1.0
	v_fmaak_f32 v146, v183, v146, 0x3e027906
	v_rcp_f32_e32 v179, v179
	v_pk_fma_f32 v[222:223], v[184:185], v[222:223], s[38:39] op_sel_hi:[1,1,0]
	v_mul_f32_e32 v146, v183, v146
	v_pk_fma_f32 v[222:223], v[184:185], v[222:223], s[48:49] op_sel_hi:[1,1,0]
	v_mul_f32_e32 v146, v175, v146
	v_pk_fma_f32 v[222:223], v[184:185], v[222:223], s[62:63] op_sel_hi:[1,1,0]
	v_mul_f32_e32 v175, v147, v146
	v_fma_f32 v146, -v147, v146, v147
	v_cmp_gt_f32_e32 vcc, 0, v147
	v_mul_f32_e32 v147, v148, v148
	v_pk_mul_f32 v[184:185], v[184:185], v[222:223]
	v_cndmask_b32_e32 v222, v146, v175, vcc
	v_fmamk_f32 v146, v179, 0x3f07dc22, v218
	v_mul_f32_e32 v147, 0xbf38aa3b, v147
	v_fmaak_f32 v146, v179, v146, 0x3f35f0e3
	v_exp_f32_e32 v147, v147
	v_fmaak_f32 v146, v179, v146, 0xbe11a98e
	v_fmaak_f32 v146, v179, v146, 0x3e027906
	v_fma_f32 v175, |v149|, s1, 1.0
	v_mul_f32_e32 v146, v179, v146
	v_rcp_f32_e32 v175, v175
	v_mul_f32_e32 v146, v147, v146
	v_mul_f32_e32 v147, v148, v146
	v_fma_f32 v146, -v148, v146, v148
	v_cmp_gt_f32_e32 vcc, 0, v148
	v_exp_f32_e32 v173, v173
	v_exp_f32_e32 v174, v174
	v_cndmask_b32_e32 v226, v146, v147, vcc
	v_mul_f32_e32 v147, v149, v149
	v_fmamk_f32 v146, v175, 0x3f07dc22, v218
	v_mul_f32_e32 v147, 0xbf38aa3b, v147
	v_fmaak_f32 v146, v175, v146, 0x3f35f0e3
	v_exp_f32_e32 v147, v147
	v_fmaak_f32 v146, v175, v146, 0xbe11a98e
	v_fmaak_f32 v146, v175, v146, 0x3e027906
	v_mul_f32_e32 v146, v175, v146
	v_mul_f32_e32 v146, v147, v146
	v_mul_f32_e32 v147, v149, v146
	v_fma_f32 v146, -v149, v146, v149
	v_cmp_gt_f32_e32 vcc, 0, v149
	v_mov_b32_e32 v179, v181
	v_mov_b32_e32 v187, v225
	v_cndmask_b32_e32 v228, v146, v147, vcc
	v_lshrrev_b32_e32 v146, 10, v171
	v_mul_lo_u32 v146, v146, s3
	v_and_or_b32 v188, v171, s4, v146
	v_pk_mul_f32 v[146:147], v[180:181], v[224:225]
	v_pk_mul_f32 v[148:149], v[178:179], v[186:187]
	v_mov_b32_e32 v178, v158
	v_mov_b32_e32 v179, v156
	v_pk_mov_b32 v[186:187], v[158:159], v[156:157] op_sel:[1,0]
	v_pk_mul_f32 v[180:181], v[178:179], v[146:147]
	v_pk_mul_f32 v[224:225], v[186:187], v[148:149]
	v_pk_fma_f32 v[146:147], v[178:179], v[146:147], v[178:179] neg_lo:[1,0,0] neg_hi:[1,0,0]
	v_pk_fma_f32 v[148:149], v[186:187], v[148:149], v[186:187] neg_lo:[1,0,0] neg_hi:[1,0,0]
	v_cmp_gt_f32_e32 vcc, 0, v156
	v_cmp_gt_f32_e64 s[4:5], 0, v158
	v_mov_b32_e32 v175, v173
	v_cndmask_b32_e32 v179, v147, v181, vcc
	v_cndmask_b32_e32 v181, v149, v225, vcc
	v_cmp_gt_f32_e32 vcc, 0, v159
	v_mov_b32_e32 v183, v185
	v_cndmask_b32_e64 v178, v146, v180, s[4:5]
	v_cndmask_b32_e32 v180, v148, v224, vcc
	v_pk_mul_f32 v[148:149], v[172:173], v[184:185]
	v_pk_mul_f32 v[158:159], v[174:175], v[182:183]
	v_mov_b32_e32 v156, v154
	v_mov_b32_e32 v174, v155
	v_mov_b32_e32 v175, v157
	v_pk_mul_f32 v[172:173], v[156:157], v[148:149]
	v_pk_mul_f32 v[182:183], v[174:175], v[158:159]
	v_pk_fma_f32 v[148:149], v[156:157], v[148:149], v[156:157] neg_lo:[1,0,0] neg_hi:[1,0,0]
	v_pk_fma_f32 v[158:159], v[174:175], v[158:159], v[174:175] neg_lo:[1,0,0] neg_hi:[1,0,0]
	v_cmp_gt_f32_e32 vcc, 0, v157
	v_cmp_gt_f32_e64 s[4:5], 0, v154
	v_add_lshl_u32 v160, v1, v207, 1
	v_cndmask_b32_e32 v157, v149, v173, vcc
	v_cndmask_b32_e64 v156, v148, v172, s[4:5]
	v_cndmask_b32_e32 v159, v159, v183, vcc
	v_cmp_gt_f32_e32 vcc, 0, v155
	v_pk_mul_f32 v[174:175], v[156:157], v[156:157]
	v_mul_f32_e32 v151, v150, v150
	v_cndmask_b32_e32 v158, v158, v182, vcc
	v_mul_f32_e32 v153, v152, v152
	v_mul_f32_e32 v209, v208, v208
	v_mul_f32_e32 v211, v210, v210
	v_mul_f32_e32 v215, v214, v214
	v_mul_f32_e32 v223, v222, v222
	v_mul_f32_e32 v227, v226, v226
	v_mul_f32_e32 v229, v228, v228
	v_add_lshl_u32 v171, v1, v188, 1
	v_cvt_pk_bf16_f32 v146, v178, v180
	v_cvt_pk_bf16_f32 v147, v156, v158
	v_pk_mul_f32 v[154:155], v[178:179], v[178:179]
	v_pk_mul_f32 v[172:173], v[180:181], v[180:181]
	v_pk_mul_f32 v[182:183], v[158:159], v[158:159]
	v_pk_mov_b32 v[154:155], v[178:179], v[154:155] op_sel:[1,0]
	v_pk_mov_b32 v[172:173], v[156:157], v[172:173] op_sel:[1,0]
	v_cvt_pk_bf16_f32 v148, v179, v157
	v_mov_b32_e32 v1, v161
	v_pk_add_f32 v[154:155], v[154:155], v[172:173]
	v_mov_b32_e32 v172, v176
	v_mov_b32_e32 v173, v174
	v_pk_mov_b32 v[174:175], v[176:177], v[182:183] op_sel:[1,0]
	v_cvt_pk_bf16_f32 v149, v176, v177
	buffer_store_dwordx4 v[146:149], v160, s[28:31], 0 offen sc1
	v_pk_add_f32 v[172:173], v[172:173], v[174:175]
	v_pk_mul_f32 v[174:175], v[178:179], v[180:181]
	v_pk_add_f32 v[154:155], v[154:155], v[172:173]
	v_pk_add_f32 v[172:173], v[178:179], v[180:181]
	s_nop 0
	v_mov_b32_e32 v173, v175
	v_pk_add_f32 v[174:175], v[156:157], v[158:159]
	v_pk_mul_f32 v[156:157], v[156:157], v[158:159]
	s_nop 0
	v_mov_b32_e32 v175, v157
	v_pk_add_f32 v[156:157], v[172:173], v[174:175]
	s_nop 0
	v_pk_add_f32 v[156:157], v[156:157], v[0:1]
	s_nop 0
	v_pk_add_f32 v[154:155], v[154:155], v[156:157]
	v_cvt_pk_bf16_f32 v146, v150, v152
	v_pk_add_f32 v[148:149], v[150:151], v[152:153]
	v_pk_add_f32 v[150:151], v[208:209], v[210:211]
	v_cvt_pk_bf16_f32 v147, v208, v210
	s_nop 0
	v_pk_add_f32 v[148:149], v[148:149], v[150:151]
	s_nop 0
	v_pk_add_f32 v[150:151], v[148:149], v[154:155]
	v_pk_add_f32 v[152:153], v[214:215], v[222:223]
	v_pk_add_f32 v[154:155], v[226:227], v[228:229]
	v_cvt_pk_bf16_f32 v148, v214, v222
	v_cvt_pk_bf16_f32 v149, v226, v228
	buffer_store_dwordx4 v[146:149], v171, s[28:31], 0 offen sc1
	v_pk_add_f32 v[152:153], v[152:153], v[154:155]
	s_nop 0
	v_pk_add_f32 v[150:151], v[152:153], v[150:151]
	v_and_b32_e32 v146, 64, v216
	v_xor_b32_e32 v1, 16, v216
	v_add_u32_e32 v148, 64, v146
	v_cmp_lt_i32_e32 vcc, v1, v148
	s_nop 1
	v_cndmask_b32_e32 v1, v216, v1, vcc
	v_lshlrev_b32_e32 v174, 2, v1
	ds_bpermute_b32 v146, v174, v150
	ds_bpermute_b32 v147, v174, v151
	v_xor_b32_e32 v1, 32, v216
	v_cmp_lt_i32_e32 vcc, v1, v148
	s_waitcnt lgkmcnt(0)
	v_pk_add_f32 v[146:147], v[150:151], v[146:147]
	v_cndmask_b32_e32 v1, v216, v1, vcc
	v_lshlrev_b32_e32 v175, 2, v1
	ds_bpermute_b32 v148, v175, v146
	ds_bpermute_b32 v149, v175, v147
	s_and_saveexec_b64 s[4:5], s[46:47]
	s_cbranch_execz .LBB0_215
	v_ashrrev_i32_e32 v171, 31, v170
	v_lshlrev_b64 v[150:151], 7, v[170:171]
	v_lshl_add_u64 v[150:151], s[12:13], 0, v[150:151]
	s_lshl_b32 s38, s36, 3
	v_lshl_add_u64 v[150:151], v[150:151], 0, s[38:39]
	s_lshl_b32 s38, s57, 3
	v_lshl_add_u64 v[150:151], v[150:151], 0, s[38:39]
	s_waitcnt lgkmcnt(0)
	v_pk_add_f32 v[146:147], v[146:147], v[148:149]
	flat_store_dwordx2 v[150:151], v[146:147]

.LBB0_395:
	s_add_i32 s66, s66, 1
	s_mov_b64 s[36:37], s[20:21]
	s_mul_i32 s20, s66, s26
	s_add_i32 s42, s20, s2
	s_cmpk_gt_i32 s42, 0x3ff
	s_cselect_b64 s[52:53], -1, 0
	s_lshl_b32 s20, s42, 3
	s_and_b32 s20, s20, 56
	s_bfe_u32 s21, s42, 0x30003
	s_mov_b32 s3, s67
	s_or_b32 s67, s20, s21
	s_mov_b32 s27, s50
	s_ashr_i32 s50, s42, 6
	s_lshl_b32 s20, s67, 19
	s_mov_b64 s[4:5], s[48:49]
	s_add_u32 s48, s18, s20
	s_addc_u32 s49, s19, 0
	s_ashr_i32 s51, s50, 31
	s_lshl_b64 s[20:21], s[50:51], 19
	s_add_u32 s20, s16, s20
	s_addc_u32 s21, s17, s21
	s_cmpk_lt_i32 s42, 0x400
	s_cselect_b32 s46, s49, s5
	s_cselect_b32 s47, s48, s4
	s_cselect_b32 s51, s21, s37
	s_cselect_b32 s54, s20, s36
	s_add_u32 s55, s36, 0x100
	s_addc_u32 s56, s37, 0
	s_mov_b32 s57, -2
	s_add_u32 s36, s4, 0x100
	s_addc_u32 s37, s5, 0
	s_add_i32 s68, 0, 0x10000
	v_add_u32_e32 v30, s68, v204
	ds_read_b128 v[14:17], v30
	ds_read_b128 v[22:25], v30 offset:1024
	ds_read_b128 v[26:29], v30 offset:2048
	ds_read_b128 v[30:33], v30 offset:3072
	s_cmp_eq_u32 s57, 12
	s_cselect_b32 s45, s46, s37
	s_cselect_b32 s44, s47, s36
	s_cselect_b32 s43, s51, s56
	s_cselect_b32 s42, s54, s55
	v_lshl_add_u64 v[178:179], s[4:5], 0, v[188:189]
	s_add_i32 m0, s60, 0xc000
	ds_read_b128 v[38:41], v209
	ds_read_b128 v[42:45], v209 offset:1024
	ds_read_b128 v[46:49], v209 offset:2048
	ds_read_b128 v[54:57], v209 offset:3072
	ds_read_b128 v[58:61], v209 offset:4096
	ds_read_b128 v[62:65], v209 offset:5120
	ds_read_b128 v[66:69], v209 offset:6144
	ds_read_b128 v[70:73], v209 offset:7168
	global_load_lds_dwordx4 v[178:179], off
	v_lshl_add_u64 v[178:179], s[4:5], 0, v[186:187]
	s_add_i32 m0, s60, 0xe000
	s_nop 0
	global_load_lds_dwordx4 v[178:179], off
	s_waitcnt lgkmcnt(8)
	s_waitcnt vmcnt(10)
	s_barrier
	s_waitcnt lgkmcnt(0)
	s_setprio 1
	s_waitcnt lgkmcnt(0)
	v_mfma_f32_16x16x32_bf16 v[174:177], v[14:17], v[38:41], 0
	v_mfma_f32_16x16x32_bf16 v[170:173], v[26:29], v[38:41], 0
	v_mfma_f32_16x16x32_bf16 v[158:161], v[14:17], v[46:49], 0
	v_mfma_f32_16x16x32_bf16 v[154:157], v[26:29], v[46:49], 0
	v_mfma_f32_16x16x32_bf16 v[142:145], v[14:17], v[58:61], 0
	v_mfma_f32_16x16x32_bf16 v[138:141], v[26:29], v[58:61], 0
	v_mfma_f32_16x16x32_bf16 v[126:129], v[14:17], v[66:69], 0
	v_mfma_f32_16x16x32_bf16 v[122:125], v[26:29], v[66:69], 0
	v_mfma_f32_16x16x32_bf16 v[174:177], v[22:25], v[42:45], v[174:177]
	v_mfma_f32_16x16x32_bf16 v[170:173], v[30:33], v[42:45], v[170:173]
	v_mfma_f32_16x16x32_bf16 v[158:161], v[22:25], v[54:57], v[158:161]
	v_mfma_f32_16x16x32_bf16 v[154:157], v[30:33], v[54:57], v[154:157]
	v_mfma_f32_16x16x32_bf16 v[142:145], v[22:25], v[62:65], v[142:145]
	v_mfma_f32_16x16x32_bf16 v[138:141], v[30:33], v[62:65], v[138:141]
	v_mfma_f32_16x16x32_bf16 v[126:129], v[22:25], v[70:73], v[126:129]
	v_mfma_f32_16x16x32_bf16 v[122:125], v[30:33], v[70:73], v[122:125]
	s_setprio 0
	s_barrier
	s_add_i32 s69, 0, 0x14000
	v_add_u32_e32 v210, s69, v204
	s_add_i32 s4, s68, s59
	ds_read_b128 v[178:181], v210
	ds_read_b128 v[190:193], v210 offset:1024
	ds_read_b128 v[200:203], v210 offset:2048
	ds_read_b128 v[222:225], v210 offset:3072
	v_lshl_add_u64 v[210:211], s[42:43], 0, v[184:185]
	s_mov_b32 m0, s4
	v_lshl_add_u64 v[214:215], s[42:43], 0, v[182:183]
	global_load_lds_dwordx4 v[210:211], off
	s_add_i32 m0, s4, 0x2000
	s_nop 0
	global_load_lds_dwordx4 v[214:215], off
	s_waitcnt vmcnt(10)
	s_barrier
	s_waitcnt lgkmcnt(0)
	s_setprio 1
	s_waitcnt lgkmcnt(0)
	v_mfma_f32_16x16x32_bf16 v[166:169], v[178:181], v[38:41], 0
	v_mfma_f32_16x16x32_bf16 v[38:41], v[200:203], v[38:41], 0
	v_mfma_f32_16x16x32_bf16 v[166:169], v[190:193], v[42:45], v[166:169]
	v_mfma_f32_16x16x32_bf16 v[38:41], v[222:225], v[42:45], v[38:41]
	v_mfma_f32_16x16x32_bf16 v[42:45], v[178:181], v[46:49], 0
	v_mfma_f32_16x16x32_bf16 v[46:49], v[200:203], v[46:49], 0
	v_mfma_f32_16x16x32_bf16 v[42:45], v[190:193], v[54:57], v[42:45]
	v_mfma_f32_16x16x32_bf16 v[46:49], v[222:225], v[54:57], v[46:49]
	v_mfma_f32_16x16x32_bf16 v[54:57], v[178:181], v[58:61], 0
	v_mfma_f32_16x16x32_bf16 v[58:61], v[200:203], v[58:61], 0
	v_mfma_f32_16x16x32_bf16 v[54:57], v[190:193], v[62:65], v[54:57]
	v_mfma_f32_16x16x32_bf16 v[58:61], v[222:225], v[62:65], v[58:61]
	v_mfma_f32_16x16x32_bf16 v[62:65], v[178:181], v[66:69], 0
	v_mfma_f32_16x16x32_bf16 v[66:69], v[200:203], v[66:69], 0
	v_mfma_f32_16x16x32_bf16 v[62:65], v[190:193], v[70:73], v[62:65]
	v_mfma_f32_16x16x32_bf16 v[66:69], v[222:225], v[70:73], v[66:69]
	s_setprio 0
	s_mov_b32 m0, s60
	v_lshl_add_u64 v[242:243], s[44:45], 0, v[184:185]
	s_barrier
	ds_read_b128 v[70:73], v209 offset:16384
	ds_read_b128 v[114:117], v209 offset:17408
	ds_read_b128 v[118:121], v209 offset:18432
	ds_read_b128 v[130:133], v209 offset:19456
	ds_read_b128 v[134:137], v209 offset:20480
	ds_read_b128 v[146:149], v209 offset:21504
	ds_read_b128 v[150:153], v209 offset:22528
	ds_read_b128 v[162:165], v209 offset:23552
	global_load_lds_dwordx4 v[242:243], off
	v_lshl_add_u64 v[244:245], s[44:45], 0, v[182:183]
	s_mov_b32 m0, s61
	s_nop 0
	global_load_lds_dwordx4 v[244:245], off
	s_barrier
	s_waitcnt lgkmcnt(0)
	s_setprio 1
	s_waitcnt lgkmcnt(0)
	v_mfma_f32_16x16x32_bf16 v[110:113], v[14:17], v[70:73], 0
	v_mfma_f32_16x16x32_bf16 v[106:109], v[26:29], v[70:73], 0
	v_mfma_f32_16x16x32_bf16 v[94:97], v[14:17], v[118:121], 0
	v_mfma_f32_16x16x32_bf16 v[90:93], v[26:29], v[118:121], 0
	v_mfma_f32_16x16x32_bf16 v[78:81], v[14:17], v[134:137], 0
	v_mfma_f32_16x16x32_bf16 v[74:77], v[26:29], v[134:137], 0
	v_mfma_f32_16x16x32_bf16 v[10:13], v[26:29], v[150:153], 0
	v_mfma_f32_16x16x32_bf16 v[110:113], v[22:25], v[114:117], v[110:113]
	v_mfma_f32_16x16x32_bf16 v[106:109], v[30:33], v[114:117], v[106:109]
	v_mfma_f32_16x16x32_bf16 v[94:97], v[22:25], v[130:133], v[94:97]
	v_mfma_f32_16x16x32_bf16 v[90:93], v[30:33], v[130:133], v[90:93]
	v_mfma_f32_16x16x32_bf16 v[78:81], v[22:25], v[146:149], v[78:81]
	v_mfma_f32_16x16x32_bf16 v[74:77], v[30:33], v[146:149], v[74:77]
	v_mfma_f32_16x16x32_bf16 v[14:17], v[14:17], v[150:153], 0
	v_mfma_f32_16x16x32_bf16 v[10:13], v[30:33], v[162:165], v[10:13]
	v_mfma_f32_16x16x32_bf16 v[14:17], v[22:25], v[162:165], v[14:17]
	s_setprio 0
	s_barrier
	s_add_u32 s4, s42, 0x40000
	s_addc_u32 s5, s43, 0
	s_add_i32 s68, s69, s59
	v_lshl_add_u64 v[18:19], s[4:5], 0, v[184:185]
	s_mov_b32 m0, s68
	s_nop 0
	global_load_lds_dwordx4 v[18:19], off
	v_lshl_add_u64 v[18:19], s[4:5], 0, v[182:183]
	s_add_i32 m0, s68, 0x2000
	s_nop 0
	global_load_lds_dwordx4 v[18:19], off
	s_waitcnt vmcnt(10)
	s_barrier
	s_setprio 1
	v_mfma_f32_16x16x32_bf16 v[18:21], v[178:181], v[70:73], 0
	v_mfma_f32_16x16x32_bf16 v[22:25], v[190:193], v[114:117], v[18:21]
	v_mfma_f32_16x16x32_bf16 v[18:21], v[200:203], v[70:73], 0
	v_mfma_f32_16x16x32_bf16 v[26:29], v[222:225], v[114:117], v[18:21]
	v_mfma_f32_16x16x32_bf16 v[18:21], v[178:181], v[118:121], 0
	v_mfma_f32_16x16x32_bf16 v[30:33], v[190:193], v[130:133], v[18:21]
	v_mfma_f32_16x16x32_bf16 v[18:21], v[200:203], v[118:121], 0
	v_mfma_f32_16x16x32_bf16 v[70:73], v[222:225], v[130:133], v[18:21]
	v_mfma_f32_16x16x32_bf16 v[18:21], v[178:181], v[134:137], 0
	v_mfma_f32_16x16x32_bf16 v[50:53], v[190:193], v[146:149], v[18:21]
	v_mfma_f32_16x16x32_bf16 v[18:21], v[200:203], v[134:137], 0
	v_mfma_f32_16x16x32_bf16 v[6:9], v[178:181], v[150:153], 0
	v_mfma_f32_16x16x32_bf16 v[2:5], v[200:203], v[150:153], 0
	v_mfma_f32_16x16x32_bf16 v[34:37], v[222:225], v[146:149], v[18:21]
	v_mfma_f32_16x16x32_bf16 v[6:9], v[190:193], v[162:165], v[6:9]
	v_mfma_f32_16x16x32_bf16 v[2:5], v[222:225], v[162:165], v[2:5]
	s_setprio 0
	s_add_i32 s68, 0, 0x18000
	v_add_u32_e32 v98, s68, v204
	s_barrier
	ds_read_b128 v[18:21], v98
	ds_read_b128 v[82:85], v98 offset:1024
	ds_read_b128 v[86:89], v98 offset:2048
	ds_read_b128 v[98:101], v98 offset:3072
	s_add_u32 s4, s44, 0x40000
	s_addc_u32 s5, s45, 0
	s_mov_b32 m0, s62
	v_lshl_add_u64 v[134:135], s[4:5], 0, v[184:185]
	ds_read_b128 v[102:105], v209 offset:32768
	ds_read_b128 v[114:117], v209 offset:33792
	ds_read_b128 v[118:121], v209 offset:34816
	ds_read_b128 v[130:133], v209 offset:35840
	ds_read_b128 v[178:181], v209 offset:36864
	ds_read_b128 v[190:193], v209 offset:37888
	ds_read_b128 v[200:203], v209 offset:38912
	ds_read_b128 v[222:225], v209 offset:39936
	global_load_lds_dwordx4 v[134:135], off
	v_lshl_add_u64 v[134:135], s[4:5], 0, v[182:183]
	s_mov_b32 m0, s63
	s_nop 0
	global_load_lds_dwordx4 v[134:135], off
	s_waitcnt lgkmcnt(8)
	s_waitcnt vmcnt(10)
	s_barrier
	s_waitcnt lgkmcnt(0)
	s_setprio 1
	s_waitcnt lgkmcnt(0)
	v_mfma_f32_16x16x32_bf16 v[134:137], v[18:21], v[102:105], v[174:177]
	v_mfma_f32_16x16x32_bf16 v[174:177], v[82:85], v[114:117], v[134:137]
	v_mfma_f32_16x16x32_bf16 v[134:137], v[86:89], v[102:105], v[170:173]
	v_mfma_f32_16x16x32_bf16 v[170:173], v[98:101], v[114:117], v[134:137]
	v_mfma_f32_16x16x32_bf16 v[134:137], v[18:21], v[118:121], v[158:161]
	v_mfma_f32_16x16x32_bf16 v[158:161], v[82:85], v[130:133], v[134:137]
	v_mfma_f32_16x16x32_bf16 v[134:137], v[86:89], v[118:121], v[154:157]
	v_mfma_f32_16x16x32_bf16 v[154:157], v[98:101], v[130:133], v[134:137]
	v_mfma_f32_16x16x32_bf16 v[134:137], v[18:21], v[178:181], v[142:145]
	v_mfma_f32_16x16x32_bf16 v[142:145], v[82:85], v[190:193], v[134:137]
	v_mfma_f32_16x16x32_bf16 v[134:137], v[86:89], v[178:181], v[138:141]
	v_mfma_f32_16x16x32_bf16 v[126:129], v[18:21], v[200:203], v[126:129]
	v_mfma_f32_16x16x32_bf16 v[122:125], v[86:89], v[200:203], v[122:125]
	v_mfma_f32_16x16x32_bf16 v[138:141], v[98:101], v[190:193], v[134:137]
	v_mfma_f32_16x16x32_bf16 v[126:129], v[82:85], v[222:225], v[126:129]
	v_mfma_f32_16x16x32_bf16 v[122:125], v[98:101], v[222:225], v[122:125]
	s_setprio 0
	s_barrier
	s_add_i32 s44, 0, 0x1c000
	v_add_u32_e32 v134, s44, v204
	s_add_i32 s4, s68, s59
	ds_read_b128 v[226:229], v134
	ds_read_b128 v[230:233], v134 offset:1024
	ds_read_b128 v[234:237], v134 offset:2048
	ds_read_b128 v[238:241], v134 offset:3072
	v_lshl_add_u64 v[134:135], v[210:211], 0, s[22:23]
	s_mov_b32 m0, s4
	s_nop 0
	global_load_lds_dwordx4 v[134:135], off
	v_lshl_add_u64 v[134:135], v[214:215], 0, s[22:23]
	s_add_i32 m0, s4, 0x2000
	s_nop 0
	global_load_lds_dwordx4 v[134:135], off
	s_waitcnt vmcnt(10)
	s_barrier
	s_waitcnt lgkmcnt(0)
	s_setprio 1
	s_waitcnt lgkmcnt(0)
	v_mfma_f32_16x16x32_bf16 v[38:41], v[234:237], v[102:105], v[38:41]
	v_mfma_f32_16x16x32_bf16 v[162:165], v[238:241], v[114:117], v[38:41]
	v_mfma_f32_16x16x32_bf16 v[38:41], v[226:229], v[118:121], v[42:45]
	v_mfma_f32_16x16x32_bf16 v[150:153], v[230:233], v[130:133], v[38:41]
	v_mfma_f32_16x16x32_bf16 v[38:41], v[234:237], v[118:121], v[46:49]
	v_mfma_f32_16x16x32_bf16 v[134:137], v[226:229], v[102:105], v[166:169]
	v_mfma_f32_16x16x32_bf16 v[146:149], v[238:241], v[130:133], v[38:41]
	v_mfma_f32_16x16x32_bf16 v[38:41], v[226:229], v[178:181], v[54:57]
	v_mfma_f32_16x16x32_bf16 v[166:169], v[230:233], v[114:117], v[134:137]
	v_mfma_f32_16x16x32_bf16 v[134:137], v[230:233], v[190:193], v[38:41]
	v_mfma_f32_16x16x32_bf16 v[38:41], v[234:237], v[178:181], v[58:61]
	v_mfma_f32_16x16x32_bf16 v[130:133], v[238:241], v[190:193], v[38:41]
	v_mfma_f32_16x16x32_bf16 v[38:41], v[226:229], v[200:203], v[62:65]
	v_mfma_f32_16x16x32_bf16 v[118:121], v[230:233], v[222:225], v[38:41]
	v_mfma_f32_16x16x32_bf16 v[38:41], v[234:237], v[200:203], v[66:69]
	v_mfma_f32_16x16x32_bf16 v[114:117], v[238:241], v[222:225], v[38:41]
	s_setprio 0
	s_mov_b32 m0, s64
	v_lshl_add_u64 v[102:103], v[242:243], 0, s[22:23]
	s_barrier
	s_nop 2
	ds_read_b128 v[38:41], v209 offset:49152
	ds_read_b128 v[42:45], v209 offset:50176
	ds_read_b128 v[46:49], v209 offset:51200
	ds_read_b128 v[54:57], v209 offset:52224
	ds_read_b128 v[58:61], v209 offset:53248
	ds_read_b128 v[62:65], v209 offset:54272
	ds_read_b128 v[66:69], v209 offset:55296
	ds_read_b128 v[178:181], v209 offset:56320
	global_load_lds_dwordx4 v[102:103], off
	v_lshl_add_u64 v[102:103], v[244:245], 0, s[22:23]
	s_mov_b32 m0, s65
	s_nop 0
	global_load_lds_dwordx4 v[102:103], off
	s_barrier
	s_waitcnt lgkmcnt(0)
	s_setprio 1
	s_waitcnt lgkmcnt(0)
	v_mfma_f32_16x16x32_bf16 v[102:105], v[18:21], v[38:41], v[110:113]
	v_mfma_f32_16x16x32_bf16 v[110:113], v[82:85], v[42:45], v[102:105]
	v_mfma_f32_16x16x32_bf16 v[102:105], v[86:89], v[38:41], v[106:109]
	v_mfma_f32_16x16x32_bf16 v[94:97], v[18:21], v[46:49], v[94:97]
	v_mfma_f32_16x16x32_bf16 v[90:93], v[86:89], v[46:49], v[90:93]
	v_mfma_f32_16x16x32_bf16 v[78:81], v[18:21], v[58:61], v[78:81]
	v_mfma_f32_16x16x32_bf16 v[74:77], v[86:89], v[58:61], v[74:77]
	v_mfma_f32_16x16x32_bf16 v[14:17], v[18:21], v[66:69], v[14:17]
	v_mfma_f32_16x16x32_bf16 v[10:13], v[86:89], v[66:69], v[10:13]
	v_mfma_f32_16x16x32_bf16 v[106:109], v[98:101], v[42:45], v[102:105]
	v_mfma_f32_16x16x32_bf16 v[94:97], v[82:85], v[54:57], v[94:97]
	v_mfma_f32_16x16x32_bf16 v[90:93], v[98:101], v[54:57], v[90:93]
	v_mfma_f32_16x16x32_bf16 v[78:81], v[82:85], v[62:65], v[78:81]
	v_mfma_f32_16x16x32_bf16 v[74:77], v[98:101], v[62:65], v[74:77]
	v_mfma_f32_16x16x32_bf16 v[18:21], v[82:85], v[178:181], v[14:17]
	v_mfma_f32_16x16x32_bf16 v[10:13], v[98:101], v[178:181], v[10:13]
	s_setprio 0
	s_barrier
	s_add_u32 s4, s42, 0x40080
	s_addc_u32 s5, s43, 0
	s_add_i32 s42, s44, s59
	v_lshl_add_u64 v[14:15], s[4:5], 0, v[184:185]
	s_mov_b32 m0, s42
	s_nop 0
	global_load_lds_dwordx4 v[14:15], off
	v_lshl_add_u64 v[14:15], s[4:5], 0, v[182:183]
	s_add_i32 m0, s42, 0x2000
	s_nop 0
	global_load_lds_dwordx4 v[14:15], off
	s_waitcnt vmcnt(10)
	s_barrier
	s_setprio 1
	v_mfma_f32_16x16x32_bf16 v[14:17], v[226:229], v[38:41], v[22:25]
	v_mfma_f32_16x16x32_bf16 v[102:105], v[230:233], v[42:45], v[14:17]
	v_mfma_f32_16x16x32_bf16 v[14:17], v[234:237], v[38:41], v[26:29]
	v_mfma_f32_16x16x32_bf16 v[98:101], v[238:241], v[42:45], v[14:17]
	v_mfma_f32_16x16x32_bf16 v[14:17], v[226:229], v[46:49], v[30:33]
	v_mfma_f32_16x16x32_bf16 v[86:89], v[230:233], v[54:57], v[14:17]
	v_mfma_f32_16x16x32_bf16 v[14:17], v[234:237], v[46:49], v[70:73]
	v_mfma_f32_16x16x32_bf16 v[82:85], v[238:241], v[54:57], v[14:17]
	v_mfma_f32_16x16x32_bf16 v[14:17], v[226:229], v[58:61], v[50:53]
	v_mfma_f32_16x16x32_bf16 v[50:53], v[230:233], v[62:65], v[14:17]
	v_mfma_f32_16x16x32_bf16 v[14:17], v[234:237], v[58:61], v[34:37]
	v_mfma_f32_16x16x32_bf16 v[6:9], v[226:229], v[66:69], v[6:9]
	v_mfma_f32_16x16x32_bf16 v[2:5], v[234:237], v[66:69], v[2:5]
	v_mfma_f32_16x16x32_bf16 v[34:37], v[238:241], v[62:65], v[14:17]
	v_mfma_f32_16x16x32_bf16 v[6:9], v[230:233], v[178:181], v[6:9]
	v_mfma_f32_16x16x32_bf16 v[2:5], v[238:241], v[178:181], v[2:5]
	s_setprio 0
	s_add_i32 s57, s57, 2
	s_add_u32 s55, s55, 0x100
	s_addc_u32 s56, s56, 0
	s_cmp_gt_u32 s57, 13
	s_mov_b64 s[4:5], s[36:37]
	s_barrier
.LBB0_396:
	s_add_u32 s36, s4, 0x100
	s_addc_u32 s37, s5, 0
	s_add_i32 s68, 0, 0x10000
	v_add_u32_e32 v30, s68, v204
	ds_read_b128 v[14:17], v30
	ds_read_b128 v[22:25], v30 offset:1024
	ds_read_b128 v[26:29], v30 offset:2048
	ds_read_b128 v[30:33], v30 offset:3072
	s_cmp_eq_u32 s57, 12
	s_cselect_b32 s45, s46, s37
	s_cselect_b32 s44, s47, s36
	s_cselect_b32 s43, s51, s56
	s_cselect_b32 s42, s54, s55
	v_lshl_add_u64 v[178:179], s[4:5], 0, v[188:189]
	s_add_i32 m0, s60, 0xc000
	ds_read_b128 v[38:41], v209
	ds_read_b128 v[42:45], v209 offset:1024
	ds_read_b128 v[46:49], v209 offset:2048
	ds_read_b128 v[54:57], v209 offset:3072
	ds_read_b128 v[58:61], v209 offset:4096
	ds_read_b128 v[62:65], v209 offset:5120
	ds_read_b128 v[66:69], v209 offset:6144
	ds_read_b128 v[70:73], v209 offset:7168
	global_load_lds_dwordx4 v[178:179], off
	v_lshl_add_u64 v[178:179], s[4:5], 0, v[186:187]
	s_add_i32 m0, s60, 0xe000
	s_nop 0
	global_load_lds_dwordx4 v[178:179], off
	s_waitcnt lgkmcnt(8)
	s_waitcnt vmcnt(10)
	s_barrier
	s_waitcnt lgkmcnt(0)
	s_setprio 1
	s_waitcnt lgkmcnt(0)
	v_mfma_f32_16x16x32_bf16 v[174:177], v[14:17], v[38:41], v[174:177]
	v_mfma_f32_16x16x32_bf16 v[170:173], v[26:29], v[38:41], v[170:173]
	v_mfma_f32_16x16x32_bf16 v[158:161], v[14:17], v[46:49], v[158:161]
	v_mfma_f32_16x16x32_bf16 v[154:157], v[26:29], v[46:49], v[154:157]
	v_mfma_f32_16x16x32_bf16 v[142:145], v[14:17], v[58:61], v[142:145]
	v_mfma_f32_16x16x32_bf16 v[138:141], v[26:29], v[58:61], v[138:141]
	v_mfma_f32_16x16x32_bf16 v[126:129], v[14:17], v[66:69], v[126:129]
	v_mfma_f32_16x16x32_bf16 v[122:125], v[26:29], v[66:69], v[122:125]
	v_mfma_f32_16x16x32_bf16 v[174:177], v[22:25], v[42:45], v[174:177]
	v_mfma_f32_16x16x32_bf16 v[170:173], v[30:33], v[42:45], v[170:173]
	v_mfma_f32_16x16x32_bf16 v[158:161], v[22:25], v[54:57], v[158:161]
	v_mfma_f32_16x16x32_bf16 v[154:157], v[30:33], v[54:57], v[154:157]
	v_mfma_f32_16x16x32_bf16 v[142:145], v[22:25], v[62:65], v[142:145]
	v_mfma_f32_16x16x32_bf16 v[138:141], v[30:33], v[62:65], v[138:141]
	v_mfma_f32_16x16x32_bf16 v[126:129], v[22:25], v[70:73], v[126:129]
	v_mfma_f32_16x16x32_bf16 v[122:125], v[30:33], v[70:73], v[122:125]
	s_setprio 0
	s_barrier
	s_add_i32 s69, 0, 0x14000
	v_add_u32_e32 v210, s69, v204
	s_add_i32 s4, s68, s59
	ds_read_b128 v[178:181], v210
	ds_read_b128 v[190:193], v210 offset:1024
	ds_read_b128 v[200:203], v210 offset:2048
	ds_read_b128 v[222:225], v210 offset:3072
	v_lshl_add_u64 v[210:211], s[42:43], 0, v[184:185]
	s_mov_b32 m0, s4
	v_lshl_add_u64 v[214:215], s[42:43], 0, v[182:183]
	global_load_lds_dwordx4 v[210:211], off
	s_add_i32 m0, s4, 0x2000
	s_nop 0
	global_load_lds_dwordx4 v[214:215], off
	s_waitcnt vmcnt(10)
	s_barrier
	s_waitcnt lgkmcnt(0)
	s_setprio 1
	s_waitcnt lgkmcnt(0)
	v_mfma_f32_16x16x32_bf16 v[166:169], v[178:181], v[38:41], v[166:169]
	v_mfma_f32_16x16x32_bf16 v[38:41], v[200:203], v[38:41], v[162:165]
	v_mfma_f32_16x16x32_bf16 v[166:169], v[190:193], v[42:45], v[166:169]
	v_mfma_f32_16x16x32_bf16 v[38:41], v[222:225], v[42:45], v[38:41]
	v_mfma_f32_16x16x32_bf16 v[42:45], v[178:181], v[46:49], v[150:153]
	v_mfma_f32_16x16x32_bf16 v[46:49], v[200:203], v[46:49], v[146:149]
	v_mfma_f32_16x16x32_bf16 v[42:45], v[190:193], v[54:57], v[42:45]
	v_mfma_f32_16x16x32_bf16 v[46:49], v[222:225], v[54:57], v[46:49]
	v_mfma_f32_16x16x32_bf16 v[54:57], v[178:181], v[58:61], v[134:137]
	v_mfma_f32_16x16x32_bf16 v[58:61], v[200:203], v[58:61], v[130:133]
	v_mfma_f32_16x16x32_bf16 v[54:57], v[190:193], v[62:65], v[54:57]
	v_mfma_f32_16x16x32_bf16 v[58:61], v[222:225], v[62:65], v[58:61]
	v_mfma_f32_16x16x32_bf16 v[62:65], v[178:181], v[66:69], v[118:121]
	v_mfma_f32_16x16x32_bf16 v[66:69], v[200:203], v[66:69], v[114:117]
	v_mfma_f32_16x16x32_bf16 v[62:65], v[190:193], v[70:73], v[62:65]
	v_mfma_f32_16x16x32_bf16 v[66:69], v[222:225], v[70:73], v[66:69]
	s_setprio 0
	s_mov_b32 m0, s60
	v_lshl_add_u64 v[242:243], s[44:45], 0, v[184:185]
	s_barrier
	ds_read_b128 v[70:73], v209 offset:16384
	ds_read_b128 v[114:117], v209 offset:17408
	ds_read_b128 v[118:121], v209 offset:18432
	ds_read_b128 v[130:133], v209 offset:19456
	ds_read_b128 v[134:137], v209 offset:20480
	ds_read_b128 v[146:149], v209 offset:21504
	ds_read_b128 v[150:153], v209 offset:22528
	ds_read_b128 v[162:165], v209 offset:23552
	global_load_lds_dwordx4 v[242:243], off
	v_lshl_add_u64 v[244:245], s[44:45], 0, v[182:183]
	s_mov_b32 m0, s61
	s_nop 0
	global_load_lds_dwordx4 v[244:245], off
	s_barrier
	s_waitcnt lgkmcnt(0)
	s_setprio 1
	s_waitcnt lgkmcnt(0)
	v_mfma_f32_16x16x32_bf16 v[110:113], v[14:17], v[70:73], v[110:113]
	v_mfma_f32_16x16x32_bf16 v[106:109], v[26:29], v[70:73], v[106:109]
	v_mfma_f32_16x16x32_bf16 v[94:97], v[14:17], v[118:121], v[94:97]
	v_mfma_f32_16x16x32_bf16 v[90:93], v[26:29], v[118:121], v[90:93]
	v_mfma_f32_16x16x32_bf16 v[78:81], v[14:17], v[134:137], v[78:81]
	v_mfma_f32_16x16x32_bf16 v[74:77], v[26:29], v[134:137], v[74:77]
	v_mfma_f32_16x16x32_bf16 v[10:13], v[26:29], v[150:153], v[10:13]
	v_mfma_f32_16x16x32_bf16 v[110:113], v[22:25], v[114:117], v[110:113]
	v_mfma_f32_16x16x32_bf16 v[106:109], v[30:33], v[114:117], v[106:109]
	v_mfma_f32_16x16x32_bf16 v[94:97], v[22:25], v[130:133], v[94:97]
	v_mfma_f32_16x16x32_bf16 v[90:93], v[30:33], v[130:133], v[90:93]
	v_mfma_f32_16x16x32_bf16 v[78:81], v[22:25], v[146:149], v[78:81]
	v_mfma_f32_16x16x32_bf16 v[74:77], v[30:33], v[146:149], v[74:77]
	v_mfma_f32_16x16x32_bf16 v[14:17], v[14:17], v[150:153], v[18:21]
	v_mfma_f32_16x16x32_bf16 v[10:13], v[30:33], v[162:165], v[10:13]
	v_mfma_f32_16x16x32_bf16 v[14:17], v[22:25], v[162:165], v[14:17]
	s_setprio 0
	s_barrier
	s_add_u32 s4, s42, 0x40000
	s_addc_u32 s5, s43, 0
	s_add_i32 s68, s69, s59
	v_lshl_add_u64 v[18:19], s[4:5], 0, v[184:185]
	s_mov_b32 m0, s68
	s_nop 0
	global_load_lds_dwordx4 v[18:19], off
	v_lshl_add_u64 v[18:19], s[4:5], 0, v[182:183]
	s_add_i32 m0, s68, 0x2000
	s_nop 0
	global_load_lds_dwordx4 v[18:19], off
	s_waitcnt vmcnt(10)
	s_barrier
	s_setprio 1
	v_mfma_f32_16x16x32_bf16 v[18:21], v[178:181], v[70:73], v[102:105]
	v_mfma_f32_16x16x32_bf16 v[22:25], v[190:193], v[114:117], v[18:21]
	v_mfma_f32_16x16x32_bf16 v[18:21], v[200:203], v[70:73], v[98:101]
	v_mfma_f32_16x16x32_bf16 v[26:29], v[222:225], v[114:117], v[18:21]
	v_mfma_f32_16x16x32_bf16 v[18:21], v[178:181], v[118:121], v[86:89]
	v_mfma_f32_16x16x32_bf16 v[30:33], v[190:193], v[130:133], v[18:21]
	v_mfma_f32_16x16x32_bf16 v[18:21], v[200:203], v[118:121], v[82:85]
	v_mfma_f32_16x16x32_bf16 v[70:73], v[222:225], v[130:133], v[18:21]
	v_mfma_f32_16x16x32_bf16 v[18:21], v[178:181], v[134:137], v[50:53]
	v_mfma_f32_16x16x32_bf16 v[50:53], v[190:193], v[146:149], v[18:21]
	v_mfma_f32_16x16x32_bf16 v[18:21], v[200:203], v[134:137], v[34:37]
	v_mfma_f32_16x16x32_bf16 v[6:9], v[178:181], v[150:153], v[6:9]
	v_mfma_f32_16x16x32_bf16 v[2:5], v[200:203], v[150:153], v[2:5]
	v_mfma_f32_16x16x32_bf16 v[34:37], v[222:225], v[146:149], v[18:21]
	v_mfma_f32_16x16x32_bf16 v[6:9], v[190:193], v[162:165], v[6:9]
	v_mfma_f32_16x16x32_bf16 v[2:5], v[222:225], v[162:165], v[2:5]
	s_setprio 0
	s_add_i32 s68, 0, 0x18000
	v_add_u32_e32 v98, s68, v204
	s_barrier
	ds_read_b128 v[18:21], v98
	ds_read_b128 v[82:85], v98 offset:1024
	ds_read_b128 v[86:89], v98 offset:2048
	ds_read_b128 v[98:101], v98 offset:3072
	s_add_u32 s4, s44, 0x40000
	s_addc_u32 s5, s45, 0
	s_mov_b32 m0, s62
	v_lshl_add_u64 v[134:135], s[4:5], 0, v[184:185]
	ds_read_b128 v[102:105], v209 offset:32768
	ds_read_b128 v[114:117], v209 offset:33792
	ds_read_b128 v[118:121], v209 offset:34816
	ds_read_b128 v[130:133], v209 offset:35840
	ds_read_b128 v[178:181], v209 offset:36864
	ds_read_b128 v[190:193], v209 offset:37888
	ds_read_b128 v[200:203], v209 offset:38912
	ds_read_b128 v[222:225], v209 offset:39936
	global_load_lds_dwordx4 v[134:135], off
	v_lshl_add_u64 v[134:135], s[4:5], 0, v[182:183]
	s_mov_b32 m0, s63
	s_nop 0
	global_load_lds_dwordx4 v[134:135], off
	s_waitcnt lgkmcnt(8)
	s_waitcnt vmcnt(10)
	s_barrier
	s_waitcnt lgkmcnt(0)
	s_setprio 1
	s_waitcnt lgkmcnt(0)
	v_mfma_f32_16x16x32_bf16 v[134:137], v[18:21], v[102:105], v[174:177]
	v_mfma_f32_16x16x32_bf16 v[174:177], v[82:85], v[114:117], v[134:137]
	v_mfma_f32_16x16x32_bf16 v[134:137], v[86:89], v[102:105], v[170:173]
	v_mfma_f32_16x16x32_bf16 v[170:173], v[98:101], v[114:117], v[134:137]
	v_mfma_f32_16x16x32_bf16 v[134:137], v[18:21], v[118:121], v[158:161]
	v_mfma_f32_16x16x32_bf16 v[158:161], v[82:85], v[130:133], v[134:137]
	v_mfma_f32_16x16x32_bf16 v[134:137], v[86:89], v[118:121], v[154:157]
	v_mfma_f32_16x16x32_bf16 v[154:157], v[98:101], v[130:133], v[134:137]
	v_mfma_f32_16x16x32_bf16 v[134:137], v[18:21], v[178:181], v[142:145]
	v_mfma_f32_16x16x32_bf16 v[142:145], v[82:85], v[190:193], v[134:137]
	v_mfma_f32_16x16x32_bf16 v[134:137], v[86:89], v[178:181], v[138:141]
	v_mfma_f32_16x16x32_bf16 v[126:129], v[18:21], v[200:203], v[126:129]
	v_mfma_f32_16x16x32_bf16 v[122:125], v[86:89], v[200:203], v[122:125]
	v_mfma_f32_16x16x32_bf16 v[138:141], v[98:101], v[190:193], v[134:137]
	v_mfma_f32_16x16x32_bf16 v[126:129], v[82:85], v[222:225], v[126:129]
	v_mfma_f32_16x16x32_bf16 v[122:125], v[98:101], v[222:225], v[122:125]
	s_setprio 0
	s_barrier
	s_add_i32 s44, 0, 0x1c000
	v_add_u32_e32 v134, s44, v204
	s_add_i32 s4, s68, s59
	ds_read_b128 v[226:229], v134
	ds_read_b128 v[230:233], v134 offset:1024
	ds_read_b128 v[234:237], v134 offset:2048
	ds_read_b128 v[238:241], v134 offset:3072
	v_lshl_add_u64 v[134:135], v[210:211], 0, s[22:23]
	s_mov_b32 m0, s4
	s_nop 0
	global_load_lds_dwordx4 v[134:135], off
	v_lshl_add_u64 v[134:135], v[214:215], 0, s[22:23]
	s_add_i32 m0, s4, 0x2000
	s_nop 0
	global_load_lds_dwordx4 v[134:135], off
	s_waitcnt vmcnt(10)
	s_barrier
	s_waitcnt lgkmcnt(0)
	s_setprio 1
	s_waitcnt lgkmcnt(0)
	v_mfma_f32_16x16x32_bf16 v[38:41], v[234:237], v[102:105], v[38:41]
	v_mfma_f32_16x16x32_bf16 v[162:165], v[238:241], v[114:117], v[38:41]
	v_mfma_f32_16x16x32_bf16 v[38:41], v[226:229], v[118:121], v[42:45]
	v_mfma_f32_16x16x32_bf16 v[150:153], v[230:233], v[130:133], v[38:41]
	v_mfma_f32_16x16x32_bf16 v[38:41], v[234:237], v[118:121], v[46:49]
	v_mfma_f32_16x16x32_bf16 v[134:137], v[226:229], v[102:105], v[166:169]
	v_mfma_f32_16x16x32_bf16 v[146:149], v[238:241], v[130:133], v[38:41]
	v_mfma_f32_16x16x32_bf16 v[38:41], v[226:229], v[178:181], v[54:57]
	v_mfma_f32_16x16x32_bf16 v[166:169], v[230:233], v[114:117], v[134:137]
	v_mfma_f32_16x16x32_bf16 v[134:137], v[230:233], v[190:193], v[38:41]
	v_mfma_f32_16x16x32_bf16 v[38:41], v[234:237], v[178:181], v[58:61]
	v_mfma_f32_16x16x32_bf16 v[130:133], v[238:241], v[190:193], v[38:41]
	v_mfma_f32_16x16x32_bf16 v[38:41], v[226:229], v[200:203], v[62:65]
	v_mfma_f32_16x16x32_bf16 v[118:121], v[230:233], v[222:225], v[38:41]
	v_mfma_f32_16x16x32_bf16 v[38:41], v[234:237], v[200:203], v[66:69]
	v_mfma_f32_16x16x32_bf16 v[114:117], v[238:241], v[222:225], v[38:41]
	s_setprio 0
	s_mov_b32 m0, s64
	v_lshl_add_u64 v[102:103], v[242:243], 0, s[22:23]
	s_barrier
	s_nop 2
	ds_read_b128 v[38:41], v209 offset:49152
	ds_read_b128 v[42:45], v209 offset:50176
	ds_read_b128 v[46:49], v209 offset:51200
	ds_read_b128 v[54:57], v209 offset:52224
	ds_read_b128 v[58:61], v209 offset:53248
	ds_read_b128 v[62:65], v209 offset:54272
	ds_read_b128 v[66:69], v209 offset:55296
	ds_read_b128 v[178:181], v209 offset:56320
	global_load_lds_dwordx4 v[102:103], off
	v_lshl_add_u64 v[102:103], v[244:245], 0, s[22:23]
	s_mov_b32 m0, s65
	s_nop 0
	global_load_lds_dwordx4 v[102:103], off
	s_barrier
	s_waitcnt lgkmcnt(0)
	s_setprio 1
	s_waitcnt lgkmcnt(0)
	v_mfma_f32_16x16x32_bf16 v[102:105], v[18:21], v[38:41], v[110:113]
	v_mfma_f32_16x16x32_bf16 v[110:113], v[82:85], v[42:45], v[102:105]
	v_mfma_f32_16x16x32_bf16 v[102:105], v[86:89], v[38:41], v[106:109]
	v_mfma_f32_16x16x32_bf16 v[94:97], v[18:21], v[46:49], v[94:97]
	v_mfma_f32_16x16x32_bf16 v[90:93], v[86:89], v[46:49], v[90:93]
	v_mfma_f32_16x16x32_bf16 v[78:81], v[18:21], v[58:61], v[78:81]
	v_mfma_f32_16x16x32_bf16 v[74:77], v[86:89], v[58:61], v[74:77]
	v_mfma_f32_16x16x32_bf16 v[14:17], v[18:21], v[66:69], v[14:17]
	v_mfma_f32_16x16x32_bf16 v[10:13], v[86:89], v[66:69], v[10:13]
	v_mfma_f32_16x16x32_bf16 v[106:109], v[98:101], v[42:45], v[102:105]
	v_mfma_f32_16x16x32_bf16 v[94:97], v[82:85], v[54:57], v[94:97]
	v_mfma_f32_16x16x32_bf16 v[90:93], v[98:101], v[54:57], v[90:93]
	v_mfma_f32_16x16x32_bf16 v[78:81], v[82:85], v[62:65], v[78:81]
	v_mfma_f32_16x16x32_bf16 v[74:77], v[98:101], v[62:65], v[74:77]
	v_mfma_f32_16x16x32_bf16 v[18:21], v[82:85], v[178:181], v[14:17]
	v_mfma_f32_16x16x32_bf16 v[10:13], v[98:101], v[178:181], v[10:13]
	s_setprio 0
	s_barrier
	s_add_u32 s4, s42, 0x40080
	s_addc_u32 s5, s43, 0
	s_add_i32 s42, s44, s59
	v_lshl_add_u64 v[14:15], s[4:5], 0, v[184:185]
	s_mov_b32 m0, s42
	s_nop 0
	global_load_lds_dwordx4 v[14:15], off
	v_lshl_add_u64 v[14:15], s[4:5], 0, v[182:183]
	s_add_i32 m0, s42, 0x2000
	s_nop 0
	global_load_lds_dwordx4 v[14:15], off
	s_waitcnt vmcnt(10)
	s_barrier
	s_setprio 1
	v_mfma_f32_16x16x32_bf16 v[14:17], v[226:229], v[38:41], v[22:25]
	v_mfma_f32_16x16x32_bf16 v[102:105], v[230:233], v[42:45], v[14:17]
	v_mfma_f32_16x16x32_bf16 v[14:17], v[234:237], v[38:41], v[26:29]
	v_mfma_f32_16x16x32_bf16 v[98:101], v[238:241], v[42:45], v[14:17]
	v_mfma_f32_16x16x32_bf16 v[14:17], v[226:229], v[46:49], v[30:33]
	v_mfma_f32_16x16x32_bf16 v[86:89], v[230:233], v[54:57], v[14:17]
	v_mfma_f32_16x16x32_bf16 v[14:17], v[234:237], v[46:49], v[70:73]
	v_mfma_f32_16x16x32_bf16 v[82:85], v[238:241], v[54:57], v[14:17]
	v_mfma_f32_16x16x32_bf16 v[14:17], v[226:229], v[58:61], v[50:53]
	v_mfma_f32_16x16x32_bf16 v[50:53], v[230:233], v[62:65], v[14:17]
	v_mfma_f32_16x16x32_bf16 v[14:17], v[234:237], v[58:61], v[34:37]
	v_mfma_f32_16x16x32_bf16 v[6:9], v[226:229], v[66:69], v[6:9]
	v_mfma_f32_16x16x32_bf16 v[2:5], v[234:237], v[66:69], v[2:5]
	v_mfma_f32_16x16x32_bf16 v[34:37], v[238:241], v[62:65], v[14:17]
	v_mfma_f32_16x16x32_bf16 v[6:9], v[230:233], v[178:181], v[6:9]
	v_mfma_f32_16x16x32_bf16 v[2:5], v[238:241], v[178:181], v[2:5]
	s_setprio 0
	s_add_i32 s57, s57, 2
	s_add_u32 s55, s55, 0x100
	s_addc_u32 s56, s56, 0
	s_cmp_gt_u32 s57, 13
	s_mov_b64 s[4:5], s[36:37]
	s_barrier
	s_cbranch_scc0 .LBB0_396
	v_lshl_or_b32 v202, s27, 8, v208
	s_and_b32 s4, s27, -4
	v_ashrrev_i32_e32 v203, 31, v202
	v_lshlrev_b64 v[14:15], 2, v[202:203]
	v_lshl_add_u64 v[16:17], s[10:11], 0, v[14:15]
	v_lshl_add_u64 v[22:23], s[12:13], 0, v[14:15]
	flat_load_dwordx4 v[70:73], v[16:17]
	flat_load_dwordx4 v[66:69], v[22:23]
	s_cmp_eq_u32 s4, 4
	s_cselect_b64 s[36:37], -1, 0
	s_cmp_lg_u32 s4, 4
	v_mov_b32_e32 v46, 0
	v_and_b32_e32 v210, 0x3ff, v202
	v_mov_b32_e32 v62, 0
	v_mov_b32_e32 v63, 0
	v_mov_b32_e32 v64, 0
	v_mov_b32_e32 v65, 0
	s_cbranch_scc1 .LBB0_399
	v_lshlrev_b32_e32 v14, 2, v210
	v_mov_b32_e32 v15, v0
	v_lshl_add_u64 v[14:15], s[14:15], 0, v[14:15]
	flat_load_dwordx4 v[62:65], v[14:15]

.LBB0_1098:
	s_add_i32 s76, s76, 1
	s_mov_b64 s[62:63], s[54:55]
	s_mul_i32 s54, s76, s26
	s_add_i32 s64, s54, s2
	s_cmpk_gt_i32 s64, 0x57f
	s_cselect_b64 s[60:61], -1, 0
	s_lshl_b32 s54, s64, 3
	s_and_b32 s54, s54, 56
	s_bfe_u32 s55, s64, 0x30003
	s_or_b32 s77, s54, s55
	s_ashr_i32 s58, s64, 6
	s_lshl_b32 s54, s77, 19
	s_mov_b64 s[36:37], s[56:57]
	s_add_u32 s56, s52, s54
	s_addc_u32 s57, s53, 0
	s_ashr_i32 s59, s58, 31
	s_lshl_b64 s[54:55], s[58:59], 19
	s_add_u32 s54, s4, s54
	s_addc_u32 s55, s5, s55
	s_cmpk_lt_i32 s64, 0x580
	s_cselect_b32 s59, s57, s37
	s_cselect_b32 s78, s56, s36
	s_cselect_b32 s79, s55, s63
	s_cselect_b32 s80, s54, s62
	s_add_u32 s81, s62, 0x100
	s_addc_u32 s82, s63, 0
	s_mov_b32 s83, -2
	s_add_u32 s62, s36, 0x100
	s_addc_u32 s63, s37, 0
	s_add_i32 s84, 0, 0x10000
	v_add_u32_e32 v70, s84, v170
	ds_read_b128 v[58:61], v70
	ds_read_b128 v[62:65], v70 offset:1024
	ds_read_b128 v[66:69], v70 offset:2048
	ds_read_b128 v[70:73], v70 offset:3072
	s_cmp_eq_u32 s83, 12
	s_cselect_b32 s67, s59, s63
	s_cselect_b32 s66, s78, s62
	s_cselect_b32 s65, s79, s82
	s_cselect_b32 s64, s80, s81
	v_lshl_add_u64 v[192:193], s[36:37], 0, v[168:169]
	s_add_i32 m0, s69, 0xc000
	ds_read_b128 v[78:81], v175
	ds_read_b128 v[86:89], v175 offset:1024
	ds_read_b128 v[90:93], v175 offset:2048
	ds_read_b128 v[94:97], v175 offset:3072
	ds_read_b128 v[176:179], v175 offset:4096
	ds_read_b128 v[180:183], v175 offset:5120
	ds_read_b128 v[184:187], v175 offset:6144
	ds_read_b128 v[188:191], v175 offset:7168
	global_load_lds_dwordx4 v[192:193], off
	v_lshl_add_u64 v[192:193], s[36:37], 0, v[166:167]
	s_add_i32 m0, s69, 0xe000
	s_nop 0
	global_load_lds_dwordx4 v[192:193], off
	s_waitcnt lgkmcnt(8)
	s_waitcnt vmcnt(10)
	s_barrier
	s_waitcnt lgkmcnt(0)
	s_setprio 1
	s_waitcnt lgkmcnt(0)
	v_mfma_f32_16x16x32_bf16 v[158:161], v[58:61], v[78:81], 0
	v_mfma_f32_16x16x32_bf16 v[150:153], v[66:69], v[78:81], 0
	v_mfma_f32_16x16x32_bf16 v[142:145], v[58:61], v[90:93], 0
	v_mfma_f32_16x16x32_bf16 v[134:137], v[66:69], v[90:93], 0
	v_mfma_f32_16x16x32_bf16 v[126:129], v[58:61], v[176:179], 0
	v_mfma_f32_16x16x32_bf16 v[118:121], v[66:69], v[176:179], 0
	v_mfma_f32_16x16x32_bf16 v[110:113], v[58:61], v[184:187], 0
	v_mfma_f32_16x16x32_bf16 v[102:105], v[66:69], v[184:187], 0
	v_mfma_f32_16x16x32_bf16 v[158:161], v[62:65], v[86:89], v[158:161]
	v_mfma_f32_16x16x32_bf16 v[150:153], v[70:73], v[86:89], v[150:153]
	v_mfma_f32_16x16x32_bf16 v[142:145], v[62:65], v[94:97], v[142:145]
	v_mfma_f32_16x16x32_bf16 v[134:137], v[70:73], v[94:97], v[134:137]
	v_mfma_f32_16x16x32_bf16 v[126:129], v[62:65], v[180:183], v[126:129]
	v_mfma_f32_16x16x32_bf16 v[118:121], v[70:73], v[180:183], v[118:121]
	v_mfma_f32_16x16x32_bf16 v[110:113], v[62:65], v[188:191], v[110:113]
	v_mfma_f32_16x16x32_bf16 v[102:105], v[70:73], v[188:191], v[102:105]
	s_setprio 0
	s_barrier
	s_add_i32 s85, 0, 0x14000
	v_add_u32_e32 v192, s85, v170
	s_add_i32 s36, s84, s68
	ds_read_b128 v[200:203], v192
	ds_read_b128 v[204:207], v192 offset:1024
	ds_read_b128 v[208:211], v192 offset:2048
	ds_read_b128 v[222:225], v192 offset:3072
	v_lshl_add_u64 v[192:193], s[64:65], 0, v[164:165]
	s_mov_b32 m0, s36
	v_lshl_add_u64 v[214:215], s[64:65], 0, v[162:163]
	global_load_lds_dwordx4 v[192:193], off
	s_add_i32 m0, s36, 0x2000
	s_nop 0
	global_load_lds_dwordx4 v[214:215], off
	s_waitcnt vmcnt(10)
	s_barrier
	s_waitcnt lgkmcnt(0)
	s_setprio 1
	s_waitcnt lgkmcnt(0)
	v_mfma_f32_16x16x32_bf16 v[154:157], v[200:203], v[78:81], 0
	v_mfma_f32_16x16x32_bf16 v[78:81], v[208:211], v[78:81], 0
	v_mfma_f32_16x16x32_bf16 v[154:157], v[204:207], v[86:89], v[154:157]
	v_mfma_f32_16x16x32_bf16 v[78:81], v[222:225], v[86:89], v[78:81]
	v_mfma_f32_16x16x32_bf16 v[86:89], v[200:203], v[90:93], 0
	v_mfma_f32_16x16x32_bf16 v[90:93], v[208:211], v[90:93], 0
	v_mfma_f32_16x16x32_bf16 v[114:117], v[208:211], v[176:179], 0
	v_mfma_f32_16x16x32_bf16 v[106:109], v[200:203], v[184:187], 0
	v_mfma_f32_16x16x32_bf16 v[98:101], v[208:211], v[184:187], 0
	v_mfma_f32_16x16x32_bf16 v[86:89], v[204:207], v[94:97], v[86:89]
	v_mfma_f32_16x16x32_bf16 v[90:93], v[222:225], v[94:97], v[90:93]
	v_mfma_f32_16x16x32_bf16 v[94:97], v[200:203], v[176:179], 0
	v_mfma_f32_16x16x32_bf16 v[114:117], v[222:225], v[180:183], v[114:117]
	v_mfma_f32_16x16x32_bf16 v[106:109], v[204:207], v[188:191], v[106:109]
	v_mfma_f32_16x16x32_bf16 v[98:101], v[222:225], v[188:191], v[98:101]
	v_mfma_f32_16x16x32_bf16 v[94:97], v[204:207], v[180:183], v[94:97]
	s_setprio 0
	s_mov_b32 m0, s69
	v_lshl_add_u64 v[234:235], s[66:67], 0, v[164:165]
	s_barrier
	ds_read_b128 v[122:125], v175 offset:16384
	ds_read_b128 v[130:133], v175 offset:17408
	ds_read_b128 v[138:141], v175 offset:18432
	ds_read_b128 v[146:149], v175 offset:19456
	ds_read_b128 v[176:179], v175 offset:20480
	ds_read_b128 v[180:183], v175 offset:21504
	ds_read_b128 v[184:187], v175 offset:22528
	ds_read_b128 v[188:191], v175 offset:23552
	global_load_lds_dwordx4 v[234:235], off
	v_lshl_add_u64 v[236:237], s[66:67], 0, v[162:163]
	s_mov_b32 m0, s70
	s_nop 0
	global_load_lds_dwordx4 v[236:237], off
	s_barrier
	s_waitcnt lgkmcnt(0)
	s_setprio 1
	s_waitcnt lgkmcnt(0)
	v_mfma_f32_16x16x32_bf16 v[82:85], v[58:61], v[122:125], 0
	v_mfma_f32_16x16x32_bf16 v[54:57], v[66:69], v[122:125], 0
	v_mfma_f32_16x16x32_bf16 v[46:49], v[58:61], v[138:141], 0
	v_mfma_f32_16x16x32_bf16 v[38:41], v[66:69], v[138:141], 0
	v_mfma_f32_16x16x32_bf16 v[30:33], v[58:61], v[176:179], 0
	v_mfma_f32_16x16x32_bf16 v[22:25], v[66:69], v[176:179], 0
	v_mfma_f32_16x16x32_bf16 v[14:17], v[58:61], v[184:187], 0
	v_mfma_f32_16x16x32_bf16 v[6:9], v[66:69], v[184:187], 0
	v_mfma_f32_16x16x32_bf16 v[82:85], v[62:65], v[130:133], v[82:85]
	v_mfma_f32_16x16x32_bf16 v[54:57], v[70:73], v[130:133], v[54:57]
	v_mfma_f32_16x16x32_bf16 v[46:49], v[62:65], v[146:149], v[46:49]
	v_mfma_f32_16x16x32_bf16 v[38:41], v[70:73], v[146:149], v[38:41]
	v_mfma_f32_16x16x32_bf16 v[30:33], v[62:65], v[180:183], v[30:33]
	v_mfma_f32_16x16x32_bf16 v[22:25], v[70:73], v[180:183], v[22:25]
	v_mfma_f32_16x16x32_bf16 v[14:17], v[62:65], v[188:191], v[14:17]
	v_mfma_f32_16x16x32_bf16 v[6:9], v[70:73], v[188:191], v[6:9]
	s_setprio 0
	s_barrier
	s_add_u32 s36, s64, 0x40000
	s_addc_u32 s37, s65, 0
	s_add_i32 s84, s85, s68
	v_lshl_add_u64 v[58:59], s[36:37], 0, v[164:165]
	s_mov_b32 m0, s84
	s_nop 0
	global_load_lds_dwordx4 v[58:59], off
	v_lshl_add_u64 v[58:59], s[36:37], 0, v[162:163]
	s_add_i32 m0, s84, 0x2000
	s_nop 0
	global_load_lds_dwordx4 v[58:59], off
	s_waitcnt vmcnt(10)
	s_barrier
	s_setprio 1
	v_mfma_f32_16x16x32_bf16 v[50:53], v[208:211], v[122:125], 0
	v_mfma_f32_16x16x32_bf16 v[42:45], v[200:203], v[138:141], 0
	v_mfma_f32_16x16x32_bf16 v[34:37], v[208:211], v[138:141], 0
	v_mfma_f32_16x16x32_bf16 v[26:29], v[200:203], v[176:179], 0
	v_mfma_f32_16x16x32_bf16 v[18:21], v[208:211], v[176:179], 0
	v_mfma_f32_16x16x32_bf16 v[10:13], v[200:203], v[184:187], 0
	v_mfma_f32_16x16x32_bf16 v[2:5], v[208:211], v[184:187], 0
	v_mfma_f32_16x16x32_bf16 v[58:61], v[200:203], v[122:125], 0
	v_mfma_f32_16x16x32_bf16 v[50:53], v[222:225], v[130:133], v[50:53]
	v_mfma_f32_16x16x32_bf16 v[42:45], v[204:207], v[146:149], v[42:45]
	v_mfma_f32_16x16x32_bf16 v[34:37], v[222:225], v[146:149], v[34:37]
	v_mfma_f32_16x16x32_bf16 v[26:29], v[204:207], v[180:183], v[26:29]
	v_mfma_f32_16x16x32_bf16 v[18:21], v[222:225], v[180:183], v[18:21]
	v_mfma_f32_16x16x32_bf16 v[10:13], v[204:207], v[188:191], v[10:13]
	v_mfma_f32_16x16x32_bf16 v[2:5], v[222:225], v[188:191], v[2:5]
	v_mfma_f32_16x16x32_bf16 v[58:61], v[204:207], v[130:133], v[58:61]
	s_setprio 0
	s_add_i32 s84, 0, 0x18000
	v_add_u32_e32 v74, s84, v170
	s_barrier
	ds_read_b128 v[62:65], v74
	ds_read_b128 v[66:69], v74 offset:1024
	ds_read_b128 v[70:73], v74 offset:2048
	ds_read_b128 v[74:77], v74 offset:3072
	s_add_u32 s36, s66, 0x40000
	s_addc_u32 s37, s67, 0
	s_mov_b32 m0, s71
	v_lshl_add_u64 v[138:139], s[36:37], 0, v[164:165]
	ds_read_b128 v[122:125], v175 offset:32768
	ds_read_b128 v[130:133], v175 offset:33792
	ds_read_b128 v[176:179], v175 offset:34816
	ds_read_b128 v[180:183], v175 offset:35840
	ds_read_b128 v[184:187], v175 offset:36864
	ds_read_b128 v[188:191], v175 offset:37888
	ds_read_b128 v[200:203], v175 offset:38912
	ds_read_b128 v[204:207], v175 offset:39936
	global_load_lds_dwordx4 v[138:139], off
	v_lshl_add_u64 v[138:139], s[36:37], 0, v[162:163]
	s_mov_b32 m0, s72
	s_nop 0
	global_load_lds_dwordx4 v[138:139], off
	s_waitcnt lgkmcnt(8)
	s_waitcnt vmcnt(10)
	s_barrier
	s_waitcnt lgkmcnt(0)
	s_setprio 1
	s_waitcnt lgkmcnt(0)
	v_mfma_f32_16x16x32_bf16 v[138:141], v[62:65], v[122:125], v[158:161]
	v_mfma_f32_16x16x32_bf16 v[158:161], v[66:69], v[130:133], v[138:141]
	v_mfma_f32_16x16x32_bf16 v[138:141], v[70:73], v[122:125], v[150:153]
	v_mfma_f32_16x16x32_bf16 v[150:153], v[74:77], v[130:133], v[138:141]
	v_mfma_f32_16x16x32_bf16 v[138:141], v[62:65], v[176:179], v[142:145]
	v_mfma_f32_16x16x32_bf16 v[134:137], v[70:73], v[176:179], v[134:137]
	v_mfma_f32_16x16x32_bf16 v[126:129], v[62:65], v[184:187], v[126:129]
	v_mfma_f32_16x16x32_bf16 v[118:121], v[70:73], v[184:187], v[118:121]
	v_mfma_f32_16x16x32_bf16 v[110:113], v[62:65], v[200:203], v[110:113]
	v_mfma_f32_16x16x32_bf16 v[102:105], v[70:73], v[200:203], v[102:105]
	v_mfma_f32_16x16x32_bf16 v[142:145], v[66:69], v[180:183], v[138:141]
	v_mfma_f32_16x16x32_bf16 v[134:137], v[74:77], v[180:183], v[134:137]
	v_mfma_f32_16x16x32_bf16 v[126:129], v[66:69], v[188:191], v[126:129]
	v_mfma_f32_16x16x32_bf16 v[118:121], v[74:77], v[188:191], v[118:121]
	v_mfma_f32_16x16x32_bf16 v[110:113], v[66:69], v[204:207], v[110:113]
	v_mfma_f32_16x16x32_bf16 v[102:105], v[74:77], v[204:207], v[102:105]
	s_setprio 0
	s_barrier
	s_add_i32 s66, 0, 0x1c000
	v_add_u32_e32 v138, s66, v170
	s_add_i32 s36, s84, s68
	ds_read_b128 v[208:211], v138
	ds_read_b128 v[222:225], v138 offset:1024
	ds_read_b128 v[226:229], v138 offset:2048
	ds_read_b128 v[230:233], v138 offset:3072
	v_lshl_add_u64 v[138:139], v[192:193], 0, s[22:23]
	s_mov_b32 m0, s36
	s_nop 0
	global_load_lds_dwordx4 v[138:139], off
	v_lshl_add_u64 v[138:139], v[214:215], 0, s[22:23]
	s_add_i32 m0, s36, 0x2000
	s_nop 0
	global_load_lds_dwordx4 v[138:139], off
	s_waitcnt vmcnt(10)
	s_barrier
	s_waitcnt lgkmcnt(0)
	s_setprio 1
	s_waitcnt lgkmcnt(0)
	v_mfma_f32_16x16x32_bf16 v[78:81], v[226:229], v[122:125], v[78:81]
	v_mfma_f32_16x16x32_bf16 v[138:141], v[208:211], v[122:125], v[154:157]
	v_mfma_f32_16x16x32_bf16 v[146:149], v[230:233], v[130:133], v[78:81]
	v_mfma_f32_16x16x32_bf16 v[78:81], v[208:211], v[176:179], v[86:89]
	v_mfma_f32_16x16x32_bf16 v[154:157], v[222:225], v[130:133], v[138:141]
	v_mfma_f32_16x16x32_bf16 v[138:141], v[222:225], v[180:183], v[78:81]
	v_mfma_f32_16x16x32_bf16 v[78:81], v[226:229], v[176:179], v[90:93]
	v_mfma_f32_16x16x32_bf16 v[130:133], v[230:233], v[180:183], v[78:81]
	v_mfma_f32_16x16x32_bf16 v[78:81], v[208:211], v[184:187], v[94:97]
	v_mfma_f32_16x16x32_bf16 v[122:125], v[222:225], v[188:191], v[78:81]
	v_mfma_f32_16x16x32_bf16 v[78:81], v[226:229], v[184:187], v[114:117]
	v_mfma_f32_16x16x32_bf16 v[114:117], v[230:233], v[188:191], v[78:81]
	v_mfma_f32_16x16x32_bf16 v[78:81], v[208:211], v[200:203], v[106:109]
	v_mfma_f32_16x16x32_bf16 v[106:109], v[222:225], v[204:207], v[78:81]
	v_mfma_f32_16x16x32_bf16 v[78:81], v[226:229], v[200:203], v[98:101]
	v_mfma_f32_16x16x32_bf16 v[98:101], v[230:233], v[204:207], v[78:81]
	s_setprio 0
	s_mov_b32 m0, s73
	v_lshl_add_u64 v[192:193], v[234:235], 0, s[22:23]
	s_barrier
	s_nop 2
	ds_read_b128 v[78:81], v175 offset:49152
	ds_read_b128 v[86:89], v175 offset:50176
	ds_read_b128 v[90:93], v175 offset:51200
	ds_read_b128 v[94:97], v175 offset:52224
	ds_read_b128 v[176:179], v175 offset:53248
	ds_read_b128 v[180:183], v175 offset:54272
	ds_read_b128 v[184:187], v175 offset:55296
	ds_read_b128 v[188:191], v175 offset:56320
	global_load_lds_dwordx4 v[192:193], off
	v_lshl_add_u64 v[192:193], v[236:237], 0, s[22:23]
	s_mov_b32 m0, s75
	s_nop 0
	global_load_lds_dwordx4 v[192:193], off
	s_barrier
	s_waitcnt lgkmcnt(0)
	s_setprio 1
	s_waitcnt lgkmcnt(0)
	v_mfma_f32_16x16x32_bf16 v[82:85], v[62:65], v[78:81], v[82:85]
	v_mfma_f32_16x16x32_bf16 v[54:57], v[70:73], v[78:81], v[54:57]
	v_mfma_f32_16x16x32_bf16 v[46:49], v[62:65], v[90:93], v[46:49]
	v_mfma_f32_16x16x32_bf16 v[38:41], v[70:73], v[90:93], v[38:41]
	v_mfma_f32_16x16x32_bf16 v[30:33], v[62:65], v[176:179], v[30:33]
	v_mfma_f32_16x16x32_bf16 v[22:25], v[70:73], v[176:179], v[22:25]
	v_mfma_f32_16x16x32_bf16 v[14:17], v[62:65], v[184:187], v[14:17]
	v_mfma_f32_16x16x32_bf16 v[6:9], v[70:73], v[184:187], v[6:9]
	v_mfma_f32_16x16x32_bf16 v[82:85], v[66:69], v[86:89], v[82:85]
	v_mfma_f32_16x16x32_bf16 v[54:57], v[74:77], v[86:89], v[54:57]
	v_mfma_f32_16x16x32_bf16 v[46:49], v[66:69], v[94:97], v[46:49]
	v_mfma_f32_16x16x32_bf16 v[38:41], v[74:77], v[94:97], v[38:41]
	v_mfma_f32_16x16x32_bf16 v[30:33], v[66:69], v[180:183], v[30:33]
	v_mfma_f32_16x16x32_bf16 v[22:25], v[74:77], v[180:183], v[22:25]
	v_mfma_f32_16x16x32_bf16 v[14:17], v[66:69], v[188:191], v[14:17]
	v_mfma_f32_16x16x32_bf16 v[6:9], v[74:77], v[188:191], v[6:9]
	s_setprio 0
	s_barrier
	s_add_u32 s36, s64, 0x40080
	s_addc_u32 s37, s65, 0
	s_add_i32 s64, s66, s68
	v_lshl_add_u64 v[62:63], s[36:37], 0, v[164:165]
	s_mov_b32 m0, s64
	s_nop 0
	global_load_lds_dwordx4 v[62:63], off
	v_lshl_add_u64 v[62:63], s[36:37], 0, v[162:163]
	s_add_i32 m0, s64, 0x2000
	s_nop 0
	global_load_lds_dwordx4 v[62:63], off
	s_waitcnt vmcnt(10)
	s_barrier
	s_setprio 1
	v_mfma_f32_16x16x32_bf16 v[58:61], v[208:211], v[78:81], v[58:61]
	v_mfma_f32_16x16x32_bf16 v[50:53], v[226:229], v[78:81], v[50:53]
	v_mfma_f32_16x16x32_bf16 v[42:45], v[208:211], v[90:93], v[42:45]
	v_mfma_f32_16x16x32_bf16 v[34:37], v[226:229], v[90:93], v[34:37]
	v_mfma_f32_16x16x32_bf16 v[26:29], v[208:211], v[176:179], v[26:29]
	v_mfma_f32_16x16x32_bf16 v[18:21], v[226:229], v[176:179], v[18:21]
	v_mfma_f32_16x16x32_bf16 v[10:13], v[208:211], v[184:187], v[10:13]
	v_mfma_f32_16x16x32_bf16 v[2:5], v[226:229], v[184:187], v[2:5]
	v_mfma_f32_16x16x32_bf16 v[74:77], v[222:225], v[86:89], v[58:61]
	v_mfma_f32_16x16x32_bf16 v[50:53], v[230:233], v[86:89], v[50:53]
	v_mfma_f32_16x16x32_bf16 v[42:45], v[222:225], v[94:97], v[42:45]
	v_mfma_f32_16x16x32_bf16 v[34:37], v[230:233], v[94:97], v[34:37]
	v_mfma_f32_16x16x32_bf16 v[26:29], v[222:225], v[180:183], v[26:29]
	v_mfma_f32_16x16x32_bf16 v[18:21], v[230:233], v[180:183], v[18:21]
	v_mfma_f32_16x16x32_bf16 v[10:13], v[222:225], v[188:191], v[10:13]
	v_mfma_f32_16x16x32_bf16 v[2:5], v[230:233], v[188:191], v[2:5]
	s_setprio 0
	s_add_i32 s83, s83, 2
	s_add_u32 s81, s81, 0x100
	s_addc_u32 s82, s82, 0
	s_cmp_gt_u32 s83, 13
	s_mov_b64 s[36:37], s[62:63]
	s_barrier
.LBB0_1099:
	s_add_u32 s62, s36, 0x100
	s_addc_u32 s63, s37, 0
	s_add_i32 s84, 0, 0x10000
	v_add_u32_e32 v70, s84, v170
	ds_read_b128 v[58:61], v70
	ds_read_b128 v[62:65], v70 offset:1024
	ds_read_b128 v[66:69], v70 offset:2048
	ds_read_b128 v[70:73], v70 offset:3072
	s_cmp_eq_u32 s83, 12
	s_cselect_b32 s67, s59, s63
	s_cselect_b32 s66, s78, s62
	s_cselect_b32 s65, s79, s82
	s_cselect_b32 s64, s80, s81
	v_lshl_add_u64 v[192:193], s[36:37], 0, v[168:169]
	s_add_i32 m0, s69, 0xc000
	ds_read_b128 v[78:81], v175
	ds_read_b128 v[86:89], v175 offset:1024
	ds_read_b128 v[90:93], v175 offset:2048
	ds_read_b128 v[94:97], v175 offset:3072
	ds_read_b128 v[176:179], v175 offset:4096
	ds_read_b128 v[180:183], v175 offset:5120
	ds_read_b128 v[184:187], v175 offset:6144
	ds_read_b128 v[188:191], v175 offset:7168
	global_load_lds_dwordx4 v[192:193], off
	v_lshl_add_u64 v[192:193], s[36:37], 0, v[166:167]
	s_add_i32 m0, s69, 0xe000
	s_nop 0
	global_load_lds_dwordx4 v[192:193], off
	s_waitcnt lgkmcnt(8)
	s_waitcnt vmcnt(10)
	s_barrier
	s_waitcnt lgkmcnt(0)
	s_setprio 1
	s_waitcnt lgkmcnt(0)
	v_mfma_f32_16x16x32_bf16 v[158:161], v[58:61], v[78:81], v[158:161]
	v_mfma_f32_16x16x32_bf16 v[150:153], v[66:69], v[78:81], v[150:153]
	v_mfma_f32_16x16x32_bf16 v[142:145], v[58:61], v[90:93], v[142:145]
	v_mfma_f32_16x16x32_bf16 v[134:137], v[66:69], v[90:93], v[134:137]
	v_mfma_f32_16x16x32_bf16 v[126:129], v[58:61], v[176:179], v[126:129]
	v_mfma_f32_16x16x32_bf16 v[118:121], v[66:69], v[176:179], v[118:121]
	v_mfma_f32_16x16x32_bf16 v[110:113], v[58:61], v[184:187], v[110:113]
	v_mfma_f32_16x16x32_bf16 v[102:105], v[66:69], v[184:187], v[102:105]
	v_mfma_f32_16x16x32_bf16 v[158:161], v[62:65], v[86:89], v[158:161]
	v_mfma_f32_16x16x32_bf16 v[150:153], v[70:73], v[86:89], v[150:153]
	v_mfma_f32_16x16x32_bf16 v[142:145], v[62:65], v[94:97], v[142:145]
	v_mfma_f32_16x16x32_bf16 v[134:137], v[70:73], v[94:97], v[134:137]
	v_mfma_f32_16x16x32_bf16 v[126:129], v[62:65], v[180:183], v[126:129]
	v_mfma_f32_16x16x32_bf16 v[118:121], v[70:73], v[180:183], v[118:121]
	v_mfma_f32_16x16x32_bf16 v[110:113], v[62:65], v[188:191], v[110:113]
	v_mfma_f32_16x16x32_bf16 v[102:105], v[70:73], v[188:191], v[102:105]
	s_setprio 0
	s_barrier
	s_add_i32 s85, 0, 0x14000
	v_add_u32_e32 v192, s85, v170
	s_add_i32 s36, s84, s68
	ds_read_b128 v[200:203], v192
	ds_read_b128 v[204:207], v192 offset:1024
	ds_read_b128 v[208:211], v192 offset:2048
	ds_read_b128 v[222:225], v192 offset:3072
	v_lshl_add_u64 v[192:193], s[64:65], 0, v[164:165]
	s_mov_b32 m0, s36
	v_lshl_add_u64 v[214:215], s[64:65], 0, v[162:163]
	global_load_lds_dwordx4 v[192:193], off
	s_add_i32 m0, s36, 0x2000
	s_nop 0
	global_load_lds_dwordx4 v[214:215], off
	s_waitcnt vmcnt(10)
	s_barrier
	s_waitcnt lgkmcnt(0)
	s_setprio 1
	s_waitcnt lgkmcnt(0)
	v_mfma_f32_16x16x32_bf16 v[154:157], v[200:203], v[78:81], v[154:157]
	v_mfma_f32_16x16x32_bf16 v[78:81], v[208:211], v[78:81], v[146:149]
	v_mfma_f32_16x16x32_bf16 v[154:157], v[204:207], v[86:89], v[154:157]
	v_mfma_f32_16x16x32_bf16 v[78:81], v[222:225], v[86:89], v[78:81]
	v_mfma_f32_16x16x32_bf16 v[86:89], v[200:203], v[90:93], v[138:141]
	v_mfma_f32_16x16x32_bf16 v[90:93], v[208:211], v[90:93], v[130:133]
	v_mfma_f32_16x16x32_bf16 v[114:117], v[208:211], v[176:179], v[114:117]
	v_mfma_f32_16x16x32_bf16 v[106:109], v[200:203], v[184:187], v[106:109]
	v_mfma_f32_16x16x32_bf16 v[98:101], v[208:211], v[184:187], v[98:101]
	v_mfma_f32_16x16x32_bf16 v[86:89], v[204:207], v[94:97], v[86:89]
	v_mfma_f32_16x16x32_bf16 v[90:93], v[222:225], v[94:97], v[90:93]
	v_mfma_f32_16x16x32_bf16 v[94:97], v[200:203], v[176:179], v[122:125]
	v_mfma_f32_16x16x32_bf16 v[114:117], v[222:225], v[180:183], v[114:117]
	v_mfma_f32_16x16x32_bf16 v[106:109], v[204:207], v[188:191], v[106:109]
	v_mfma_f32_16x16x32_bf16 v[98:101], v[222:225], v[188:191], v[98:101]
	v_mfma_f32_16x16x32_bf16 v[94:97], v[204:207], v[180:183], v[94:97]
	s_setprio 0
	s_mov_b32 m0, s69
	v_lshl_add_u64 v[234:235], s[66:67], 0, v[164:165]
	s_barrier
	ds_read_b128 v[122:125], v175 offset:16384
	ds_read_b128 v[130:133], v175 offset:17408
	ds_read_b128 v[138:141], v175 offset:18432
	ds_read_b128 v[146:149], v175 offset:19456
	ds_read_b128 v[176:179], v175 offset:20480
	ds_read_b128 v[180:183], v175 offset:21504
	ds_read_b128 v[184:187], v175 offset:22528
	ds_read_b128 v[188:191], v175 offset:23552
	global_load_lds_dwordx4 v[234:235], off
	v_lshl_add_u64 v[236:237], s[66:67], 0, v[162:163]
	s_mov_b32 m0, s70
	s_nop 0
	global_load_lds_dwordx4 v[236:237], off
	s_barrier
	s_waitcnt lgkmcnt(0)
	s_setprio 1
	s_waitcnt lgkmcnt(0)
	v_mfma_f32_16x16x32_bf16 v[82:85], v[58:61], v[122:125], v[82:85]
	v_mfma_f32_16x16x32_bf16 v[54:57], v[66:69], v[122:125], v[54:57]
	v_mfma_f32_16x16x32_bf16 v[46:49], v[58:61], v[138:141], v[46:49]
	v_mfma_f32_16x16x32_bf16 v[38:41], v[66:69], v[138:141], v[38:41]
	v_mfma_f32_16x16x32_bf16 v[30:33], v[58:61], v[176:179], v[30:33]
	v_mfma_f32_16x16x32_bf16 v[22:25], v[66:69], v[176:179], v[22:25]
	v_mfma_f32_16x16x32_bf16 v[14:17], v[58:61], v[184:187], v[14:17]
	v_mfma_f32_16x16x32_bf16 v[6:9], v[66:69], v[184:187], v[6:9]
	v_mfma_f32_16x16x32_bf16 v[82:85], v[62:65], v[130:133], v[82:85]
	v_mfma_f32_16x16x32_bf16 v[54:57], v[70:73], v[130:133], v[54:57]
	v_mfma_f32_16x16x32_bf16 v[46:49], v[62:65], v[146:149], v[46:49]
	v_mfma_f32_16x16x32_bf16 v[38:41], v[70:73], v[146:149], v[38:41]
	v_mfma_f32_16x16x32_bf16 v[30:33], v[62:65], v[180:183], v[30:33]
	v_mfma_f32_16x16x32_bf16 v[22:25], v[70:73], v[180:183], v[22:25]
	v_mfma_f32_16x16x32_bf16 v[14:17], v[62:65], v[188:191], v[14:17]
	v_mfma_f32_16x16x32_bf16 v[6:9], v[70:73], v[188:191], v[6:9]
	s_setprio 0
	s_barrier
	s_add_u32 s36, s64, 0x40000
	s_addc_u32 s37, s65, 0
	s_add_i32 s84, s85, s68
	v_lshl_add_u64 v[58:59], s[36:37], 0, v[164:165]
	s_mov_b32 m0, s84
	s_nop 0
	global_load_lds_dwordx4 v[58:59], off
	v_lshl_add_u64 v[58:59], s[36:37], 0, v[162:163]
	s_add_i32 m0, s84, 0x2000
	s_nop 0
	global_load_lds_dwordx4 v[58:59], off
	s_waitcnt vmcnt(10)
	s_barrier
	s_setprio 1
	v_mfma_f32_16x16x32_bf16 v[50:53], v[208:211], v[122:125], v[50:53]
	v_mfma_f32_16x16x32_bf16 v[42:45], v[200:203], v[138:141], v[42:45]
	v_mfma_f32_16x16x32_bf16 v[34:37], v[208:211], v[138:141], v[34:37]
	v_mfma_f32_16x16x32_bf16 v[26:29], v[200:203], v[176:179], v[26:29]
	v_mfma_f32_16x16x32_bf16 v[18:21], v[208:211], v[176:179], v[18:21]
	v_mfma_f32_16x16x32_bf16 v[10:13], v[200:203], v[184:187], v[10:13]
	v_mfma_f32_16x16x32_bf16 v[2:5], v[208:211], v[184:187], v[2:5]
	v_mfma_f32_16x16x32_bf16 v[58:61], v[200:203], v[122:125], v[74:77]
	v_mfma_f32_16x16x32_bf16 v[50:53], v[222:225], v[130:133], v[50:53]
	v_mfma_f32_16x16x32_bf16 v[42:45], v[204:207], v[146:149], v[42:45]
	v_mfma_f32_16x16x32_bf16 v[34:37], v[222:225], v[146:149], v[34:37]
	v_mfma_f32_16x16x32_bf16 v[26:29], v[204:207], v[180:183], v[26:29]
	v_mfma_f32_16x16x32_bf16 v[18:21], v[222:225], v[180:183], v[18:21]
	v_mfma_f32_16x16x32_bf16 v[10:13], v[204:207], v[188:191], v[10:13]
	v_mfma_f32_16x16x32_bf16 v[2:5], v[222:225], v[188:191], v[2:5]
	v_mfma_f32_16x16x32_bf16 v[58:61], v[204:207], v[130:133], v[58:61]
	s_setprio 0
	s_add_i32 s84, 0, 0x18000
	v_add_u32_e32 v74, s84, v170
	s_barrier
	ds_read_b128 v[62:65], v74
	ds_read_b128 v[66:69], v74 offset:1024
	ds_read_b128 v[70:73], v74 offset:2048
	ds_read_b128 v[74:77], v74 offset:3072
	s_add_u32 s36, s66, 0x40000
	s_addc_u32 s37, s67, 0
	s_mov_b32 m0, s71
	v_lshl_add_u64 v[138:139], s[36:37], 0, v[164:165]
	ds_read_b128 v[122:125], v175 offset:32768
	ds_read_b128 v[130:133], v175 offset:33792
	ds_read_b128 v[176:179], v175 offset:34816
	ds_read_b128 v[180:183], v175 offset:35840
	ds_read_b128 v[184:187], v175 offset:36864
	ds_read_b128 v[188:191], v175 offset:37888
	ds_read_b128 v[200:203], v175 offset:38912
	ds_read_b128 v[204:207], v175 offset:39936
	global_load_lds_dwordx4 v[138:139], off
	v_lshl_add_u64 v[138:139], s[36:37], 0, v[162:163]
	s_mov_b32 m0, s72
	s_nop 0
	global_load_lds_dwordx4 v[138:139], off
	s_waitcnt lgkmcnt(8)
	s_waitcnt vmcnt(10)
	s_barrier
	s_waitcnt lgkmcnt(0)
	s_setprio 1
	s_waitcnt lgkmcnt(0)
	v_mfma_f32_16x16x32_bf16 v[138:141], v[62:65], v[122:125], v[158:161]
	v_mfma_f32_16x16x32_bf16 v[158:161], v[66:69], v[130:133], v[138:141]
	v_mfma_f32_16x16x32_bf16 v[138:141], v[70:73], v[122:125], v[150:153]
	v_mfma_f32_16x16x32_bf16 v[150:153], v[74:77], v[130:133], v[138:141]
	v_mfma_f32_16x16x32_bf16 v[138:141], v[62:65], v[176:179], v[142:145]
	v_mfma_f32_16x16x32_bf16 v[134:137], v[70:73], v[176:179], v[134:137]
	v_mfma_f32_16x16x32_bf16 v[126:129], v[62:65], v[184:187], v[126:129]
	v_mfma_f32_16x16x32_bf16 v[118:121], v[70:73], v[184:187], v[118:121]
	v_mfma_f32_16x16x32_bf16 v[110:113], v[62:65], v[200:203], v[110:113]
	v_mfma_f32_16x16x32_bf16 v[102:105], v[70:73], v[200:203], v[102:105]
	v_mfma_f32_16x16x32_bf16 v[142:145], v[66:69], v[180:183], v[138:141]
	v_mfma_f32_16x16x32_bf16 v[134:137], v[74:77], v[180:183], v[134:137]
	v_mfma_f32_16x16x32_bf16 v[126:129], v[66:69], v[188:191], v[126:129]
	v_mfma_f32_16x16x32_bf16 v[118:121], v[74:77], v[188:191], v[118:121]
	v_mfma_f32_16x16x32_bf16 v[110:113], v[66:69], v[204:207], v[110:113]
	v_mfma_f32_16x16x32_bf16 v[102:105], v[74:77], v[204:207], v[102:105]
	s_setprio 0
	s_barrier
	s_add_i32 s66, 0, 0x1c000
	v_add_u32_e32 v138, s66, v170
	s_add_i32 s36, s84, s68
	ds_read_b128 v[208:211], v138
	ds_read_b128 v[222:225], v138 offset:1024
	ds_read_b128 v[226:229], v138 offset:2048
	ds_read_b128 v[230:233], v138 offset:3072
	v_lshl_add_u64 v[138:139], v[192:193], 0, s[22:23]
	s_mov_b32 m0, s36
	s_nop 0
	global_load_lds_dwordx4 v[138:139], off
	v_lshl_add_u64 v[138:139], v[214:215], 0, s[22:23]
	s_add_i32 m0, s36, 0x2000
	s_nop 0
	global_load_lds_dwordx4 v[138:139], off
	s_waitcnt vmcnt(10)
	s_barrier
	s_waitcnt lgkmcnt(0)
	s_setprio 1
	s_waitcnt lgkmcnt(0)
	v_mfma_f32_16x16x32_bf16 v[78:81], v[226:229], v[122:125], v[78:81]
	v_mfma_f32_16x16x32_bf16 v[138:141], v[208:211], v[122:125], v[154:157]
	v_mfma_f32_16x16x32_bf16 v[146:149], v[230:233], v[130:133], v[78:81]
	v_mfma_f32_16x16x32_bf16 v[78:81], v[208:211], v[176:179], v[86:89]
	v_mfma_f32_16x16x32_bf16 v[154:157], v[222:225], v[130:133], v[138:141]
	v_mfma_f32_16x16x32_bf16 v[138:141], v[222:225], v[180:183], v[78:81]
	v_mfma_f32_16x16x32_bf16 v[78:81], v[226:229], v[176:179], v[90:93]
	v_mfma_f32_16x16x32_bf16 v[130:133], v[230:233], v[180:183], v[78:81]
	v_mfma_f32_16x16x32_bf16 v[78:81], v[208:211], v[184:187], v[94:97]
	v_mfma_f32_16x16x32_bf16 v[122:125], v[222:225], v[188:191], v[78:81]
	v_mfma_f32_16x16x32_bf16 v[78:81], v[226:229], v[184:187], v[114:117]
	v_mfma_f32_16x16x32_bf16 v[114:117], v[230:233], v[188:191], v[78:81]
	v_mfma_f32_16x16x32_bf16 v[78:81], v[208:211], v[200:203], v[106:109]
	v_mfma_f32_16x16x32_bf16 v[106:109], v[222:225], v[204:207], v[78:81]
	v_mfma_f32_16x16x32_bf16 v[78:81], v[226:229], v[200:203], v[98:101]
	v_mfma_f32_16x16x32_bf16 v[98:101], v[230:233], v[204:207], v[78:81]
	s_setprio 0
	s_mov_b32 m0, s73
	v_lshl_add_u64 v[192:193], v[234:235], 0, s[22:23]
	s_barrier
	s_nop 2
	ds_read_b128 v[78:81], v175 offset:49152
	ds_read_b128 v[86:89], v175 offset:50176
	ds_read_b128 v[90:93], v175 offset:51200
	ds_read_b128 v[94:97], v175 offset:52224
	ds_read_b128 v[176:179], v175 offset:53248
	ds_read_b128 v[180:183], v175 offset:54272
	ds_read_b128 v[184:187], v175 offset:55296
	ds_read_b128 v[188:191], v175 offset:56320
	global_load_lds_dwordx4 v[192:193], off
	v_lshl_add_u64 v[192:193], v[236:237], 0, s[22:23]
	s_mov_b32 m0, s75
	s_nop 0
	global_load_lds_dwordx4 v[192:193], off
	s_barrier
	s_waitcnt lgkmcnt(0)
	s_setprio 1
	s_waitcnt lgkmcnt(0)
	v_mfma_f32_16x16x32_bf16 v[82:85], v[62:65], v[78:81], v[82:85]
	v_mfma_f32_16x16x32_bf16 v[54:57], v[70:73], v[78:81], v[54:57]
	v_mfma_f32_16x16x32_bf16 v[46:49], v[62:65], v[90:93], v[46:49]
	v_mfma_f32_16x16x32_bf16 v[38:41], v[70:73], v[90:93], v[38:41]
	v_mfma_f32_16x16x32_bf16 v[30:33], v[62:65], v[176:179], v[30:33]
	v_mfma_f32_16x16x32_bf16 v[22:25], v[70:73], v[176:179], v[22:25]
	v_mfma_f32_16x16x32_bf16 v[14:17], v[62:65], v[184:187], v[14:17]
	v_mfma_f32_16x16x32_bf16 v[6:9], v[70:73], v[184:187], v[6:9]
	v_mfma_f32_16x16x32_bf16 v[82:85], v[66:69], v[86:89], v[82:85]
	v_mfma_f32_16x16x32_bf16 v[54:57], v[74:77], v[86:89], v[54:57]
	v_mfma_f32_16x16x32_bf16 v[46:49], v[66:69], v[94:97], v[46:49]
	v_mfma_f32_16x16x32_bf16 v[38:41], v[74:77], v[94:97], v[38:41]
	v_mfma_f32_16x16x32_bf16 v[30:33], v[66:69], v[180:183], v[30:33]
	v_mfma_f32_16x16x32_bf16 v[22:25], v[74:77], v[180:183], v[22:25]
	v_mfma_f32_16x16x32_bf16 v[14:17], v[66:69], v[188:191], v[14:17]
	v_mfma_f32_16x16x32_bf16 v[6:9], v[74:77], v[188:191], v[6:9]
	s_setprio 0
	s_barrier
	s_add_u32 s36, s64, 0x40080
	s_addc_u32 s37, s65, 0
	s_add_i32 s64, s66, s68
	v_lshl_add_u64 v[62:63], s[36:37], 0, v[164:165]
	s_mov_b32 m0, s64
	s_nop 0
	global_load_lds_dwordx4 v[62:63], off
	v_lshl_add_u64 v[62:63], s[36:37], 0, v[162:163]
	s_add_i32 m0, s64, 0x2000
	s_nop 0
	global_load_lds_dwordx4 v[62:63], off
	s_waitcnt vmcnt(10)
	s_barrier
	s_setprio 1
	v_mfma_f32_16x16x32_bf16 v[58:61], v[208:211], v[78:81], v[58:61]
	v_mfma_f32_16x16x32_bf16 v[50:53], v[226:229], v[78:81], v[50:53]
	v_mfma_f32_16x16x32_bf16 v[42:45], v[208:211], v[90:93], v[42:45]
	v_mfma_f32_16x16x32_bf16 v[34:37], v[226:229], v[90:93], v[34:37]
	v_mfma_f32_16x16x32_bf16 v[26:29], v[208:211], v[176:179], v[26:29]
	v_mfma_f32_16x16x32_bf16 v[18:21], v[226:229], v[176:179], v[18:21]
	v_mfma_f32_16x16x32_bf16 v[10:13], v[208:211], v[184:187], v[10:13]
	v_mfma_f32_16x16x32_bf16 v[2:5], v[226:229], v[184:187], v[2:5]
	v_mfma_f32_16x16x32_bf16 v[74:77], v[222:225], v[86:89], v[58:61]
	v_mfma_f32_16x16x32_bf16 v[50:53], v[230:233], v[86:89], v[50:53]
	v_mfma_f32_16x16x32_bf16 v[42:45], v[222:225], v[94:97], v[42:45]
	v_mfma_f32_16x16x32_bf16 v[34:37], v[230:233], v[94:97], v[34:37]
	v_mfma_f32_16x16x32_bf16 v[26:29], v[222:225], v[180:183], v[26:29]
	v_mfma_f32_16x16x32_bf16 v[18:21], v[230:233], v[180:183], v[18:21]
	v_mfma_f32_16x16x32_bf16 v[10:13], v[222:225], v[188:191], v[10:13]
	v_mfma_f32_16x16x32_bf16 v[2:5], v[230:233], v[188:191], v[2:5]
	s_setprio 0
	s_add_i32 s83, s83, 2
	s_add_u32 s81, s81, 0x100
	s_addc_u32 s82, s82, 0
	s_cmp_gt_u32 s83, 13
	s_mov_b64 s[36:37], s[62:63]
	s_barrier
	s_cbranch_scc0 .LBB0_1099
	v_lshl_or_b32 v58, s27, 8, v174
	v_mov_b32_e32 v177, v1
	v_ashrrev_i32_e32 v59, 31, v58
	v_lshlrev_b64 v[58:59], 2, v[58:59]
	v_lshl_add_u64 v[66:67], s[46:47], 0, v[58:59]
	v_lshl_add_u64 v[70:71], s[48:49], 0, v[58:59]
	flat_load_dwordx4 v[86:89], v[66:67]
	flat_load_dwordx4 v[78:81], v[70:71]
	flat_load_dwordx4 v[62:65], v[66:67] offset:16
	flat_load_dwordx4 v[58:61], v[70:71] offset:16
	flat_load_dwordx4 v[94:97], v[66:67] offset:512
	flat_load_dwordx4 v[90:93], v[70:71] offset:512
	s_nop 0
	flat_load_dwordx4 v[66:69], v[66:67] offset:528
	s_nop 0
	flat_load_dwordx4 v[70:73], v[70:71] offset:528
	s_lshl_b32 s3, s3, 8
	v_lshl_or_b32 v176, s27, 7, v174
	v_add_u32_e32 v184, s3, v177
	v_lshl_add_u32 v177, v177, 3, s33
	s_waitcnt vmcnt(0)
	ds_read_b64 v[178:179], v177
	s_movk_i32 s27, 0xb00
	s_and_b64 vcc, exec, s[60:61]
	s_waitcnt lgkmcnt(0)
	v_xor_b32_e32 v89, 0x80000000, v89
	v_xor_b32_e32 v88, 0x80000000, v88
	v_pk_fma_f32 v[160:161], v[88:89], v[178:179], v[160:161] op_sel_hi:[1,0,1]
	v_pk_fma_f32 v[158:159], v[86:87], v[178:179], v[158:159] op_sel_hi:[1,0,1] neg_lo:[1,0,0] neg_hi:[1,0,0]
	v_pk_fma_f32 v[160:161], v[178:179], v[160:161], v[80:81] op_sel:[1,0,0]
	v_pk_fma_f32 v[158:159], v[178:179], v[158:159], v[78:79] op_sel:[1,0,0]
	v_pk_fma_f32 v[154:155], v[94:95], v[178:179], v[154:155] op_sel_hi:[1,0,1] neg_lo:[1,0,0] neg_hi:[1,0,0]
	v_mul_f32_e32 v182, 0xbfb8aa3b, v160
	v_pk_fma_f32 v[180:181], v[178:179], v[154:155], v[90:91] op_sel:[1,0,0]
	v_mul_f32_e32 v154, 0xbfb8aa3b, v158
	v_mul_f32_e32 v155, 0xbfb8aa3b, v159
	v_mul_f32_e32 v183, 0xbfb8aa3b, v161
	v_exp_f32_e32 v154, v154
	v_exp_f32_e32 v155, v155
	v_exp_f32_e32 v182, v182
	v_exp_f32_e32 v183, v183
	v_add_f32_e32 v154, 1.0, v154
	v_add_f32_e32 v155, 1.0, v155
	v_add_f32_e32 v182, 1.0, v182
	v_add_f32_e32 v183, 1.0, v183
	v_rcp_f32_e32 v154, v154
	v_rcp_f32_e32 v155, v155
	v_rcp_f32_e32 v182, v182
	v_rcp_f32_e32 v183, v183
	v_xor_b32_e32 v97, 0x80000000, v97
	v_xor_b32_e32 v96, 0x80000000, v96
	v_xor_b32_e32 v65, 0x80000000, v65
	v_xor_b32_e32 v64, 0x80000000, v64
	v_pk_fma_f32 v[156:157], v[96:97], v[178:179], v[156:157] op_sel_hi:[1,0,1]
	v_pk_fma_f32 v[152:153], v[64:65], v[178:179], v[152:153] op_sel_hi:[1,0,1]
	v_pk_fma_f32 v[150:151], v[62:63], v[178:179], v[150:151] op_sel_hi:[1,0,1] neg_lo:[1,0,0] neg_hi:[1,0,0]
	v_pk_fma_f32 v[156:157], v[178:179], v[156:157], v[92:93] op_sel:[1,0,0]
	v_pk_mul_f32 v[160:161], v[160:161], v[182:183]
	v_pk_mul_f32 v[158:159], v[158:159], v[154:155]
	v_pk_fma_f32 v[152:153], v[178:179], v[152:153], v[60:61] op_sel:[1,0,0]
	v_pk_fma_f32 v[150:151], v[178:179], v[150:151], v[58:59] op_sel:[1,0,0]
	v_pk_mul_f32 v[154:155], v[156:157], v[160:161]
	v_pk_mul_f32 v[156:157], v[180:181], v[158:159]
	v_mul_f32_e32 v158, 0xbfb8aa3b, v150
	v_mul_f32_e32 v159, 0xbfb8aa3b, v151
	v_mul_f32_e32 v160, 0xbfb8aa3b, v152
	v_mul_f32_e32 v161, 0xbfb8aa3b, v153
	v_exp_f32_e32 v158, v158
	v_exp_f32_e32 v159, v159
	v_exp_f32_e32 v160, v160
	v_exp_f32_e32 v161, v161
	v_add_f32_e32 v158, 1.0, v158
	v_add_f32_e32 v159, 1.0, v159
	v_add_f32_e32 v160, 1.0, v160
	v_add_f32_e32 v161, 1.0, v161
	v_rcp_f32_e32 v158, v158
	v_rcp_f32_e32 v159, v159
	v_rcp_f32_e32 v160, v160
	v_rcp_f32_e32 v161, v161
	v_xor_b32_e32 v69, 0x80000000, v69
	v_xor_b32_e32 v68, 0x80000000, v68
	v_pk_fma_f32 v[148:149], v[68:69], v[178:179], v[148:149] op_sel_hi:[1,0,1]
	v_pk_fma_f32 v[146:147], v[66:67], v[178:179], v[146:147] op_sel_hi:[1,0,1] neg_lo:[1,0,0] neg_hi:[1,0,0]
	v_pk_fma_f32 v[148:149], v[178:179], v[148:149], v[72:73] op_sel:[1,0,0]
	v_pk_fma_f32 v[146:147], v[178:179], v[146:147], v[70:71] op_sel:[1,0,0]
	v_pk_mul_f32 v[152:153], v[152:153], v[160:161]
	v_pk_mul_f32 v[150:151], v[150:151], v[158:159]
	v_mul_lo_u32 v158, v184, s27
	v_pk_mul_f32 v[152:153], v[148:149], v[152:153]
	v_pk_mul_f32 v[148:149], v[146:147], v[150:151]
	v_add_lshl_u32 v150, v158, v176, 1
	v_cvt_pk_bf16_f32 v146, v156, v157
	v_cvt_pk_bf16_f32 v147, v154, v155
	v_cvt_pk_bf16_f32 v148, v148, v149
	v_cvt_pk_bf16_f32 v149, v152, v153
	buffer_store_dwordx4 v[146:149], v150, s[28:31], 0 offen sc1
	ds_read_b64 v[146:147], v177 offset:128
	s_waitcnt lgkmcnt(0)
	v_pk_fma_f32 v[142:143], v[86:87], v[146:147], v[142:143] op_sel_hi:[1,0,1] neg_lo:[1,0,0] neg_hi:[1,0,0]
	s_nop 0
	v_pk_fma_f32 v[142:143], v[146:147], v[142:143], v[78:79] op_sel:[1,0,0]
	v_pk_fma_f32 v[144:145], v[88:89], v[146:147], v[144:145] op_sel_hi:[1,0,1]
	v_mul_f32_e32 v148, 0xbfb8aa3b, v142
	v_mul_f32_e32 v149, 0xbfb8aa3b, v143
	v_pk_fma_f32 v[144:145], v[146:147], v[144:145], v[80:81] op_sel:[1,0,0]
	v_exp_f32_e32 v148, v148
	v_exp_f32_e32 v149, v149
	v_mul_f32_e32 v150, 0xbfb8aa3b, v144
	v_mul_f32_e32 v151, 0xbfb8aa3b, v145
	v_exp_f32_e32 v150, v150
	v_exp_f32_e32 v151, v151
	v_add_f32_e32 v148, 1.0, v148
	v_add_f32_e32 v149, 1.0, v149
	v_rcp_f32_e32 v148, v148
	v_rcp_f32_e32 v149, v149
	v_add_f32_e32 v150, 1.0, v150
	v_add_f32_e32 v151, 1.0, v151
	v_rcp_f32_e32 v150, v150
	v_rcp_f32_e32 v151, v151
	v_pk_fma_f32 v[138:139], v[94:95], v[146:147], v[138:139] op_sel_hi:[1,0,1] neg_lo:[1,0,0] neg_hi:[1,0,0]
	v_pk_fma_f32 v[134:135], v[62:63], v[146:147], v[134:135] op_sel_hi:[1,0,1] neg_lo:[1,0,0] neg_hi:[1,0,0]
	v_pk_fma_f32 v[138:139], v[146:147], v[138:139], v[90:91] op_sel:[1,0,0]
	v_pk_mul_f32 v[142:143], v[142:143], v[148:149]
	v_pk_fma_f32 v[134:135], v[146:147], v[134:135], v[58:59] op_sel:[1,0,0]
	v_pk_fma_f32 v[140:141], v[96:97], v[146:147], v[140:141] op_sel_hi:[1,0,1]
	v_pk_mul_f32 v[138:139], v[138:139], v[142:143]
	v_pk_fma_f32 v[136:137], v[64:65], v[146:147], v[136:137] op_sel_hi:[1,0,1]
	v_mul_f32_e32 v142, 0xbfb8aa3b, v134
	v_mul_f32_e32 v143, 0xbfb8aa3b, v135
	v_pk_fma_f32 v[140:141], v[146:147], v[140:141], v[92:93] op_sel:[1,0,0]
	v_pk_mul_f32 v[144:145], v[144:145], v[150:151]
	v_pk_fma_f32 v[136:137], v[146:147], v[136:137], v[60:61] op_sel:[1,0,0]
	v_exp_f32_e32 v142, v142
	v_exp_f32_e32 v143, v143
	v_pk_mul_f32 v[140:141], v[140:141], v[144:145]
	v_mul_f32_e32 v144, 0xbfb8aa3b, v136
	v_mul_f32_e32 v145, 0xbfb8aa3b, v137
	v_exp_f32_e32 v144, v144
	v_exp_f32_e32 v145, v145
	v_add_f32_e32 v142, 1.0, v142
	v_add_f32_e32 v143, 1.0, v143
	v_rcp_f32_e32 v142, v142
	v_rcp_f32_e32 v143, v143
	v_add_f32_e32 v144, 1.0, v144
	v_add_f32_e32 v145, 1.0, v145
	v_rcp_f32_e32 v144, v144
	v_rcp_f32_e32 v145, v145
	v_pk_fma_f32 v[130:131], v[66:67], v[146:147], v[130:131] op_sel_hi:[1,0,1] neg_lo:[1,0,0] neg_hi:[1,0,0]
	v_pk_mul_f32 v[134:135], v[134:135], v[142:143]
	v_pk_fma_f32 v[130:131], v[146:147], v[130:131], v[70:71] op_sel:[1,0,0]
	v_pk_fma_f32 v[132:133], v[68:69], v[146:147], v[132:133] op_sel_hi:[1,0,1]
	v_pk_mul_f32 v[134:135], v[130:131], v[134:135]
	v_add_u32_e32 v130, 0xb000, v176
	v_pk_fma_f32 v[132:133], v[146:147], v[132:133], v[72:73] op_sel:[1,0,0]
	v_pk_mul_f32 v[136:137], v[136:137], v[144:145]
	v_add_lshl_u32 v131, v158, v130, 1
	v_pk_mul_f32 v[136:137], v[132:133], v[136:137]
	v_cvt_pk_bf16_f32 v132, v138, v139
	v_cvt_pk_bf16_f32 v133, v140, v141
	v_cvt_pk_bf16_f32 v134, v134, v135
	s_nop 0
	v_cvt_pk_bf16_f32 v135, v136, v137
	buffer_store_dwordx4 v[132:135], v131, s[28:31], 0 offen sc1
	v_mov_b32_e32 v131, v171
	s_nop 0
	v_add_u32_e32 v138, s3, v131
	v_lshl_add_u32 v131, v131, 3, s33
	ds_read_b64 v[132:133], v131
	s_waitcnt lgkmcnt(0)
	v_pk_fma_f32 v[128:129], v[88:89], v[132:133], v[128:129] op_sel_hi:[1,0,1]
	v_pk_fma_f32 v[126:127], v[86:87], v[132:133], v[126:127] op_sel_hi:[1,0,1] neg_lo:[1,0,0] neg_hi:[1,0,0]
	v_pk_fma_f32 v[128:129], v[132:133], v[128:129], v[80:81] op_sel:[1,0,0]
	v_pk_fma_f32 v[126:127], v[132:133], v[126:127], v[78:79] op_sel:[1,0,0]
	v_mul_f32_e32 v136, 0xbfb8aa3b, v128
	v_mul_f32_e32 v134, 0xbfb8aa3b, v126
	v_mul_f32_e32 v135, 0xbfb8aa3b, v127
	v_mul_f32_e32 v137, 0xbfb8aa3b, v129
	v_exp_f32_e32 v134, v134
	v_exp_f32_e32 v135, v135
	v_exp_f32_e32 v136, v136
	v_exp_f32_e32 v137, v137
	v_add_f32_e32 v134, 1.0, v134
	v_add_f32_e32 v135, 1.0, v135
	v_add_f32_e32 v136, 1.0, v136
	v_add_f32_e32 v137, 1.0, v137
	v_rcp_f32_e32 v134, v134
	v_rcp_f32_e32 v135, v135
	v_rcp_f32_e32 v136, v136
	v_rcp_f32_e32 v137, v137
	v_pk_fma_f32 v[124:125], v[96:97], v[132:133], v[124:125] op_sel_hi:[1,0,1]
	v_pk_fma_f32 v[122:123], v[94:95], v[132:133], v[122:123] op_sel_hi:[1,0,1] neg_lo:[1,0,0] neg_hi:[1,0,0]
	v_pk_fma_f32 v[120:121], v[64:65], v[132:133], v[120:121] op_sel_hi:[1,0,1]
	v_pk_fma_f32 v[118:119], v[62:63], v[132:133], v[118:119] op_sel_hi:[1,0,1] neg_lo:[1,0,0] neg_hi:[1,0,0]
	v_pk_fma_f32 v[124:125], v[132:133], v[124:125], v[92:93] op_sel:[1,0,0]
	v_pk_fma_f32 v[122:123], v[132:133], v[122:123], v[90:91] op_sel:[1,0,0]
	v_pk_mul_f32 v[128:129], v[128:129], v[136:137]
	v_pk_mul_f32 v[126:127], v[126:127], v[134:135]
	v_pk_fma_f32 v[120:121], v[132:133], v[120:121], v[60:61] op_sel:[1,0,0]
	v_pk_fma_f32 v[118:119], v[132:133], v[118:119], v[58:59] op_sel:[1,0,0]
	v_pk_mul_f32 v[124:125], v[124:125], v[128:129]
	v_pk_mul_f32 v[122:123], v[122:123], v[126:127]
	v_mul_f32_e32 v126, 0xbfb8aa3b, v118
	v_mul_f32_e32 v127, 0xbfb8aa3b, v119
	v_mul_f32_e32 v128, 0xbfb8aa3b, v120
	v_mul_f32_e32 v129, 0xbfb8aa3b, v121
	v_exp_f32_e32 v126, v126
	v_exp_f32_e32 v127, v127
	v_exp_f32_e32 v128, v128
	v_exp_f32_e32 v129, v129
	v_add_f32_e32 v126, 1.0, v126
	v_add_f32_e32 v127, 1.0, v127
	v_add_f32_e32 v128, 1.0, v128
	v_add_f32_e32 v129, 1.0, v129
	v_rcp_f32_e32 v126, v126
	v_rcp_f32_e32 v127, v127
	v_rcp_f32_e32 v128, v128
	v_rcp_f32_e32 v129, v129
	v_pk_fma_f32 v[116:117], v[68:69], v[132:133], v[116:117] op_sel_hi:[1,0,1]
	v_pk_fma_f32 v[114:115], v[66:67], v[132:133], v[114:115] op_sel_hi:[1,0,1] neg_lo:[1,0,0] neg_hi:[1,0,0]
	v_pk_fma_f32 v[116:117], v[132:133], v[116:117], v[72:73] op_sel:[1,0,0]
	v_pk_fma_f32 v[114:115], v[132:133], v[114:115], v[70:71] op_sel:[1,0,0]
	v_pk_mul_f32 v[120:121], v[120:121], v[128:129]
	v_pk_mul_f32 v[118:119], v[118:119], v[126:127]
	v_mul_lo_u32 v126, v138, s27
	v_pk_mul_f32 v[120:121], v[116:117], v[120:121]
	v_pk_mul_f32 v[116:117], v[114:115], v[118:119]
	v_add_lshl_u32 v118, v126, v176, 1
	v_cvt_pk_bf16_f32 v114, v122, v123
	v_cvt_pk_bf16_f32 v115, v124, v125
	v_cvt_pk_bf16_f32 v116, v116, v117
	v_cvt_pk_bf16_f32 v117, v120, v121
	buffer_store_dwordx4 v[114:117], v118, s[28:31], 0 offen sc1
	ds_read_b64 v[114:115], v131 offset:128
	s_waitcnt lgkmcnt(0)
	v_pk_fma_f32 v[112:113], v[88:89], v[114:115], v[112:113] op_sel_hi:[1,0,1]
	v_pk_fma_f32 v[110:111], v[86:87], v[114:115], v[110:111] op_sel_hi:[1,0,1] neg_lo:[1,0,0] neg_hi:[1,0,0]
	v_pk_fma_f32 v[112:113], v[114:115], v[112:113], v[80:81] op_sel:[1,0,0]
	v_pk_fma_f32 v[110:111], v[114:115], v[110:111], v[78:79] op_sel:[1,0,0]
	v_mul_f32_e32 v118, 0xbfb8aa3b, v112
	v_mul_f32_e32 v116, 0xbfb8aa3b, v110
	v_mul_f32_e32 v117, 0xbfb8aa3b, v111
	v_mul_f32_e32 v119, 0xbfb8aa3b, v113
	v_exp_f32_e32 v116, v116
	v_exp_f32_e32 v117, v117
	v_exp_f32_e32 v118, v118
	v_exp_f32_e32 v119, v119
	v_add_f32_e32 v116, 1.0, v116
	v_add_f32_e32 v117, 1.0, v117
	v_add_f32_e32 v118, 1.0, v118
	v_add_f32_e32 v119, 1.0, v119
	v_rcp_f32_e32 v116, v116
	v_rcp_f32_e32 v117, v117
	v_rcp_f32_e32 v118, v118
	v_rcp_f32_e32 v119, v119
	v_pk_fma_f32 v[108:109], v[96:97], v[114:115], v[108:109] op_sel_hi:[1,0,1]
	v_pk_fma_f32 v[106:107], v[94:95], v[114:115], v[106:107] op_sel_hi:[1,0,1] neg_lo:[1,0,0] neg_hi:[1,0,0]
	v_pk_fma_f32 v[104:105], v[64:65], v[114:115], v[104:105] op_sel_hi:[1,0,1]
	v_pk_fma_f32 v[102:103], v[62:63], v[114:115], v[102:103] op_sel_hi:[1,0,1] neg_lo:[1,0,0] neg_hi:[1,0,0]
	v_pk_fma_f32 v[108:109], v[114:115], v[108:109], v[92:93] op_sel:[1,0,0]
	v_pk_fma_f32 v[106:107], v[114:115], v[106:107], v[90:91] op_sel:[1,0,0]
	v_pk_mul_f32 v[112:113], v[112:113], v[118:119]
	v_pk_mul_f32 v[110:111], v[110:111], v[116:117]
	v_pk_fma_f32 v[104:105], v[114:115], v[104:105], v[60:61] op_sel:[1,0,0]
	v_pk_fma_f32 v[102:103], v[114:115], v[102:103], v[58:59] op_sel:[1,0,0]
	v_pk_mul_f32 v[108:109], v[108:109], v[112:113]
	v_pk_mul_f32 v[106:107], v[106:107], v[110:111]
	v_mul_f32_e32 v110, 0xbfb8aa3b, v102
	v_mul_f32_e32 v111, 0xbfb8aa3b, v103
	v_mul_f32_e32 v112, 0xbfb8aa3b, v104
	v_mul_f32_e32 v113, 0xbfb8aa3b, v105
	v_exp_f32_e32 v110, v110
	v_exp_f32_e32 v111, v111
	v_exp_f32_e32 v112, v112
	v_exp_f32_e32 v113, v113
	v_add_f32_e32 v110, 1.0, v110
	v_add_f32_e32 v111, 1.0, v111
	v_add_f32_e32 v112, 1.0, v112
	v_add_f32_e32 v113, 1.0, v113
	v_rcp_f32_e32 v110, v110
	v_rcp_f32_e32 v111, v111
	v_rcp_f32_e32 v112, v112
	v_rcp_f32_e32 v113, v113
	v_pk_fma_f32 v[100:101], v[68:69], v[114:115], v[100:101] op_sel_hi:[1,0,1]
	v_pk_fma_f32 v[98:99], v[66:67], v[114:115], v[98:99] op_sel_hi:[1,0,1] neg_lo:[1,0,0] neg_hi:[1,0,0]
	v_pk_fma_f32 v[100:101], v[114:115], v[100:101], v[72:73] op_sel:[1,0,0]
	v_pk_fma_f32 v[98:99], v[114:115], v[98:99], v[70:71] op_sel:[1,0,0]
	v_pk_mul_f32 v[104:105], v[104:105], v[112:113]
	v_pk_mul_f32 v[102:103], v[102:103], v[110:111]
	v_pk_mul_f32 v[104:105], v[100:101], v[104:105]
	v_pk_mul_f32 v[100:101], v[98:99], v[102:103]
	v_add_lshl_u32 v102, v126, v130, 1
	v_cvt_pk_bf16_f32 v98, v106, v107
	v_cvt_pk_bf16_f32 v99, v108, v109
	v_cvt_pk_bf16_f32 v100, v100, v101
	v_cvt_pk_bf16_f32 v101, v104, v105
	buffer_store_dwordx4 v[98:101], v102, s[28:31], 0 offen sc1
	s_nop 1
	v_mov_b32_e32 v98, v172
	s_nop 0
	v_lshl_add_u32 v105, v98, 3, s33
	v_add_u32_e32 v104, s3, v98
	ds_read_b64 v[98:99], v105
	s_waitcnt lgkmcnt(0)
	v_pk_fma_f32 v[84:85], v[88:89], v[98:99], v[84:85] op_sel_hi:[1,0,1]
	v_pk_fma_f32 v[82:83], v[86:87], v[98:99], v[82:83] op_sel_hi:[1,0,1] neg_lo:[1,0,0] neg_hi:[1,0,0]
	v_pk_fma_f32 v[84:85], v[98:99], v[84:85], v[80:81] op_sel:[1,0,0]
	v_pk_fma_f32 v[82:83], v[98:99], v[82:83], v[78:79] op_sel:[1,0,0]
	v_mul_f32_e32 v102, 0xbfb8aa3b, v84
	v_mul_f32_e32 v100, 0xbfb8aa3b, v82
	v_mul_f32_e32 v101, 0xbfb8aa3b, v83
	v_mul_f32_e32 v103, 0xbfb8aa3b, v85
	v_exp_f32_e32 v100, v100
	v_exp_f32_e32 v101, v101
	v_exp_f32_e32 v102, v102
	v_exp_f32_e32 v103, v103
	v_add_f32_e32 v100, 1.0, v100
	v_add_f32_e32 v101, 1.0, v101
	v_add_f32_e32 v102, 1.0, v102
	v_add_f32_e32 v103, 1.0, v103
	v_rcp_f32_e32 v100, v100
	v_rcp_f32_e32 v101, v101
	v_rcp_f32_e32 v102, v102
	v_rcp_f32_e32 v103, v103
	v_pk_fma_f32 v[76:77], v[96:97], v[98:99], v[76:77] op_sel_hi:[1,0,1]
	v_pk_fma_f32 v[74:75], v[94:95], v[98:99], v[74:75] op_sel_hi:[1,0,1] neg_lo:[1,0,0] neg_hi:[1,0,0]
	v_pk_fma_f32 v[56:57], v[64:65], v[98:99], v[56:57] op_sel_hi:[1,0,1]
	v_pk_fma_f32 v[54:55], v[62:63], v[98:99], v[54:55] op_sel_hi:[1,0,1] neg_lo:[1,0,0] neg_hi:[1,0,0]
	v_pk_fma_f32 v[76:77], v[98:99], v[76:77], v[92:93] op_sel:[1,0,0]
	v_pk_fma_f32 v[74:75], v[98:99], v[74:75], v[90:91] op_sel:[1,0,0]
	v_pk_mul_f32 v[84:85], v[84:85], v[102:103]
	v_pk_mul_f32 v[82:83], v[82:83], v[100:101]
	v_pk_fma_f32 v[56:57], v[98:99], v[56:57], v[60:61] op_sel:[1,0,0]
	v_pk_fma_f32 v[54:55], v[98:99], v[54:55], v[58:59] op_sel:[1,0,0]
	v_pk_mul_f32 v[76:77], v[76:77], v[84:85]
	v_pk_mul_f32 v[74:75], v[74:75], v[82:83]
	v_mul_f32_e32 v82, 0xbfb8aa3b, v54
	v_mul_f32_e32 v83, 0xbfb8aa3b, v55
	v_mul_f32_e32 v84, 0xbfb8aa3b, v56
	v_mul_f32_e32 v85, 0xbfb8aa3b, v57
	v_exp_f32_e32 v82, v82
	v_exp_f32_e32 v83, v83
	v_exp_f32_e32 v84, v84
	v_exp_f32_e32 v85, v85
	v_add_f32_e32 v82, 1.0, v82
	v_add_f32_e32 v83, 1.0, v83
	v_add_f32_e32 v84, 1.0, v84
	v_add_f32_e32 v85, 1.0, v85
	v_rcp_f32_e32 v82, v82
	v_rcp_f32_e32 v83, v83
	v_rcp_f32_e32 v84, v84
	v_rcp_f32_e32 v85, v85
	v_pk_fma_f32 v[52:53], v[68:69], v[98:99], v[52:53] op_sel_hi:[1,0,1]
	v_pk_fma_f32 v[50:51], v[66:67], v[98:99], v[50:51] op_sel_hi:[1,0,1] neg_lo:[1,0,0] neg_hi:[1,0,0]
	v_pk_fma_f32 v[52:53], v[98:99], v[52:53], v[72:73] op_sel:[1,0,0]
	v_pk_fma_f32 v[50:51], v[98:99], v[50:51], v[70:71] op_sel:[1,0,0]
	v_pk_mul_f32 v[56:57], v[56:57], v[84:85]
	v_pk_mul_f32 v[54:55], v[54:55], v[82:83]
	v_mul_lo_u32 v82, v104, s27
	v_pk_mul_f32 v[56:57], v[52:53], v[56:57]
	v_pk_mul_f32 v[52:53], v[50:51], v[54:55]
	v_add_lshl_u32 v54, v82, v176, 1
	v_cvt_pk_bf16_f32 v50, v74, v75
	v_cvt_pk_bf16_f32 v51, v76, v77
	v_cvt_pk_bf16_f32 v52, v52, v53
	v_cvt_pk_bf16_f32 v53, v56, v57
	buffer_store_dwordx4 v[50:53], v54, s[28:31], 0 offen sc1
	ds_read_b64 v[50:51], v105 offset:128
	s_waitcnt lgkmcnt(0)
	v_pk_fma_f32 v[48:49], v[88:89], v[50:51], v[48:49] op_sel_hi:[1,0,1]
	v_pk_fma_f32 v[46:47], v[86:87], v[50:51], v[46:47] op_sel_hi:[1,0,1] neg_lo:[1,0,0] neg_hi:[1,0,0]
	v_pk_fma_f32 v[48:49], v[50:51], v[48:49], v[80:81] op_sel:[1,0,0]
	v_pk_fma_f32 v[46:47], v[50:51], v[46:47], v[78:79] op_sel:[1,0,0]
	v_mul_f32_e32 v54, 0xbfb8aa3b, v48
	v_mul_f32_e32 v52, 0xbfb8aa3b, v46
	v_mul_f32_e32 v53, 0xbfb8aa3b, v47
	v_mul_f32_e32 v55, 0xbfb8aa3b, v49
	v_exp_f32_e32 v52, v52
	v_exp_f32_e32 v53, v53
	v_exp_f32_e32 v54, v54
	v_exp_f32_e32 v55, v55
	v_add_f32_e32 v52, 1.0, v52
	v_add_f32_e32 v53, 1.0, v53
	v_add_f32_e32 v54, 1.0, v54
	v_add_f32_e32 v55, 1.0, v55
	v_rcp_f32_e32 v52, v52
	v_rcp_f32_e32 v53, v53
	v_rcp_f32_e32 v54, v54
	v_rcp_f32_e32 v55, v55
	v_pk_fma_f32 v[44:45], v[96:97], v[50:51], v[44:45] op_sel_hi:[1,0,1]
	v_pk_fma_f32 v[42:43], v[94:95], v[50:51], v[42:43] op_sel_hi:[1,0,1] neg_lo:[1,0,0] neg_hi:[1,0,0]
	v_pk_fma_f32 v[40:41], v[64:65], v[50:51], v[40:41] op_sel_hi:[1,0,1]
	v_pk_fma_f32 v[38:39], v[62:63], v[50:51], v[38:39] op_sel_hi:[1,0,1] neg_lo:[1,0,0] neg_hi:[1,0,0]
	v_pk_fma_f32 v[44:45], v[50:51], v[44:45], v[92:93] op_sel:[1,0,0]
	v_pk_fma_f32 v[42:43], v[50:51], v[42:43], v[90:91] op_sel:[1,0,0]
	v_pk_mul_f32 v[48:49], v[48:49], v[54:55]
	v_pk_mul_f32 v[46:47], v[46:47], v[52:53]
	v_pk_fma_f32 v[40:41], v[50:51], v[40:41], v[60:61] op_sel:[1,0,0]
	v_pk_fma_f32 v[38:39], v[50:51], v[38:39], v[58:59] op_sel:[1,0,0]
	v_pk_mul_f32 v[44:45], v[44:45], v[48:49]
	v_pk_mul_f32 v[42:43], v[42:43], v[46:47]
	v_mul_f32_e32 v46, 0xbfb8aa3b, v38
	v_mul_f32_e32 v47, 0xbfb8aa3b, v39
	v_mul_f32_e32 v48, 0xbfb8aa3b, v40
	v_mul_f32_e32 v49, 0xbfb8aa3b, v41
	v_exp_f32_e32 v46, v46
	v_exp_f32_e32 v47, v47
	v_exp_f32_e32 v48, v48
	v_exp_f32_e32 v49, v49
	v_add_f32_e32 v46, 1.0, v46
	v_add_f32_e32 v47, 1.0, v47
	v_add_f32_e32 v48, 1.0, v48
	v_add_f32_e32 v49, 1.0, v49
	v_rcp_f32_e32 v46, v46
	v_rcp_f32_e32 v47, v47
	v_rcp_f32_e32 v48, v48
	v_rcp_f32_e32 v49, v49
	v_pk_fma_f32 v[36:37], v[68:69], v[50:51], v[36:37] op_sel_hi:[1,0,1]
	v_pk_fma_f32 v[34:35], v[66:67], v[50:51], v[34:35] op_sel_hi:[1,0,1] neg_lo:[1,0,0] neg_hi:[1,0,0]
	v_pk_fma_f32 v[36:37], v[50:51], v[36:37], v[72:73] op_sel:[1,0,0]
	v_pk_fma_f32 v[34:35], v[50:51], v[34:35], v[70:71] op_sel:[1,0,0]
	v_pk_mul_f32 v[40:41], v[40:41], v[48:49]
	v_pk_mul_f32 v[38:39], v[38:39], v[46:47]
	v_pk_mul_f32 v[40:41], v[36:37], v[40:41]
	v_pk_mul_f32 v[36:37], v[34:35], v[38:39]
	v_add_lshl_u32 v38, v82, v130, 1
	v_cvt_pk_bf16_f32 v34, v42, v43
	v_cvt_pk_bf16_f32 v35, v44, v45
	v_cvt_pk_bf16_f32 v36, v36, v37
	v_cvt_pk_bf16_f32 v37, v40, v41
	buffer_store_dwordx4 v[34:37], v38, s[28:31], 0 offen sc1
	s_nop 1
	v_mov_b32_e32 v34, v173
	s_nop 0
	v_lshl_add_u32 v41, v34, 3, s33
	v_add_u32_e32 v40, s3, v34
	ds_read_b64 v[34:35], v41
	s_mov_b32 s3, s77
	s_waitcnt lgkmcnt(0)
	v_pk_fma_f32 v[32:33], v[88:89], v[34:35], v[32:33] op_sel_hi:[1,0,1]
	v_pk_fma_f32 v[30:31], v[86:87], v[34:35], v[30:31] op_sel_hi:[1,0,1] neg_lo:[1,0,0] neg_hi:[1,0,0]
	v_pk_fma_f32 v[32:33], v[34:35], v[32:33], v[80:81] op_sel:[1,0,0]
	v_pk_fma_f32 v[30:31], v[34:35], v[30:31], v[78:79] op_sel:[1,0,0]
	v_mul_f32_e32 v38, 0xbfb8aa3b, v32
	v_mul_f32_e32 v36, 0xbfb8aa3b, v30
	v_mul_f32_e32 v37, 0xbfb8aa3b, v31
	v_mul_f32_e32 v39, 0xbfb8aa3b, v33
	v_exp_f32_e32 v36, v36
	v_exp_f32_e32 v37, v37
	v_exp_f32_e32 v38, v38
	v_exp_f32_e32 v39, v39
	v_add_f32_e32 v36, 1.0, v36
	v_add_f32_e32 v37, 1.0, v37
	v_add_f32_e32 v38, 1.0, v38
	v_add_f32_e32 v39, 1.0, v39
	v_rcp_f32_e32 v36, v36
	v_rcp_f32_e32 v37, v37
	v_rcp_f32_e32 v38, v38
	v_rcp_f32_e32 v39, v39
	v_pk_fma_f32 v[28:29], v[96:97], v[34:35], v[28:29] op_sel_hi:[1,0,1]
	v_pk_fma_f32 v[26:27], v[94:95], v[34:35], v[26:27] op_sel_hi:[1,0,1] neg_lo:[1,0,0] neg_hi:[1,0,0]
	v_pk_fma_f32 v[24:25], v[64:65], v[34:35], v[24:25] op_sel_hi:[1,0,1]
	v_pk_fma_f32 v[22:23], v[62:63], v[34:35], v[22:23] op_sel_hi:[1,0,1] neg_lo:[1,0,0] neg_hi:[1,0,0]
	v_pk_fma_f32 v[28:29], v[34:35], v[28:29], v[92:93] op_sel:[1,0,0]
	v_pk_fma_f32 v[26:27], v[34:35], v[26:27], v[90:91] op_sel:[1,0,0]
	v_pk_mul_f32 v[32:33], v[32:33], v[38:39]
	v_pk_mul_f32 v[30:31], v[30:31], v[36:37]
	v_pk_fma_f32 v[24:25], v[34:35], v[24:25], v[60:61] op_sel:[1,0,0]
	v_pk_fma_f32 v[22:23], v[34:35], v[22:23], v[58:59] op_sel:[1,0,0]
	v_pk_mul_f32 v[28:29], v[28:29], v[32:33]
	v_pk_mul_f32 v[26:27], v[26:27], v[30:31]
	v_mul_f32_e32 v30, 0xbfb8aa3b, v22
	v_mul_f32_e32 v31, 0xbfb8aa3b, v23
	v_mul_f32_e32 v32, 0xbfb8aa3b, v24
	v_mul_f32_e32 v33, 0xbfb8aa3b, v25
	v_exp_f32_e32 v30, v30
	v_exp_f32_e32 v31, v31
	v_exp_f32_e32 v32, v32
	v_exp_f32_e32 v33, v33
	v_add_f32_e32 v30, 1.0, v30
	v_add_f32_e32 v31, 1.0, v31
	v_add_f32_e32 v32, 1.0, v32
	v_add_f32_e32 v33, 1.0, v33
	v_rcp_f32_e32 v30, v30
	v_rcp_f32_e32 v31, v31
	v_rcp_f32_e32 v32, v32
	v_rcp_f32_e32 v33, v33
	v_pk_fma_f32 v[20:21], v[68:69], v[34:35], v[20:21] op_sel_hi:[1,0,1]
	v_pk_fma_f32 v[18:19], v[66:67], v[34:35], v[18:19] op_sel_hi:[1,0,1] neg_lo:[1,0,0] neg_hi:[1,0,0]
	v_pk_fma_f32 v[20:21], v[34:35], v[20:21], v[72:73] op_sel:[1,0,0]
	v_pk_fma_f32 v[18:19], v[34:35], v[18:19], v[70:71] op_sel:[1,0,0]
	v_pk_mul_f32 v[24:25], v[24:25], v[32:33]
	v_pk_mul_f32 v[22:23], v[22:23], v[30:31]
	v_mul_lo_u32 v30, v40, s27
	v_pk_mul_f32 v[24:25], v[20:21], v[24:25]
	v_pk_mul_f32 v[20:21], v[18:19], v[22:23]
	v_add_lshl_u32 v22, v30, v176, 1
	v_cvt_pk_bf16_f32 v18, v26, v27
	v_cvt_pk_bf16_f32 v19, v28, v29
	v_cvt_pk_bf16_f32 v20, v20, v21
	v_cvt_pk_bf16_f32 v21, v24, v25
	buffer_store_dwordx4 v[18:21], v22, s[28:31], 0 offen sc1
	ds_read_b64 v[18:19], v41 offset:128
	s_mov_b32 s27, s58
	s_waitcnt lgkmcnt(0)
	v_pk_fma_f32 v[16:17], v[88:89], v[18:19], v[16:17] op_sel_hi:[1,0,1]
	v_pk_fma_f32 v[14:15], v[86:87], v[18:19], v[14:15] op_sel_hi:[1,0,1] neg_lo:[1,0,0] neg_hi:[1,0,0]
	v_pk_fma_f32 v[16:17], v[18:19], v[16:17], v[80:81] op_sel:[1,0,0]
	v_pk_fma_f32 v[14:15], v[18:19], v[14:15], v[78:79] op_sel:[1,0,0]
	v_mul_f32_e32 v22, 0xbfb8aa3b, v16
	v_mul_f32_e32 v20, 0xbfb8aa3b, v14
	v_mul_f32_e32 v21, 0xbfb8aa3b, v15
	v_mul_f32_e32 v23, 0xbfb8aa3b, v17
	v_exp_f32_e32 v20, v20
	v_exp_f32_e32 v21, v21
	v_exp_f32_e32 v22, v22
	v_exp_f32_e32 v23, v23
	v_add_f32_e32 v20, 1.0, v20
	v_add_f32_e32 v21, 1.0, v21
	v_add_f32_e32 v22, 1.0, v22
	v_add_f32_e32 v23, 1.0, v23
	v_rcp_f32_e32 v20, v20
	v_rcp_f32_e32 v21, v21
	v_rcp_f32_e32 v22, v22
	v_rcp_f32_e32 v23, v23
	v_pk_fma_f32 v[12:13], v[96:97], v[18:19], v[12:13] op_sel_hi:[1,0,1]
	v_pk_fma_f32 v[10:11], v[94:95], v[18:19], v[10:11] op_sel_hi:[1,0,1] neg_lo:[1,0,0] neg_hi:[1,0,0]
	v_pk_fma_f32 v[8:9], v[64:65], v[18:19], v[8:9] op_sel_hi:[1,0,1]
	v_pk_fma_f32 v[6:7], v[62:63], v[18:19], v[6:7] op_sel_hi:[1,0,1] neg_lo:[1,0,0] neg_hi:[1,0,0]
	v_pk_fma_f32 v[12:13], v[18:19], v[12:13], v[92:93] op_sel:[1,0,0]
	v_pk_fma_f32 v[10:11], v[18:19], v[10:11], v[90:91] op_sel:[1,0,0]
	v_pk_mul_f32 v[16:17], v[16:17], v[22:23]
	v_pk_mul_f32 v[14:15], v[14:15], v[20:21]
	v_pk_fma_f32 v[8:9], v[18:19], v[8:9], v[60:61] op_sel:[1,0,0]
	v_pk_fma_f32 v[6:7], v[18:19], v[6:7], v[58:59] op_sel:[1,0,0]
	v_pk_mul_f32 v[12:13], v[12:13], v[16:17]
	v_pk_mul_f32 v[10:11], v[10:11], v[14:15]
	v_mul_f32_e32 v14, 0xbfb8aa3b, v6
	v_mul_f32_e32 v15, 0xbfb8aa3b, v7
	v_mul_f32_e32 v16, 0xbfb8aa3b, v8
	v_mul_f32_e32 v17, 0xbfb8aa3b, v9
	v_exp_f32_e32 v14, v14
	v_exp_f32_e32 v15, v15
	v_exp_f32_e32 v16, v16
	v_exp_f32_e32 v17, v17
	v_add_f32_e32 v14, 1.0, v14
	v_add_f32_e32 v15, 1.0, v15
	v_add_f32_e32 v16, 1.0, v16
	v_add_f32_e32 v17, 1.0, v17
	v_rcp_f32_e32 v14, v14
	v_rcp_f32_e32 v15, v15
	v_rcp_f32_e32 v16, v16
	v_rcp_f32_e32 v17, v17
	v_pk_fma_f32 v[4:5], v[68:69], v[18:19], v[4:5] op_sel_hi:[1,0,1]
	v_pk_fma_f32 v[2:3], v[66:67], v[18:19], v[2:3] op_sel_hi:[1,0,1] neg_lo:[1,0,0] neg_hi:[1,0,0]
	v_pk_fma_f32 v[4:5], v[18:19], v[4:5], v[72:73] op_sel:[1,0,0]
	v_pk_fma_f32 v[2:3], v[18:19], v[2:3], v[70:71] op_sel:[1,0,0]
	v_pk_mul_f32 v[8:9], v[8:9], v[16:17]
	v_pk_mul_f32 v[6:7], v[6:7], v[14:15]
	v_pk_mul_f32 v[8:9], v[4:5], v[8:9]
	v_pk_mul_f32 v[4:5], v[2:3], v[6:7]
	v_add_lshl_u32 v6, v30, v130, 1
	v_cvt_pk_bf16_f32 v2, v10, v11
	v_cvt_pk_bf16_f32 v3, v12, v13
	v_cvt_pk_bf16_f32 v4, v4, v5
	v_cvt_pk_bf16_f32 v5, v8, v9
	buffer_store_dwordx4 v[2:5], v6, s[28:31], 0 offen sc1
	s_cbranch_vccz .LBB0_1098
	s_waitcnt vmcnt(0)
	v_readlane_b32 s76, v255, 13
	s_cmpk_gt_u32 s38, 0xff
	v_readlane_b32 s77, v255, 14
	s_cbranch_scc1 .LBB0_1103
	s_barrier

.LBB0_1178:
	s_add_u32 s27, s36, 0x100
	s_addc_u32 s91, s37, 0
	s_add_u32 s36, s42, 0x80
	s_addc_u32 s37, s43, 0
	s_mov_b32 s42, 0
	s_waitcnt lgkmcnt(0)
	s_add_i32 s92, s42, 2
	s_add_u32 s72, s36, 0x80
	s_addc_u32 s43, s37, 0
	s_add_i32 s93, 0, 0x10000
	v_add_u32_e32 v1, s93, v223
	ds_read_b128 v[50:53], v1
	ds_read_b128 v[54:57], v1 offset:1024
	ds_read_b128 v[58:61], v1 offset:2048
	ds_read_b128 v[62:65], v1 offset:3072
	s_cmp_eq_u32 s88, s42
	s_cselect_b32 s42, s66, s72
	s_cselect_b32 s43, s67, s43
	s_cselect_b32 s73, s71, s91
	s_cselect_b32 s72, s70, s27
	v_lshl_add_u64 v[178:179], s[36:37], 0, v[206:207]
	s_add_i32 m0, s79, 0xc000
	ds_read_b128 v[66:69], v230
	ds_read_b128 v[70:73], v230 offset:1024
	ds_read_b128 v[74:77], v230 offset:2048
	ds_read_b128 v[78:81], v230 offset:3072
	ds_read_b128 v[146:149], v230 offset:4096
	ds_read_b128 v[154:157], v230 offset:5120
	ds_read_b128 v[170:173], v230 offset:6144
	ds_read_b128 v[174:177], v230 offset:7168
	global_load_lds_dwordx4 v[178:179], off
	v_lshl_add_u64 v[178:179], s[36:37], 0, v[204:205]
	s_add_i32 m0, s79, 0xe000
	s_nop 0
	global_load_lds_dwordx4 v[178:179], off
	s_waitcnt lgkmcnt(8)
	s_waitcnt vmcnt(10)
	s_barrier
	s_waitcnt lgkmcnt(0)
	s_setprio 1
	s_waitcnt lgkmcnt(0)
	v_mfma_f32_16x16x32_bf16 v[166:169], v[50:53], v[66:69], 0
	v_mfma_f32_16x16x32_bf16 v[162:165], v[58:61], v[66:69], 0
	v_mfma_f32_16x16x32_bf16 v[142:145], v[50:53], v[74:77], 0
	v_mfma_f32_16x16x32_bf16 v[138:141], v[58:61], v[74:77], 0
	v_mfma_f32_16x16x32_bf16 v[126:129], v[50:53], v[146:149], 0
	v_mfma_f32_16x16x32_bf16 v[122:125], v[58:61], v[146:149], 0
	v_mfma_f32_16x16x32_bf16 v[110:113], v[50:53], v[170:173], 0
	v_mfma_f32_16x16x32_bf16 v[106:109], v[58:61], v[170:173], 0
	v_mfma_f32_16x16x32_bf16 v[166:169], v[54:57], v[70:73], v[166:169]
	v_mfma_f32_16x16x32_bf16 v[162:165], v[62:65], v[70:73], v[162:165]
	v_mfma_f32_16x16x32_bf16 v[142:145], v[54:57], v[78:81], v[142:145]
	v_mfma_f32_16x16x32_bf16 v[138:141], v[62:65], v[78:81], v[138:141]
	v_mfma_f32_16x16x32_bf16 v[126:129], v[54:57], v[154:157], v[126:129]
	v_mfma_f32_16x16x32_bf16 v[122:125], v[62:65], v[154:157], v[122:125]
	v_mfma_f32_16x16x32_bf16 v[110:113], v[54:57], v[174:177], v[110:113]
	v_mfma_f32_16x16x32_bf16 v[106:109], v[62:65], v[174:177], v[106:109]
	s_setprio 0
	s_barrier
	s_add_i32 s94, 0, 0x14000
	s_add_i32 s93, s93, s78
	v_add_u32_e32 v1, s94, v223
	v_lshl_add_u64 v[214:215], s[72:73], 0, v[202:203]
	s_mov_b32 m0, s93
	ds_read_b128 v[178:181], v1
	ds_read_b128 v[182:185], v1 offset:1024
	ds_read_b128 v[186:189], v1 offset:2048
	ds_read_b128 v[190:193], v1 offset:3072
	global_load_lds_dwordx4 v[214:215], off
	v_lshl_add_u64 v[236:237], s[72:73], 0, v[200:201]
	s_add_i32 m0, s93, 0x2000
	s_nop 0
	global_load_lds_dwordx4 v[236:237], off
	s_waitcnt vmcnt(10)
	s_barrier
	s_waitcnt lgkmcnt(0)
	s_setprio 1
	s_waitcnt lgkmcnt(0)
	v_mfma_f32_16x16x32_bf16 v[158:161], v[178:181], v[66:69], 0
	v_mfma_f32_16x16x32_bf16 v[66:69], v[186:189], v[66:69], 0
	v_mfma_f32_16x16x32_bf16 v[158:161], v[182:185], v[70:73], v[158:161]
	v_mfma_f32_16x16x32_bf16 v[66:69], v[190:193], v[70:73], v[66:69]
	v_mfma_f32_16x16x32_bf16 v[70:73], v[178:181], v[74:77], 0
	v_mfma_f32_16x16x32_bf16 v[74:77], v[186:189], v[74:77], 0
	v_mfma_f32_16x16x32_bf16 v[114:117], v[186:189], v[146:149], 0
	v_mfma_f32_16x16x32_bf16 v[102:105], v[178:181], v[170:173], 0
	v_mfma_f32_16x16x32_bf16 v[98:101], v[186:189], v[170:173], 0
	v_mfma_f32_16x16x32_bf16 v[70:73], v[182:185], v[78:81], v[70:73]
	v_mfma_f32_16x16x32_bf16 v[74:77], v[190:193], v[78:81], v[74:77]
	v_mfma_f32_16x16x32_bf16 v[78:81], v[178:181], v[146:149], 0
	v_mfma_f32_16x16x32_bf16 v[114:117], v[190:193], v[154:157], v[114:117]
	v_mfma_f32_16x16x32_bf16 v[102:105], v[182:185], v[174:177], v[102:105]
	v_mfma_f32_16x16x32_bf16 v[98:101], v[190:193], v[174:177], v[98:101]
	v_mfma_f32_16x16x32_bf16 v[78:81], v[182:185], v[154:157], v[78:81]
	s_setprio 0
	s_mov_b32 m0, s79
	v_lshl_add_u64 v[238:239], s[42:43], 0, v[202:203]
	s_barrier
	ds_read_b128 v[118:121], v230 offset:16384
	ds_read_b128 v[130:133], v230 offset:17408
	ds_read_b128 v[134:137], v230 offset:18432
	ds_read_b128 v[146:149], v230 offset:19456
	ds_read_b128 v[150:153], v230 offset:20480
	ds_read_b128 v[154:157], v230 offset:21504
	ds_read_b128 v[170:173], v230 offset:22528
	ds_read_b128 v[174:177], v230 offset:23552
	global_load_lds_dwordx4 v[238:239], off
	v_lshl_add_u64 v[240:241], s[42:43], 0, v[200:201]
	s_mov_b32 m0, s80
	s_nop 0
	global_load_lds_dwordx4 v[240:241], off
	s_barrier
	s_waitcnt lgkmcnt(0)
	s_setprio 1
	s_waitcnt lgkmcnt(0)
	v_mfma_f32_16x16x32_bf16 v[94:97], v[50:53], v[118:121], 0
	v_mfma_f32_16x16x32_bf16 v[90:93], v[58:61], v[118:121], 0
	v_mfma_f32_16x16x32_bf16 v[46:49], v[50:53], v[134:137], 0
	v_mfma_f32_16x16x32_bf16 v[42:45], v[58:61], v[134:137], 0
	v_mfma_f32_16x16x32_bf16 v[30:33], v[50:53], v[150:153], 0
	v_mfma_f32_16x16x32_bf16 v[26:29], v[58:61], v[150:153], 0
	v_mfma_f32_16x16x32_bf16 v[14:17], v[50:53], v[170:173], 0
	v_mfma_f32_16x16x32_bf16 v[10:13], v[58:61], v[170:173], 0
	v_mfma_f32_16x16x32_bf16 v[94:97], v[54:57], v[130:133], v[94:97]
	v_mfma_f32_16x16x32_bf16 v[90:93], v[62:65], v[130:133], v[90:93]
	v_mfma_f32_16x16x32_bf16 v[46:49], v[54:57], v[146:149], v[46:49]
	v_mfma_f32_16x16x32_bf16 v[42:45], v[62:65], v[146:149], v[42:45]
	v_mfma_f32_16x16x32_bf16 v[30:33], v[54:57], v[154:157], v[30:33]
	v_mfma_f32_16x16x32_bf16 v[26:29], v[62:65], v[154:157], v[26:29]
	v_mfma_f32_16x16x32_bf16 v[14:17], v[54:57], v[174:177], v[14:17]
	v_mfma_f32_16x16x32_bf16 v[10:13], v[62:65], v[174:177], v[10:13]
	s_setprio 0
	s_barrier
	s_add_u32 s72, s72, s4
	s_addc_u32 s73, s73, 0
	s_add_i32 s93, s94, s78
	v_lshl_add_u64 v[242:243], s[72:73], 0, v[202:203]
	s_mov_b32 m0, s93
	v_lshl_add_u64 v[244:245], s[72:73], 0, v[200:201]
	global_load_lds_dwordx4 v[242:243], off
	s_add_i32 m0, s93, 0x2000
	s_nop 0
	global_load_lds_dwordx4 v[244:245], off
	s_waitcnt vmcnt(10)
	s_barrier
	s_setprio 1
	v_mfma_f32_16x16x32_bf16 v[38:41], v[178:181], v[134:137], 0
	v_mfma_f32_16x16x32_bf16 v[34:37], v[186:189], v[134:137], 0
	v_mfma_f32_16x16x32_bf16 v[22:25], v[178:181], v[150:153], 0
	v_mfma_f32_16x16x32_bf16 v[18:21], v[186:189], v[150:153], 0
	v_mfma_f32_16x16x32_bf16 v[6:9], v[178:181], v[170:173], 0
	v_mfma_f32_16x16x32_bf16 v[2:5], v[186:189], v[170:173], 0
	v_mfma_f32_16x16x32_bf16 v[50:53], v[178:181], v[118:121], 0
	v_mfma_f32_16x16x32_bf16 v[54:57], v[186:189], v[118:121], 0
	v_mfma_f32_16x16x32_bf16 v[38:41], v[182:185], v[146:149], v[38:41]
	v_mfma_f32_16x16x32_bf16 v[34:37], v[190:193], v[146:149], v[34:37]
	v_mfma_f32_16x16x32_bf16 v[22:25], v[182:185], v[154:157], v[22:25]
	v_mfma_f32_16x16x32_bf16 v[18:21], v[190:193], v[154:157], v[18:21]
	v_mfma_f32_16x16x32_bf16 v[6:9], v[182:185], v[174:177], v[6:9]
	v_mfma_f32_16x16x32_bf16 v[2:5], v[190:193], v[174:177], v[2:5]
	v_mfma_f32_16x16x32_bf16 v[50:53], v[182:185], v[130:133], v[50:53]
	v_mfma_f32_16x16x32_bf16 v[54:57], v[190:193], v[130:133], v[54:57]
	s_setprio 0
	s_add_i32 s72, 0, 0x18000
	v_add_u32_e32 v1, s72, v223
	s_barrier
	ds_read_b128 v[58:61], v1
	ds_read_b128 v[62:65], v1 offset:1024
	ds_read_b128 v[82:85], v1 offset:2048
	ds_read_b128 v[86:89], v1 offset:3072
	s_add_u32 s42, s42, s4
	s_addc_u32 s43, s43, 0
	s_mov_b32 m0, s81
	v_lshl_add_u64 v[134:135], s[42:43], 0, v[202:203]
	ds_read_b128 v[118:121], v230 offset:32768
	ds_read_b128 v[130:133], v230 offset:33792
	ds_read_b128 v[146:149], v230 offset:34816
	ds_read_b128 v[154:157], v230 offset:35840
	ds_read_b128 v[170:173], v230 offset:36864
	ds_read_b128 v[174:177], v230 offset:37888
	ds_read_b128 v[178:181], v230 offset:38912
	ds_read_b128 v[182:185], v230 offset:39936
	global_load_lds_dwordx4 v[134:135], off
	v_lshl_add_u64 v[134:135], s[42:43], 0, v[200:201]
	s_mov_b32 m0, s82
	s_nop 0
	global_load_lds_dwordx4 v[134:135], off
	s_waitcnt lgkmcnt(8)
	s_waitcnt vmcnt(10)
	s_barrier
	s_waitcnt lgkmcnt(0)
	s_setprio 1
	s_waitcnt lgkmcnt(0)
	v_mfma_f32_16x16x32_bf16 v[134:137], v[58:61], v[118:121], v[166:169]
	v_mfma_f32_16x16x32_bf16 v[166:169], v[62:65], v[130:133], v[134:137]
	v_mfma_f32_16x16x32_bf16 v[134:137], v[82:85], v[118:121], v[162:165]
	v_mfma_f32_16x16x32_bf16 v[162:165], v[86:89], v[130:133], v[134:137]
	v_mfma_f32_16x16x32_bf16 v[134:137], v[58:61], v[146:149], v[142:145]
	v_mfma_f32_16x16x32_bf16 v[142:145], v[62:65], v[154:157], v[134:137]
	v_mfma_f32_16x16x32_bf16 v[134:137], v[82:85], v[146:149], v[138:141]
	v_mfma_f32_16x16x32_bf16 v[126:129], v[58:61], v[170:173], v[126:129]
	v_mfma_f32_16x16x32_bf16 v[122:125], v[82:85], v[170:173], v[122:125]
	v_mfma_f32_16x16x32_bf16 v[110:113], v[58:61], v[178:181], v[110:113]
	v_mfma_f32_16x16x32_bf16 v[106:109], v[82:85], v[178:181], v[106:109]
	v_mfma_f32_16x16x32_bf16 v[138:141], v[86:89], v[154:157], v[134:137]
	v_mfma_f32_16x16x32_bf16 v[126:129], v[62:65], v[174:177], v[126:129]
	v_mfma_f32_16x16x32_bf16 v[122:125], v[86:89], v[174:177], v[122:125]
	v_mfma_f32_16x16x32_bf16 v[110:113], v[62:65], v[182:185], v[110:113]
	v_mfma_f32_16x16x32_bf16 v[106:109], v[86:89], v[182:185], v[106:109]
	s_setprio 0
	s_barrier
	s_add_i32 s42, 0, 0x1c000
	s_add_i32 s43, s72, s78
	v_add_u32_e32 v1, s42, v223
	v_lshl_add_u64 v[134:135], v[214:215], 0, s[22:23]
	s_mov_b32 m0, s43
	ds_read_b128 v[186:189], v1
	ds_read_b128 v[190:193], v1 offset:1024
	ds_read_b128 v[208:211], v1 offset:2048
	ds_read_b128 v[232:235], v1 offset:3072
	global_load_lds_dwordx4 v[134:135], off
	v_lshl_add_u64 v[134:135], v[236:237], 0, s[22:23]
	s_add_i32 m0, s43, 0x2000
	s_nop 0
	global_load_lds_dwordx4 v[134:135], off
	s_waitcnt vmcnt(10)
	s_barrier
	s_waitcnt lgkmcnt(0)
	s_setprio 1
	s_waitcnt lgkmcnt(0)
	v_mfma_f32_16x16x32_bf16 v[66:69], v[208:211], v[118:121], v[66:69]
	v_mfma_f32_16x16x32_bf16 v[134:137], v[186:189], v[118:121], v[158:161]
	v_mfma_f32_16x16x32_bf16 v[150:153], v[232:235], v[130:133], v[66:69]
	v_mfma_f32_16x16x32_bf16 v[66:69], v[186:189], v[146:149], v[70:73]
	v_mfma_f32_16x16x32_bf16 v[158:161], v[190:193], v[130:133], v[134:137]
	v_mfma_f32_16x16x32_bf16 v[134:137], v[190:193], v[154:157], v[66:69]
	v_mfma_f32_16x16x32_bf16 v[66:69], v[208:211], v[146:149], v[74:77]
	v_mfma_f32_16x16x32_bf16 v[130:133], v[232:235], v[154:157], v[66:69]
	v_mfma_f32_16x16x32_bf16 v[66:69], v[186:189], v[170:173], v[78:81]
	v_mfma_f32_16x16x32_bf16 v[118:121], v[190:193], v[174:177], v[66:69]
	v_mfma_f32_16x16x32_bf16 v[66:69], v[208:211], v[170:173], v[114:117]
	v_mfma_f32_16x16x32_bf16 v[114:117], v[232:235], v[174:177], v[66:69]
	v_mfma_f32_16x16x32_bf16 v[66:69], v[186:189], v[178:181], v[102:105]
	v_mfma_f32_16x16x32_bf16 v[102:105], v[190:193], v[182:185], v[66:69]
	v_mfma_f32_16x16x32_bf16 v[66:69], v[208:211], v[178:181], v[98:101]
	v_mfma_f32_16x16x32_bf16 v[98:101], v[232:235], v[182:185], v[66:69]
	s_setprio 0
	s_mov_b32 m0, s86
	v_lshl_add_u64 v[178:179], v[238:239], 0, s[22:23]
	s_barrier
	s_nop 2
	ds_read_b128 v[66:69], v230 offset:49152
	ds_read_b128 v[70:73], v230 offset:50176
	ds_read_b128 v[74:77], v230 offset:51200
	ds_read_b128 v[78:81], v230 offset:52224
	ds_read_b128 v[146:149], v230 offset:53248
	ds_read_b128 v[154:157], v230 offset:54272
	ds_read_b128 v[170:173], v230 offset:55296
	ds_read_b128 v[174:177], v230 offset:56320
	global_load_lds_dwordx4 v[178:179], off
	v_lshl_add_u64 v[178:179], v[240:241], 0, s[22:23]
	s_mov_b32 m0, s87
	s_nop 0
	global_load_lds_dwordx4 v[178:179], off
	s_barrier
	s_waitcnt lgkmcnt(0)
	s_setprio 1
	s_waitcnt lgkmcnt(0)
	v_mfma_f32_16x16x32_bf16 v[94:97], v[58:61], v[66:69], v[94:97]
	v_mfma_f32_16x16x32_bf16 v[90:93], v[82:85], v[66:69], v[90:93]
	v_mfma_f32_16x16x32_bf16 v[46:49], v[58:61], v[74:77], v[46:49]
	v_mfma_f32_16x16x32_bf16 v[42:45], v[82:85], v[74:77], v[42:45]
	v_mfma_f32_16x16x32_bf16 v[30:33], v[58:61], v[146:149], v[30:33]
	v_mfma_f32_16x16x32_bf16 v[26:29], v[82:85], v[146:149], v[26:29]
	v_mfma_f32_16x16x32_bf16 v[14:17], v[58:61], v[170:173], v[14:17]
	v_mfma_f32_16x16x32_bf16 v[10:13], v[82:85], v[170:173], v[10:13]
	v_mfma_f32_16x16x32_bf16 v[94:97], v[62:65], v[70:73], v[94:97]
	v_mfma_f32_16x16x32_bf16 v[90:93], v[86:89], v[70:73], v[90:93]
	v_mfma_f32_16x16x32_bf16 v[46:49], v[62:65], v[78:81], v[46:49]
	v_mfma_f32_16x16x32_bf16 v[42:45], v[86:89], v[78:81], v[42:45]
	v_mfma_f32_16x16x32_bf16 v[30:33], v[62:65], v[154:157], v[30:33]
	v_mfma_f32_16x16x32_bf16 v[26:29], v[86:89], v[154:157], v[26:29]
	v_mfma_f32_16x16x32_bf16 v[14:17], v[62:65], v[174:177], v[14:17]
	v_mfma_f32_16x16x32_bf16 v[10:13], v[86:89], v[174:177], v[10:13]
	s_setprio 0
	s_barrier
	s_add_i32 s42, s42, s78
	v_lshl_add_u64 v[58:59], v[242:243], 0, s[22:23]
	s_mov_b32 m0, s42
	s_nop 0
	global_load_lds_dwordx4 v[58:59], off
	v_lshl_add_u64 v[58:59], v[244:245], 0, s[22:23]
	s_add_i32 m0, s42, 0x2000
	s_nop 0
	global_load_lds_dwordx4 v[58:59], off
	s_waitcnt vmcnt(10)
	s_barrier
	s_setprio 1
	v_mfma_f32_16x16x32_bf16 v[50:53], v[186:189], v[66:69], v[50:53]
	v_mfma_f32_16x16x32_bf16 v[86:89], v[190:193], v[70:73], v[50:53]
	v_mfma_f32_16x16x32_bf16 v[50:53], v[208:211], v[66:69], v[54:57]
	v_mfma_f32_16x16x32_bf16 v[38:41], v[186:189], v[74:77], v[38:41]
	v_mfma_f32_16x16x32_bf16 v[34:37], v[208:211], v[74:77], v[34:37]
	v_mfma_f32_16x16x32_bf16 v[22:25], v[186:189], v[146:149], v[22:25]
	v_mfma_f32_16x16x32_bf16 v[18:21], v[208:211], v[146:149], v[18:21]
	v_mfma_f32_16x16x32_bf16 v[6:9], v[186:189], v[170:173], v[6:9]
	v_mfma_f32_16x16x32_bf16 v[2:5], v[208:211], v[170:173], v[2:5]
	v_mfma_f32_16x16x32_bf16 v[82:85], v[232:235], v[70:73], v[50:53]
	v_mfma_f32_16x16x32_bf16 v[38:41], v[190:193], v[78:81], v[38:41]
	v_mfma_f32_16x16x32_bf16 v[34:37], v[232:235], v[78:81], v[34:37]
	v_mfma_f32_16x16x32_bf16 v[22:25], v[190:193], v[154:157], v[22:25]
	v_mfma_f32_16x16x32_bf16 v[18:21], v[232:235], v[154:157], v[18:21]
	v_mfma_f32_16x16x32_bf16 v[6:9], v[190:193], v[174:177], v[6:9]
	v_mfma_f32_16x16x32_bf16 v[2:5], v[232:235], v[174:177], v[2:5]
	s_setprio 0
	s_add_u32 s27, s27, 0x100
	s_addc_u32 s91, s91, 0
	s_add_u32 s36, s36, 0x100
	s_addc_u32 s37, s37, 0
	s_cmp_ge_u32 s92, s84
	s_mov_b32 s42, s92
	s_barrier
.LBB0_1179:
	s_add_i32 s92, s42, 2
	s_add_u32 s72, s36, 0x80
	s_addc_u32 s43, s37, 0
	s_add_i32 s93, 0, 0x10000
	v_add_u32_e32 v1, s93, v223
	ds_read_b128 v[50:53], v1
	ds_read_b128 v[54:57], v1 offset:1024
	ds_read_b128 v[58:61], v1 offset:2048
	ds_read_b128 v[62:65], v1 offset:3072
	s_cmp_eq_u32 s88, s42
	s_cselect_b32 s42, s66, s72
	s_cselect_b32 s43, s67, s43
	s_cselect_b32 s73, s71, s91
	s_cselect_b32 s72, s70, s27
	v_lshl_add_u64 v[178:179], s[36:37], 0, v[206:207]
	s_add_i32 m0, s79, 0xc000
	ds_read_b128 v[66:69], v230
	ds_read_b128 v[70:73], v230 offset:1024
	ds_read_b128 v[74:77], v230 offset:2048
	ds_read_b128 v[78:81], v230 offset:3072
	ds_read_b128 v[146:149], v230 offset:4096
	ds_read_b128 v[154:157], v230 offset:5120
	ds_read_b128 v[170:173], v230 offset:6144
	ds_read_b128 v[174:177], v230 offset:7168
	global_load_lds_dwordx4 v[178:179], off
	v_lshl_add_u64 v[178:179], s[36:37], 0, v[204:205]
	s_add_i32 m0, s79, 0xe000
	s_nop 0
	global_load_lds_dwordx4 v[178:179], off
	s_waitcnt lgkmcnt(8)
	s_waitcnt vmcnt(10)
	s_barrier
	s_waitcnt lgkmcnt(0)
	s_setprio 1
	s_waitcnt lgkmcnt(0)
	v_mfma_f32_16x16x32_bf16 v[166:169], v[50:53], v[66:69], v[166:169]
	v_mfma_f32_16x16x32_bf16 v[162:165], v[58:61], v[66:69], v[162:165]
	v_mfma_f32_16x16x32_bf16 v[142:145], v[50:53], v[74:77], v[142:145]
	v_mfma_f32_16x16x32_bf16 v[138:141], v[58:61], v[74:77], v[138:141]
	v_mfma_f32_16x16x32_bf16 v[126:129], v[50:53], v[146:149], v[126:129]
	v_mfma_f32_16x16x32_bf16 v[122:125], v[58:61], v[146:149], v[122:125]
	v_mfma_f32_16x16x32_bf16 v[110:113], v[50:53], v[170:173], v[110:113]
	v_mfma_f32_16x16x32_bf16 v[106:109], v[58:61], v[170:173], v[106:109]
	v_mfma_f32_16x16x32_bf16 v[166:169], v[54:57], v[70:73], v[166:169]
	v_mfma_f32_16x16x32_bf16 v[162:165], v[62:65], v[70:73], v[162:165]
	v_mfma_f32_16x16x32_bf16 v[142:145], v[54:57], v[78:81], v[142:145]
	v_mfma_f32_16x16x32_bf16 v[138:141], v[62:65], v[78:81], v[138:141]
	v_mfma_f32_16x16x32_bf16 v[126:129], v[54:57], v[154:157], v[126:129]
	v_mfma_f32_16x16x32_bf16 v[122:125], v[62:65], v[154:157], v[122:125]
	v_mfma_f32_16x16x32_bf16 v[110:113], v[54:57], v[174:177], v[110:113]
	v_mfma_f32_16x16x32_bf16 v[106:109], v[62:65], v[174:177], v[106:109]
	s_setprio 0
	s_barrier
	s_add_i32 s94, 0, 0x14000
	s_add_i32 s93, s93, s78
	v_add_u32_e32 v1, s94, v223
	v_lshl_add_u64 v[214:215], s[72:73], 0, v[202:203]
	s_mov_b32 m0, s93
	ds_read_b128 v[178:181], v1
	ds_read_b128 v[182:185], v1 offset:1024
	ds_read_b128 v[186:189], v1 offset:2048
	ds_read_b128 v[190:193], v1 offset:3072
	global_load_lds_dwordx4 v[214:215], off
	v_lshl_add_u64 v[236:237], s[72:73], 0, v[200:201]
	s_add_i32 m0, s93, 0x2000
	s_nop 0
	global_load_lds_dwordx4 v[236:237], off
	s_waitcnt vmcnt(10)
	s_barrier
	s_waitcnt lgkmcnt(0)
	s_setprio 1
	s_waitcnt lgkmcnt(0)
	v_mfma_f32_16x16x32_bf16 v[158:161], v[178:181], v[66:69], v[158:161]
	v_mfma_f32_16x16x32_bf16 v[66:69], v[186:189], v[66:69], v[150:153]
	v_mfma_f32_16x16x32_bf16 v[158:161], v[182:185], v[70:73], v[158:161]
	v_mfma_f32_16x16x32_bf16 v[66:69], v[190:193], v[70:73], v[66:69]
	v_mfma_f32_16x16x32_bf16 v[70:73], v[178:181], v[74:77], v[134:137]
	v_mfma_f32_16x16x32_bf16 v[74:77], v[186:189], v[74:77], v[130:133]
	v_mfma_f32_16x16x32_bf16 v[114:117], v[186:189], v[146:149], v[114:117]
	v_mfma_f32_16x16x32_bf16 v[102:105], v[178:181], v[170:173], v[102:105]
	v_mfma_f32_16x16x32_bf16 v[98:101], v[186:189], v[170:173], v[98:101]
	v_mfma_f32_16x16x32_bf16 v[70:73], v[182:185], v[78:81], v[70:73]
	v_mfma_f32_16x16x32_bf16 v[74:77], v[190:193], v[78:81], v[74:77]
	v_mfma_f32_16x16x32_bf16 v[78:81], v[178:181], v[146:149], v[118:121]
	v_mfma_f32_16x16x32_bf16 v[114:117], v[190:193], v[154:157], v[114:117]
	v_mfma_f32_16x16x32_bf16 v[102:105], v[182:185], v[174:177], v[102:105]
	v_mfma_f32_16x16x32_bf16 v[98:101], v[190:193], v[174:177], v[98:101]
	v_mfma_f32_16x16x32_bf16 v[78:81], v[182:185], v[154:157], v[78:81]
	s_setprio 0
	s_mov_b32 m0, s79
	v_lshl_add_u64 v[238:239], s[42:43], 0, v[202:203]
	s_barrier
	ds_read_b128 v[118:121], v230 offset:16384
	ds_read_b128 v[130:133], v230 offset:17408
	ds_read_b128 v[134:137], v230 offset:18432
	ds_read_b128 v[146:149], v230 offset:19456
	ds_read_b128 v[150:153], v230 offset:20480
	ds_read_b128 v[154:157], v230 offset:21504
	ds_read_b128 v[170:173], v230 offset:22528
	ds_read_b128 v[174:177], v230 offset:23552
	global_load_lds_dwordx4 v[238:239], off
	v_lshl_add_u64 v[240:241], s[42:43], 0, v[200:201]
	s_mov_b32 m0, s80
	s_nop 0
	global_load_lds_dwordx4 v[240:241], off
	s_barrier
	s_waitcnt lgkmcnt(0)
	s_setprio 1
	s_waitcnt lgkmcnt(0)
	v_mfma_f32_16x16x32_bf16 v[94:97], v[50:53], v[118:121], v[94:97]
	v_mfma_f32_16x16x32_bf16 v[90:93], v[58:61], v[118:121], v[90:93]
	v_mfma_f32_16x16x32_bf16 v[46:49], v[50:53], v[134:137], v[46:49]
	v_mfma_f32_16x16x32_bf16 v[42:45], v[58:61], v[134:137], v[42:45]
	v_mfma_f32_16x16x32_bf16 v[30:33], v[50:53], v[150:153], v[30:33]
	v_mfma_f32_16x16x32_bf16 v[26:29], v[58:61], v[150:153], v[26:29]
	v_mfma_f32_16x16x32_bf16 v[14:17], v[50:53], v[170:173], v[14:17]
	v_mfma_f32_16x16x32_bf16 v[10:13], v[58:61], v[170:173], v[10:13]
	v_mfma_f32_16x16x32_bf16 v[94:97], v[54:57], v[130:133], v[94:97]
	v_mfma_f32_16x16x32_bf16 v[90:93], v[62:65], v[130:133], v[90:93]
	v_mfma_f32_16x16x32_bf16 v[46:49], v[54:57], v[146:149], v[46:49]
	v_mfma_f32_16x16x32_bf16 v[42:45], v[62:65], v[146:149], v[42:45]
	v_mfma_f32_16x16x32_bf16 v[30:33], v[54:57], v[154:157], v[30:33]
	v_mfma_f32_16x16x32_bf16 v[26:29], v[62:65], v[154:157], v[26:29]
	v_mfma_f32_16x16x32_bf16 v[14:17], v[54:57], v[174:177], v[14:17]
	v_mfma_f32_16x16x32_bf16 v[10:13], v[62:65], v[174:177], v[10:13]
	s_setprio 0
	s_barrier
	s_add_u32 s72, s72, s4
	s_addc_u32 s73, s73, 0
	s_add_i32 s93, s94, s78
	v_lshl_add_u64 v[242:243], s[72:73], 0, v[202:203]
	s_mov_b32 m0, s93
	v_lshl_add_u64 v[244:245], s[72:73], 0, v[200:201]
	global_load_lds_dwordx4 v[242:243], off
	s_add_i32 m0, s93, 0x2000
	s_nop 0
	global_load_lds_dwordx4 v[244:245], off
	s_waitcnt vmcnt(10)
	s_barrier
	s_setprio 1
	v_mfma_f32_16x16x32_bf16 v[38:41], v[178:181], v[134:137], v[38:41]
	v_mfma_f32_16x16x32_bf16 v[34:37], v[186:189], v[134:137], v[34:37]
	v_mfma_f32_16x16x32_bf16 v[22:25], v[178:181], v[150:153], v[22:25]
	v_mfma_f32_16x16x32_bf16 v[18:21], v[186:189], v[150:153], v[18:21]
	v_mfma_f32_16x16x32_bf16 v[6:9], v[178:181], v[170:173], v[6:9]
	v_mfma_f32_16x16x32_bf16 v[2:5], v[186:189], v[170:173], v[2:5]
	v_mfma_f32_16x16x32_bf16 v[50:53], v[178:181], v[118:121], v[86:89]
	v_mfma_f32_16x16x32_bf16 v[54:57], v[186:189], v[118:121], v[82:85]
	v_mfma_f32_16x16x32_bf16 v[38:41], v[182:185], v[146:149], v[38:41]
	v_mfma_f32_16x16x32_bf16 v[34:37], v[190:193], v[146:149], v[34:37]
	v_mfma_f32_16x16x32_bf16 v[22:25], v[182:185], v[154:157], v[22:25]
	v_mfma_f32_16x16x32_bf16 v[18:21], v[190:193], v[154:157], v[18:21]
	v_mfma_f32_16x16x32_bf16 v[6:9], v[182:185], v[174:177], v[6:9]
	v_mfma_f32_16x16x32_bf16 v[2:5], v[190:193], v[174:177], v[2:5]
	v_mfma_f32_16x16x32_bf16 v[50:53], v[182:185], v[130:133], v[50:53]
	v_mfma_f32_16x16x32_bf16 v[54:57], v[190:193], v[130:133], v[54:57]
	s_setprio 0
	s_add_i32 s72, 0, 0x18000
	v_add_u32_e32 v1, s72, v223
	s_barrier
	ds_read_b128 v[58:61], v1
	ds_read_b128 v[62:65], v1 offset:1024
	ds_read_b128 v[82:85], v1 offset:2048
	ds_read_b128 v[86:89], v1 offset:3072
	s_add_u32 s42, s42, s4
	s_addc_u32 s43, s43, 0
	s_mov_b32 m0, s81
	v_lshl_add_u64 v[134:135], s[42:43], 0, v[202:203]
	ds_read_b128 v[118:121], v230 offset:32768
	ds_read_b128 v[130:133], v230 offset:33792
	ds_read_b128 v[146:149], v230 offset:34816
	ds_read_b128 v[154:157], v230 offset:35840
	ds_read_b128 v[170:173], v230 offset:36864
	ds_read_b128 v[174:177], v230 offset:37888
	ds_read_b128 v[178:181], v230 offset:38912
	ds_read_b128 v[182:185], v230 offset:39936
	global_load_lds_dwordx4 v[134:135], off
	v_lshl_add_u64 v[134:135], s[42:43], 0, v[200:201]
	s_mov_b32 m0, s82
	s_nop 0
	global_load_lds_dwordx4 v[134:135], off
	s_waitcnt lgkmcnt(8)
	s_waitcnt vmcnt(10)
	s_barrier
	s_waitcnt lgkmcnt(0)
	s_setprio 1
	s_waitcnt lgkmcnt(0)
	v_mfma_f32_16x16x32_bf16 v[134:137], v[58:61], v[118:121], v[166:169]
	v_mfma_f32_16x16x32_bf16 v[166:169], v[62:65], v[130:133], v[134:137]
	v_mfma_f32_16x16x32_bf16 v[134:137], v[82:85], v[118:121], v[162:165]
	v_mfma_f32_16x16x32_bf16 v[162:165], v[86:89], v[130:133], v[134:137]
	v_mfma_f32_16x16x32_bf16 v[134:137], v[58:61], v[146:149], v[142:145]
	v_mfma_f32_16x16x32_bf16 v[142:145], v[62:65], v[154:157], v[134:137]
	v_mfma_f32_16x16x32_bf16 v[134:137], v[82:85], v[146:149], v[138:141]
	v_mfma_f32_16x16x32_bf16 v[126:129], v[58:61], v[170:173], v[126:129]
	v_mfma_f32_16x16x32_bf16 v[122:125], v[82:85], v[170:173], v[122:125]
	v_mfma_f32_16x16x32_bf16 v[110:113], v[58:61], v[178:181], v[110:113]
	v_mfma_f32_16x16x32_bf16 v[106:109], v[82:85], v[178:181], v[106:109]
	v_mfma_f32_16x16x32_bf16 v[138:141], v[86:89], v[154:157], v[134:137]
	v_mfma_f32_16x16x32_bf16 v[126:129], v[62:65], v[174:177], v[126:129]
	v_mfma_f32_16x16x32_bf16 v[122:125], v[86:89], v[174:177], v[122:125]
	v_mfma_f32_16x16x32_bf16 v[110:113], v[62:65], v[182:185], v[110:113]
	v_mfma_f32_16x16x32_bf16 v[106:109], v[86:89], v[182:185], v[106:109]
	s_setprio 0
	s_barrier
	s_add_i32 s42, 0, 0x1c000
	s_add_i32 s43, s72, s78
	v_add_u32_e32 v1, s42, v223
	v_lshl_add_u64 v[134:135], v[214:215], 0, s[22:23]
	s_mov_b32 m0, s43
	ds_read_b128 v[186:189], v1
	ds_read_b128 v[190:193], v1 offset:1024
	ds_read_b128 v[208:211], v1 offset:2048
	ds_read_b128 v[232:235], v1 offset:3072
	global_load_lds_dwordx4 v[134:135], off
	v_lshl_add_u64 v[134:135], v[236:237], 0, s[22:23]
	s_add_i32 m0, s43, 0x2000
	s_nop 0
	global_load_lds_dwordx4 v[134:135], off
	s_waitcnt vmcnt(10)
	s_barrier
	s_waitcnt lgkmcnt(0)
	s_setprio 1
	s_waitcnt lgkmcnt(0)
	v_mfma_f32_16x16x32_bf16 v[66:69], v[208:211], v[118:121], v[66:69]
	v_mfma_f32_16x16x32_bf16 v[134:137], v[186:189], v[118:121], v[158:161]
	v_mfma_f32_16x16x32_bf16 v[150:153], v[232:235], v[130:133], v[66:69]
	v_mfma_f32_16x16x32_bf16 v[66:69], v[186:189], v[146:149], v[70:73]
	v_mfma_f32_16x16x32_bf16 v[158:161], v[190:193], v[130:133], v[134:137]
	v_mfma_f32_16x16x32_bf16 v[134:137], v[190:193], v[154:157], v[66:69]
	v_mfma_f32_16x16x32_bf16 v[66:69], v[208:211], v[146:149], v[74:77]
	v_mfma_f32_16x16x32_bf16 v[130:133], v[232:235], v[154:157], v[66:69]
	v_mfma_f32_16x16x32_bf16 v[66:69], v[186:189], v[170:173], v[78:81]
	v_mfma_f32_16x16x32_bf16 v[118:121], v[190:193], v[174:177], v[66:69]
	v_mfma_f32_16x16x32_bf16 v[66:69], v[208:211], v[170:173], v[114:117]
	v_mfma_f32_16x16x32_bf16 v[114:117], v[232:235], v[174:177], v[66:69]
	v_mfma_f32_16x16x32_bf16 v[66:69], v[186:189], v[178:181], v[102:105]
	v_mfma_f32_16x16x32_bf16 v[102:105], v[190:193], v[182:185], v[66:69]
	v_mfma_f32_16x16x32_bf16 v[66:69], v[208:211], v[178:181], v[98:101]
	v_mfma_f32_16x16x32_bf16 v[98:101], v[232:235], v[182:185], v[66:69]
	s_setprio 0
	s_mov_b32 m0, s86
	v_lshl_add_u64 v[178:179], v[238:239], 0, s[22:23]
	s_barrier
	s_nop 2
	ds_read_b128 v[66:69], v230 offset:49152
	ds_read_b128 v[70:73], v230 offset:50176
	ds_read_b128 v[74:77], v230 offset:51200
	ds_read_b128 v[78:81], v230 offset:52224
	ds_read_b128 v[146:149], v230 offset:53248
	ds_read_b128 v[154:157], v230 offset:54272
	ds_read_b128 v[170:173], v230 offset:55296
	ds_read_b128 v[174:177], v230 offset:56320
	global_load_lds_dwordx4 v[178:179], off
	v_lshl_add_u64 v[178:179], v[240:241], 0, s[22:23]
	s_mov_b32 m0, s87
	s_nop 0
	global_load_lds_dwordx4 v[178:179], off
	s_barrier
	s_waitcnt lgkmcnt(0)
	s_setprio 1
	s_waitcnt lgkmcnt(0)
	v_mfma_f32_16x16x32_bf16 v[94:97], v[58:61], v[66:69], v[94:97]
	v_mfma_f32_16x16x32_bf16 v[90:93], v[82:85], v[66:69], v[90:93]
	v_mfma_f32_16x16x32_bf16 v[46:49], v[58:61], v[74:77], v[46:49]
	v_mfma_f32_16x16x32_bf16 v[42:45], v[82:85], v[74:77], v[42:45]
	v_mfma_f32_16x16x32_bf16 v[30:33], v[58:61], v[146:149], v[30:33]
	v_mfma_f32_16x16x32_bf16 v[26:29], v[82:85], v[146:149], v[26:29]
	v_mfma_f32_16x16x32_bf16 v[14:17], v[58:61], v[170:173], v[14:17]
	v_mfma_f32_16x16x32_bf16 v[10:13], v[82:85], v[170:173], v[10:13]
	v_mfma_f32_16x16x32_bf16 v[94:97], v[62:65], v[70:73], v[94:97]
	v_mfma_f32_16x16x32_bf16 v[90:93], v[86:89], v[70:73], v[90:93]
	v_mfma_f32_16x16x32_bf16 v[46:49], v[62:65], v[78:81], v[46:49]
	v_mfma_f32_16x16x32_bf16 v[42:45], v[86:89], v[78:81], v[42:45]
	v_mfma_f32_16x16x32_bf16 v[30:33], v[62:65], v[154:157], v[30:33]
	v_mfma_f32_16x16x32_bf16 v[26:29], v[86:89], v[154:157], v[26:29]
	v_mfma_f32_16x16x32_bf16 v[14:17], v[62:65], v[174:177], v[14:17]
	v_mfma_f32_16x16x32_bf16 v[10:13], v[86:89], v[174:177], v[10:13]
	s_setprio 0
	s_barrier
	s_add_i32 s42, s42, s78
	v_lshl_add_u64 v[58:59], v[242:243], 0, s[22:23]
	s_mov_b32 m0, s42
	s_nop 0
	global_load_lds_dwordx4 v[58:59], off
	v_lshl_add_u64 v[58:59], v[244:245], 0, s[22:23]
	s_add_i32 m0, s42, 0x2000
	s_nop 0
	global_load_lds_dwordx4 v[58:59], off
	s_waitcnt vmcnt(10)
	s_barrier
	s_setprio 1
	v_mfma_f32_16x16x32_bf16 v[50:53], v[186:189], v[66:69], v[50:53]
	v_mfma_f32_16x16x32_bf16 v[86:89], v[190:193], v[70:73], v[50:53]
	v_mfma_f32_16x16x32_bf16 v[50:53], v[208:211], v[66:69], v[54:57]
	v_mfma_f32_16x16x32_bf16 v[38:41], v[186:189], v[74:77], v[38:41]
	v_mfma_f32_16x16x32_bf16 v[34:37], v[208:211], v[74:77], v[34:37]
	v_mfma_f32_16x16x32_bf16 v[22:25], v[186:189], v[146:149], v[22:25]
	v_mfma_f32_16x16x32_bf16 v[18:21], v[208:211], v[146:149], v[18:21]
	v_mfma_f32_16x16x32_bf16 v[6:9], v[186:189], v[170:173], v[6:9]
	v_mfma_f32_16x16x32_bf16 v[2:5], v[208:211], v[170:173], v[2:5]
	v_mfma_f32_16x16x32_bf16 v[82:85], v[232:235], v[70:73], v[50:53]
	v_mfma_f32_16x16x32_bf16 v[38:41], v[190:193], v[78:81], v[38:41]
	v_mfma_f32_16x16x32_bf16 v[34:37], v[232:235], v[78:81], v[34:37]
	v_mfma_f32_16x16x32_bf16 v[22:25], v[190:193], v[154:157], v[22:25]
	v_mfma_f32_16x16x32_bf16 v[18:21], v[232:235], v[154:157], v[18:21]
	v_mfma_f32_16x16x32_bf16 v[6:9], v[190:193], v[174:177], v[6:9]
	v_mfma_f32_16x16x32_bf16 v[2:5], v[232:235], v[174:177], v[2:5]
	s_setprio 0
	s_add_u32 s27, s27, 0x100
	s_addc_u32 s91, s91, 0
	s_add_u32 s36, s36, 0x100
	s_addc_u32 s37, s37, 0
	s_cmp_ge_u32 s92, s84
	s_mov_b32 s42, s92
	s_barrier
	s_cbranch_scc0 .LBB0_1179
	s_lshl_b32 s3, s3, 8
	s_add_i32 s27, s3, s85
	v_lshl_or_b32 v210, s38, 8, v224
	v_or_b32_e32 v146, s27, v221
	v_ashrrev_i32_e32 v147, 31, v146
	v_ashrrev_i32_e32 v211, 31, v210
	v_lshlrev_b64 v[50:51], 2, v[210:211]
	v_lshl_add_u64 v[208:209], v[210:211], 1, s[48:49]
	v_lshlrev_b64 v[148:149], 11, v[146:147]
	v_lshl_add_u64 v[52:53], s[52:53], 0, v[50:51]
	v_lshl_add_u64 v[54:55], s[54:55], 0, v[50:51]
	v_lshl_add_u64 v[148:149], v[208:209], 0, v[148:149]
	global_load_dwordx4 v[74:77], v[52:53], off
	global_load_dwordx4 v[66:69], v[52:53], off offset:16
	global_load_dwordx4 v[78:81], v[54:55], off
	global_load_dwordx4 v[70:73], v[54:55], off offset:16
	global_load_dwordx4 v[58:61], v[52:53], off offset:512
	s_nop 0
	global_load_dwordx4 v[50:53], v[52:53], off offset:528
	s_nop 0
	global_load_dwordx4 v[62:65], v[54:55], off offset:512
	s_nop 0
	global_load_dwordx4 v[54:57], v[54:55], off offset:528
	global_load_dwordx4 v[190:193], v[148:149], off
	global_load_dwordx4 v[186:189], v[148:149], off offset:256
	v_or_b32_e32 v148, 16, v146
	v_ashrrev_i32_e32 v149, 31, v148
	v_lshlrev_b64 v[148:149], 11, v[148:149]
	v_lshl_add_u64 v[148:149], v[208:209], 0, v[148:149]
	global_load_dwordx4 v[182:185], v[148:149], off
	global_load_dwordx4 v[178:181], v[148:149], off offset:256
	v_or_b32_e32 v148, 32, v146
	v_or_b32_e32 v146, 48, v146
	v_ashrrev_i32_e32 v149, 31, v148
	v_ashrrev_i32_e32 v147, 31, v146
	v_lshlrev_b64 v[148:149], 11, v[148:149]
	v_lshlrev_b64 v[146:147], 11, v[146:147]
	v_mov_b32_e32 v1, v222
	v_lshl_add_u64 v[148:149], v[208:209], 0, v[148:149]
	v_lshl_add_u64 v[146:147], v[208:209], 0, v[146:147]
	global_load_dwordx4 v[174:177], v[148:149], off
	global_load_dwordx4 v[170:173], v[148:149], off offset:256
	global_load_dwordx4 v[154:157], v[146:147], off
	s_nop 0
	global_load_dwordx4 v[146:149], v[146:147], off offset:256
	v_cndmask_b32_e64 v211, 0, 1, s[56:57]
	v_cmp_ne_u32_e64 s[42:43], 1, v211
	s_andn2_b64 vcc, exec, s[56:57]
	v_lshl_add_u32 v231, v1, 3, s33
	s_cbranch_vccnz .LBB0_1182
	ds_read_b64 v[214:215], v231
	s_waitcnt lgkmcnt(0)
	v_mov_b32_e32 v212, v215
	s_branch .LBB0_1183
